# v43 + ssm_c WC part: first six ring loads issued before the carry-in (H) staging waits (prologue de-serialisation), ring order rotated
# speedup vs baseline: 1.0024x; 1.0024x over previous
; #define LAS __attribute__((address_space(3)))
; template <int PMODE> __device__ __forceinline__ void ssm_c_task(unsigned char* ws, LAS unsigned char* lds, int l, int task, int tid_in) {
;     ...
; #pragma unroll 2
;         for (int ks = 0; ks < (PMODE == 3 ? 0 : 16); ++ks) {
;             bf16x8 bfr[4];
; #pragma unroll
;             for (int c = 0; c < 4; ++c) bfr[c] = *(const LAS bf16x8*)(lds + SS_UB + (((2 * ks + (kk >> 1)) * 64 + c * 16 + rr) * 32 + (kk & 1) * 16));
;             const int j = hh * 32 + 2 * ks + (kk >> 1);
; #pragma unroll
;             for (int a = 0; a < 8; ++a) { const int i = wid * 8 + a;
;                 const bf16x8 af = *(const LAS bf16x8*)(lds + SS_KT + (i - j + 63) * 512 + rr * 32 + (kk & 1) * 16);
; #pragma unroll
;                 for (int c = 0; c < 4; ++c) acc[a][c] = __builtin_amdgcn_mfma_f32_16x16x32_bf16(af, bfr[c], acc[a][c], 0, 0, 0); }
;         }
.LBB0_835:
	v_add_u32_e32 v171, v170, v217
	v_add_u32_e32 v184, v169, v217
	v_add_u32_e32 v44, 0x10000, v171
	ds_read_b128 v[210:213], v184 offset:4096
	ds_read_b128 v[172:175], v44
	v_add_u32_e32 v44, 0x10200, v171
	ds_read_b128 v[176:179], v44
	v_add_u32_e32 v44, 0x10400, v171
	ds_read_b128 v[180:183], v44
	v_add_u32_e32 v44, 0x10600, v171
	ds_read_b128 v[186:189], v44
	ds_read_b128 v[44:47], v184 offset:1024
	ds_read_b128 v[132:135], v184 offset:1536
	ds_read_b128 v[194:197], v184 offset:2048
	ds_read_b128 v[198:201], v184 offset:2560
	ds_read_b128 v[202:205], v184 offset:3072
	ds_read_b128 v[206:209], v184 offset:3584
	s_waitcnt lgkmcnt(9)
	v_mfma_f32_16x16x32_bf16 v[28:31], v[210:213], v[172:175], v[28:31]
	s_add_i32 s3, s3, -2
	v_add_u32_e32 v170, 0x2000, v170
	v_add_u32_e32 v169, 0xfffff800, v169
	s_waitcnt lgkmcnt(8)
	v_mfma_f32_16x16x32_bf16 v[24:27], v[210:213], v[176:179], v[24:27]
	s_cmp_lg_u32 s3, 0
	s_waitcnt lgkmcnt(7)
	v_mfma_f32_16x16x32_bf16 v[20:23], v[210:213], v[180:183], v[20:23]
	s_waitcnt lgkmcnt(6)
	v_mfma_f32_16x16x32_bf16 v[16:19], v[210:213], v[186:189], v[16:19]
	ds_read_b128 v[210:213], v184 offset:4608
	s_waitcnt lgkmcnt(6)
	v_mfma_f32_16x16x32_bf16 v[128:131], v[44:47], v[172:175], v[128:131]
	v_mfma_f32_16x16x32_bf16 v[124:127], v[44:47], v[176:179], v[124:127]
	v_mfma_f32_16x16x32_bf16 v[120:123], v[44:47], v[180:183], v[120:123]
	s_waitcnt lgkmcnt(5)
	v_mfma_f32_16x16x32_bf16 v[112:115], v[132:135], v[172:175], v[112:115]
	v_mfma_f32_16x16x32_bf16 v[108:111], v[132:135], v[176:179], v[108:111]
	v_mfma_f32_16x16x32_bf16 v[104:107], v[132:135], v[180:183], v[104:107]
	s_waitcnt lgkmcnt(4)
	v_mfma_f32_16x16x32_bf16 v[96:99], v[194:197], v[172:175], v[96:99]
	v_mfma_f32_16x16x32_bf16 v[92:95], v[194:197], v[176:179], v[92:95]
	v_mfma_f32_16x16x32_bf16 v[88:91], v[194:197], v[180:183], v[88:91]
	s_waitcnt lgkmcnt(3)
	v_mfma_f32_16x16x32_bf16 v[80:83], v[198:201], v[172:175], v[80:83]
	v_mfma_f32_16x16x32_bf16 v[76:79], v[198:201], v[176:179], v[76:79]
	v_mfma_f32_16x16x32_bf16 v[72:75], v[198:201], v[180:183], v[72:75]
	s_waitcnt lgkmcnt(2)
	v_mfma_f32_16x16x32_bf16 v[64:67], v[202:205], v[172:175], v[64:67]
	v_mfma_f32_16x16x32_bf16 v[60:63], v[202:205], v[176:179], v[60:63]
	v_mfma_f32_16x16x32_bf16 v[56:59], v[202:205], v[180:183], v[56:59]
	s_waitcnt lgkmcnt(1)
	v_mfma_f32_16x16x32_bf16 v[48:51], v[206:209], v[172:175], v[48:51]
	v_mfma_f32_16x16x32_bf16 v[40:43], v[206:209], v[176:179], v[40:43]
	v_mfma_f32_16x16x32_bf16 v[36:39], v[206:209], v[180:183], v[36:39]
	s_waitcnt lgkmcnt(0)
	v_mfma_f32_16x16x32_bf16 v[12:15], v[210:213], v[172:175], v[12:15]
	v_add_u32_e32 v172, 0x11000, v171
	ds_read_b128 v[172:175], v172
	v_mfma_f32_16x16x32_bf16 v[8:11], v[210:213], v[176:179], v[8:11]
	v_add_u32_e32 v176, 0x11200, v171
	ds_read_b128 v[176:179], v176
	v_mfma_f32_16x16x32_bf16 v[4:7], v[210:213], v[180:183], v[4:7]
	v_add_u32_e32 v180, 0x11400, v171
	v_add_u32_e32 v171, 0x11600, v171
	ds_read_b128 v[180:183], v180
	v_mfma_f32_16x16x32_bf16 v[116:119], v[44:47], v[186:189], v[116:119]
	v_mfma_f32_16x16x32_bf16 v[100:103], v[132:135], v[186:189], v[100:103]
	v_mfma_f32_16x16x32_bf16 v[84:87], v[194:197], v[186:189], v[84:87]
	v_mfma_f32_16x16x32_bf16 v[68:71], v[198:201], v[186:189], v[68:71]
	v_mfma_f32_16x16x32_bf16 v[52:55], v[202:205], v[186:189], v[52:55]
	v_mfma_f32_16x16x32_bf16 v[32:35], v[206:209], v[186:189], v[32:35]
	v_mfma_f32_16x16x32_bf16 v[0:3], v[210:213], v[186:189], v[0:3]
	ds_read_b128 v[186:189], v171
	ds_read_b128 v[210:213], v184
	s_waitcnt lgkmcnt(0)
	v_mfma_f32_16x16x32_bf16 v[128:131], v[210:213], v[172:175], v[128:131]
	v_mfma_f32_16x16x32_bf16 v[124:127], v[210:213], v[176:179], v[124:127]
	v_mfma_f32_16x16x32_bf16 v[120:123], v[210:213], v[180:183], v[120:123]
	v_mfma_f32_16x16x32_bf16 v[116:119], v[210:213], v[186:189], v[116:119]
	ds_read_b128 v[210:213], v184 offset:512
	s_waitcnt lgkmcnt(0)
	v_mfma_f32_16x16x32_bf16 v[112:115], v[210:213], v[172:175], v[112:115]
	v_mfma_f32_16x16x32_bf16 v[108:111], v[210:213], v[176:179], v[108:111]
	v_mfma_f32_16x16x32_bf16 v[104:107], v[210:213], v[180:183], v[104:107]
	v_mfma_f32_16x16x32_bf16 v[100:103], v[210:213], v[186:189], v[100:103]
	v_mfma_f32_16x16x32_bf16 v[96:99], v[44:47], v[172:175], v[96:99]
	v_mfma_f32_16x16x32_bf16 v[92:95], v[44:47], v[176:179], v[92:95]
	v_mfma_f32_16x16x32_bf16 v[88:91], v[44:47], v[180:183], v[88:91]
	v_mfma_f32_16x16x32_bf16 v[84:87], v[44:47], v[186:189], v[84:87]
	v_mfma_f32_16x16x32_bf16 v[80:83], v[132:135], v[172:175], v[80:83]
	v_mfma_f32_16x16x32_bf16 v[76:79], v[132:135], v[176:179], v[76:79]
	v_mfma_f32_16x16x32_bf16 v[72:75], v[132:135], v[180:183], v[72:75]
	v_mfma_f32_16x16x32_bf16 v[68:71], v[132:135], v[186:189], v[68:71]
	v_mfma_f32_16x16x32_bf16 v[64:67], v[194:197], v[172:175], v[64:67]
	v_mfma_f32_16x16x32_bf16 v[60:63], v[194:197], v[176:179], v[60:63]
	v_mfma_f32_16x16x32_bf16 v[56:59], v[194:197], v[180:183], v[56:59]
	v_mfma_f32_16x16x32_bf16 v[52:55], v[194:197], v[186:189], v[52:55]
	v_mfma_f32_16x16x32_bf16 v[48:51], v[198:201], v[172:175], v[48:51]
	v_mfma_f32_16x16x32_bf16 v[40:43], v[198:201], v[176:179], v[40:43]
	v_mfma_f32_16x16x32_bf16 v[36:39], v[198:201], v[180:183], v[36:39]
	v_mfma_f32_16x16x32_bf16 v[32:35], v[198:201], v[186:189], v[32:35]
	v_mfma_f32_16x16x32_bf16 v[28:31], v[202:205], v[172:175], v[28:31]
	v_mfma_f32_16x16x32_bf16 v[24:27], v[202:205], v[176:179], v[24:27]
	v_mfma_f32_16x16x32_bf16 v[20:23], v[202:205], v[180:183], v[20:23]
	v_mfma_f32_16x16x32_bf16 v[16:19], v[202:205], v[186:189], v[16:19]
	v_mfma_f32_16x16x32_bf16 v[12:15], v[206:209], v[172:175], v[12:15]
	v_mfma_f32_16x16x32_bf16 v[8:11], v[206:209], v[176:179], v[8:11]
	v_mfma_f32_16x16x32_bf16 v[4:7], v[206:209], v[180:183], v[4:7]
	v_mfma_f32_16x16x32_bf16 v[0:3], v[206:209], v[186:189], v[0:3]
	s_cbranch_scc1 .LBB0_835
; #define LAS __attribute__((address_space(3)))
; template <int PMODE> __device__ __forceinline__ void ssm_c_task(unsigned char* ws, LAS unsigned char* lds, int l, int task, int tid_in) {
;     ...
;         __syncthreads();
;     }
;     if (PMODE >= 2) {
; #pragma unroll
;         for (int a = 0; a < 8; ++a)
; #pragma unroll
;             for (int c = 0; c < 4; ++c) asm volatile("" :: "v"(acc[a][c]));
;         __syncthreads(); return; }
;     { const bf16* Hb = (const bf16*)(ws + AR_H); int tid = tid_in; asm volatile("" : "+v"(tid));
;       u32x4 v[4];
; #pragma unroll
;       for (int r = 0; r < 4; ++r) { const int c = r * 512 + tid, col = c & 63, kc = c >> 6; v[r] = *(const u32x4*)(Hb + ((size_t)((cb * 64 + col) * NG + g) * 256 + kc * 8)); }
; #pragma unroll
;       for (int r = 0; r < 4; ++r) { const int c = r * 512 + tid; *(LAS u32x4*)(lds + SS_UB + c * 16) = v[r]; } }
;     __syncthreads();
;     { const bf16* WC = (const bf16*)(ws + WS_WC) + ((size_t)(g * 1024 + wid * 128 + rr) * 256 + 8 * kk);
; #pragma unroll 1
;       for (int ks = 0; ks < 8; ++ks) {
;           bf16x8 bfr[4], afr[8];
; #pragma unroll
;           for (int a = 0; a < 8; ++a) afr[a] = *(const bf16x8*)(WC + (size_t)a * 16 * 256 + ks * 32);
; #pragma unroll
;           for (int c = 0; c < 4; ++c) bfr[c] = *(const LAS bf16x8*)(lds + SS_UB + (((ks * 4 + kk) * 64 + c * 16 + rr) * 16));
; #pragma unroll
;           for (int a = 0; a < 8; ++a)
; #pragma unroll
;               for (int c = 0; c < 4; ++c) acc[a][c] = __builtin_amdgcn_mfma_f32_16x16x32_bf16(afr[a], bfr[c], acc[a][c], 0, 0, 0);
;       } }
	v_mov_b32_e32 v169, v136
	s_barrier
	s_lshl_b32 s3, s16, 11
	v_lshlrev_b32_e32 v44, 5, v169
	v_and_b32_e32 v44, 0x7e0, v44
	s_add_i32 s3, s3, s56
	v_add_u32_e32 v44, s3, v44
	v_ashrrev_i32_e32 v45, 31, v44
	v_lshlrev_b64 v[44:45], 9, v[44:45]
	v_lshl_add_u64 v[174:175], s[22:23], 0, v[44:45]
	v_ashrrev_i32_e32 v44, 3, v169
	v_add_u32_e32 v132, 0x200, v169
	v_and_b32_e32 v44, -8, v44
	v_ashrrev_i32_e32 v132, 3, v132
	v_add_u32_e32 v170, 0x400, v169
	v_ashrrev_i32_e32 v45, 31, v44
	v_and_b32_e32 v132, -8, v132
	v_ashrrev_i32_e32 v170, 3, v170
	v_add_u32_e32 v176, 0x600, v169
	v_lshl_add_u64 v[44:45], v[44:45], 1, v[174:175]
	v_ashrrev_i32_e32 v133, 31, v132
	v_and_b32_e32 v170, -8, v170
	v_ashrrev_i32_e32 v176, 3, v176
	global_load_dwordx4 v[44:47], v[44:45], off
	v_lshl_add_u64 v[132:133], v[132:133], 1, v[174:175]
	v_ashrrev_i32_e32 v171, 31, v170
	v_and_b32_e32 v176, -8, v176
	global_load_dwordx4 v[132:135], v[132:133], off
	v_lshl_add_u64 v[170:171], v[170:171], 1, v[174:175]
	v_ashrrev_i32_e32 v177, 31, v176
	global_load_dwordx4 v[170:173], v[170:171], off
	v_lshl_add_u64 v[174:175], v[176:177], 1, v[174:175]
	global_load_dwordx4 v[174:177], v[174:175], off
	v_lshl_add_u32 v169, v169, 4, 0
	v_add_u32_e32 v169, 0x10000, v169
	v_lshl_add_u32 v182, s56, 10, v218
	v_ashrrev_i32_e32 v183, 31, v182
	v_lshlrev_b64 v[182:183], 9, v[182:183]
	v_lshl_add_u64 v[190:191], v[166:167], 0, v[182:183]
	s_mov_b32 s62, 0xd400000
	s_mov_b32 s63, 0
	s_mov_b32 s50, 0x2000
	s_mov_b32 s51, 0
	v_lshl_add_u64 v[190:191], v[190:191], 0, s[62:63]
	s_mov_b32 s62, 0xffff2040
	s_mov_b32 s63, -1
	global_load_dwordx4 v[192:195], v[190:191], off
	v_lshl_add_u64 v[190:191], v[190:191], 0, s[50:51]
	global_load_dwordx4 v[196:199], v[190:191], off
	v_lshl_add_u64 v[190:191], v[190:191], 0, s[50:51]
	global_load_dwordx4 v[200:203], v[190:191], off
	v_lshl_add_u64 v[190:191], v[190:191], 0, s[50:51]
	global_load_dwordx4 v[204:207], v[190:191], off
	v_lshl_add_u64 v[190:191], v[190:191], 0, s[50:51]
	global_load_dwordx4 v[208:211], v[190:191], off
	v_lshl_add_u64 v[190:191], v[190:191], 0, s[50:51]
	global_load_dwordx4 v[212:215], v[190:191], off
	v_lshl_add_u64 v[190:191], v[190:191], 0, s[50:51]
	s_waitcnt vmcnt(9)
	ds_write_b128 v169, v[44:47]
	s_waitcnt vmcnt(8)
	ds_write_b128 v169, v[132:135] offset:8192
	s_waitcnt vmcnt(7)
	ds_write_b128 v169, v[170:173] offset:16384
	s_waitcnt vmcnt(6)
	ds_write_b128 v169, v[174:177] offset:24576
	v_lshl_add_u32 v44, s56, 10, v218
	v_ashrrev_i32_e32 v45, 31, v44
	v_lshlrev_b64 v[44:45], 9, v[44:45]
	v_lshl_add_u64 v[132:133], v[166:167], 0, v[44:45]
	v_mov_b32_e32 v169, v222
	global_load_dwordx4 v[170:173], v[190:191], off
	v_lshl_add_u64 v[190:191], v[190:191], 0, s[50:51]
	s_waitcnt lgkmcnt(0)
	s_barrier
.LBB0_837:
	ds_read_b128 v[44:47], v169 offset:0
	ds_read_b128 v[174:177], v169 offset:256
	ds_read_b128 v[178:181], v169 offset:512
	ds_read_b128 v[186:189], v169 offset:768
	s_waitcnt lgkmcnt(0)
	s_waitcnt vmcnt(6)
	v_mfma_f32_16x16x32_bf16 v[128:131], v[192:195], v[44:47], v[128:131]
	v_mfma_f32_16x16x32_bf16 v[124:127], v[192:195], v[174:177], v[124:127]
	v_mfma_f32_16x16x32_bf16 v[120:123], v[192:195], v[178:181], v[120:123]
	v_mfma_f32_16x16x32_bf16 v[116:119], v[192:195], v[186:189], v[116:119]
	global_load_dwordx4 v[192:195], v[190:191], off
	v_lshl_add_u64 v[190:191], v[190:191], 0, s[62:63]
	ds_read_b128 v[232:235], v169 offset:4096
	ds_read_b128 v[236:239], v169 offset:4352
	ds_read_b128 v[240:243], v169 offset:4608
	ds_read_b128 v[244:247], v169 offset:4864
	s_waitcnt vmcnt(6)
	v_mfma_f32_16x16x32_bf16 v[112:115], v[196:199], v[44:47], v[112:115]
	v_mfma_f32_16x16x32_bf16 v[108:111], v[196:199], v[174:177], v[108:111]
	v_mfma_f32_16x16x32_bf16 v[104:107], v[196:199], v[178:181], v[104:107]
	v_mfma_f32_16x16x32_bf16 v[100:103], v[196:199], v[186:189], v[100:103]
	global_load_dwordx4 v[196:199], v[190:191], off
	v_lshl_add_u64 v[190:191], v[190:191], 0, s[50:51]
	s_waitcnt vmcnt(6)
	v_mfma_f32_16x16x32_bf16 v[96:99], v[200:203], v[44:47], v[96:99]
	v_mfma_f32_16x16x32_bf16 v[92:95], v[200:203], v[174:177], v[92:95]
	v_mfma_f32_16x16x32_bf16 v[88:91], v[200:203], v[178:181], v[88:91]
	v_mfma_f32_16x16x32_bf16 v[84:87], v[200:203], v[186:189], v[84:87]
	global_load_dwordx4 v[200:203], v[190:191], off
	v_lshl_add_u64 v[190:191], v[190:191], 0, s[50:51]
	s_waitcnt vmcnt(6)
	v_mfma_f32_16x16x32_bf16 v[80:83], v[204:207], v[44:47], v[80:83]
	v_mfma_f32_16x16x32_bf16 v[76:79], v[204:207], v[174:177], v[76:79]
	v_mfma_f32_16x16x32_bf16 v[72:75], v[204:207], v[178:181], v[72:75]
	v_mfma_f32_16x16x32_bf16 v[68:71], v[204:207], v[186:189], v[68:71]
	global_load_dwordx4 v[204:207], v[190:191], off
	v_lshl_add_u64 v[190:191], v[190:191], 0, s[50:51]
	s_waitcnt vmcnt(6)
	v_mfma_f32_16x16x32_bf16 v[64:67], v[208:211], v[44:47], v[64:67]
	v_mfma_f32_16x16x32_bf16 v[60:63], v[208:211], v[174:177], v[60:63]
	v_mfma_f32_16x16x32_bf16 v[56:59], v[208:211], v[178:181], v[56:59]
	v_mfma_f32_16x16x32_bf16 v[52:55], v[208:211], v[186:189], v[52:55]
	global_load_dwordx4 v[208:211], v[190:191], off
	v_lshl_add_u64 v[190:191], v[190:191], 0, s[50:51]
	s_waitcnt vmcnt(6)
	v_mfma_f32_16x16x32_bf16 v[48:51], v[212:215], v[44:47], v[48:51]
	v_mfma_f32_16x16x32_bf16 v[40:43], v[212:215], v[174:177], v[40:43]
	v_mfma_f32_16x16x32_bf16 v[36:39], v[212:215], v[178:181], v[36:39]
	v_mfma_f32_16x16x32_bf16 v[32:35], v[212:215], v[186:189], v[32:35]
	global_load_dwordx4 v[212:215], v[190:191], off
	v_lshl_add_u64 v[190:191], v[190:191], 0, s[50:51]
	s_waitcnt vmcnt(6)
; #define LAS __attribute__((address_space(3)))
; template <int PMODE> __device__ __forceinline__ void ssm_c_task(unsigned char* ws, LAS unsigned char* lds, int l, int task, int tid_in) {
;     ...
;     { const bf16* WC = (const bf16*)(ws + WS_WC) + ((size_t)(g * 1024 + wid * 128 + rr) * 256 + 8 * kk);
; #pragma unroll 1
;       for (int ks = 0; ks < 8; ++ks) {
;           bf16x8 bfr[4], afr[8];
; #pragma unroll
;           for (int a = 0; a < 8; ++a) afr[a] = *(const bf16x8*)(WC + (size_t)a * 16 * 256 + ks * 32);
; #pragma unroll
;           for (int c = 0; c < 4; ++c) bfr[c] = *(const LAS bf16x8*)(lds + SS_UB + (((ks * 4 + kk) * 64 + c * 16 + rr) * 16));
; #pragma unroll
;           for (int a = 0; a < 8; ++a)
; #pragma unroll
;               for (int c = 0; c < 4; ++c) acc[a][c] = __builtin_amdgcn_mfma_f32_16x16x32_bf16(afr[a], bfr[c], acc[a][c], 0, 0, 0);
;       } }
	v_mfma_f32_16x16x32_bf16 v[28:31], v[170:173], v[44:47], v[28:31]
	v_mfma_f32_16x16x32_bf16 v[24:27], v[170:173], v[174:177], v[24:27]
	v_mfma_f32_16x16x32_bf16 v[20:23], v[170:173], v[178:181], v[20:23]
	v_mfma_f32_16x16x32_bf16 v[16:19], v[170:173], v[186:189], v[16:19]
	global_load_dwordx4 v[170:173], v[190:191], off
	v_lshl_add_u64 v[190:191], v[190:191], 0, s[50:51]
	s_waitcnt vmcnt(6)
	v_mfma_f32_16x16x32_bf16 v[12:15], v[192:195], v[44:47], v[12:15]
	v_mfma_f32_16x16x32_bf16 v[8:11], v[192:195], v[174:177], v[8:11]
	v_mfma_f32_16x16x32_bf16 v[4:7], v[192:195], v[178:181], v[4:7]
	v_mfma_f32_16x16x32_bf16 v[0:3], v[192:195], v[186:189], v[0:3]
	global_load_dwordx4 v[192:195], v[190:191], off
	v_lshl_add_u64 v[190:191], v[190:191], 0, s[50:51]
	s_waitcnt lgkmcnt(0)
	s_waitcnt vmcnt(6)
	v_mfma_f32_16x16x32_bf16 v[128:131], v[196:199], v[232:235], v[128:131]
	v_mfma_f32_16x16x32_bf16 v[124:127], v[196:199], v[236:239], v[124:127]
	v_mfma_f32_16x16x32_bf16 v[120:123], v[196:199], v[240:243], v[120:123]
	v_mfma_f32_16x16x32_bf16 v[116:119], v[196:199], v[244:247], v[116:119]
	global_load_dwordx4 v[196:199], v[190:191], off
	v_lshl_add_u64 v[190:191], v[190:191], 0, s[62:63]
	ds_read_b128 v[44:47], v169 offset:8192
	ds_read_b128 v[174:177], v169 offset:8448
	ds_read_b128 v[178:181], v169 offset:8704
	ds_read_b128 v[186:189], v169 offset:8960
	s_waitcnt vmcnt(6)
	v_mfma_f32_16x16x32_bf16 v[112:115], v[200:203], v[232:235], v[112:115]
	v_mfma_f32_16x16x32_bf16 v[108:111], v[200:203], v[236:239], v[108:111]
	v_mfma_f32_16x16x32_bf16 v[104:107], v[200:203], v[240:243], v[104:107]
	v_mfma_f32_16x16x32_bf16 v[100:103], v[200:203], v[244:247], v[100:103]
	global_load_dwordx4 v[200:203], v[190:191], off
	v_lshl_add_u64 v[190:191], v[190:191], 0, s[50:51]
	s_waitcnt vmcnt(6)
	v_mfma_f32_16x16x32_bf16 v[96:99], v[204:207], v[232:235], v[96:99]
	v_mfma_f32_16x16x32_bf16 v[92:95], v[204:207], v[236:239], v[92:95]
	v_mfma_f32_16x16x32_bf16 v[88:91], v[204:207], v[240:243], v[88:91]
	v_mfma_f32_16x16x32_bf16 v[84:87], v[204:207], v[244:247], v[84:87]
	global_load_dwordx4 v[204:207], v[190:191], off
	v_lshl_add_u64 v[190:191], v[190:191], 0, s[50:51]
	s_waitcnt vmcnt(6)
	v_mfma_f32_16x16x32_bf16 v[80:83], v[208:211], v[232:235], v[80:83]
	v_mfma_f32_16x16x32_bf16 v[76:79], v[208:211], v[236:239], v[76:79]
	v_mfma_f32_16x16x32_bf16 v[72:75], v[208:211], v[240:243], v[72:75]
	v_mfma_f32_16x16x32_bf16 v[68:71], v[208:211], v[244:247], v[68:71]
	global_load_dwordx4 v[208:211], v[190:191], off
	v_lshl_add_u64 v[190:191], v[190:191], 0, s[50:51]
	s_waitcnt vmcnt(6)
	v_mfma_f32_16x16x32_bf16 v[64:67], v[212:215], v[232:235], v[64:67]
	v_mfma_f32_16x16x32_bf16 v[60:63], v[212:215], v[236:239], v[60:63]
	v_mfma_f32_16x16x32_bf16 v[56:59], v[212:215], v[240:243], v[56:59]
	v_mfma_f32_16x16x32_bf16 v[52:55], v[212:215], v[244:247], v[52:55]
	global_load_dwordx4 v[212:215], v[190:191], off
	v_lshl_add_u64 v[190:191], v[190:191], 0, s[50:51]
	s_waitcnt vmcnt(6)
	v_mfma_f32_16x16x32_bf16 v[48:51], v[170:173], v[232:235], v[48:51]
	v_mfma_f32_16x16x32_bf16 v[40:43], v[170:173], v[236:239], v[40:43]
	v_mfma_f32_16x16x32_bf16 v[36:39], v[170:173], v[240:243], v[36:39]
	v_mfma_f32_16x16x32_bf16 v[32:35], v[170:173], v[244:247], v[32:35]
	global_load_dwordx4 v[170:173], v[190:191], off
	v_lshl_add_u64 v[190:191], v[190:191], 0, s[50:51]
	s_waitcnt vmcnt(6)
	v_mfma_f32_16x16x32_bf16 v[28:31], v[192:195], v[232:235], v[28:31]
	v_mfma_f32_16x16x32_bf16 v[24:27], v[192:195], v[236:239], v[24:27]
	v_mfma_f32_16x16x32_bf16 v[20:23], v[192:195], v[240:243], v[20:23]
	v_mfma_f32_16x16x32_bf16 v[16:19], v[192:195], v[244:247], v[16:19]
	global_load_dwordx4 v[192:195], v[190:191], off
	v_lshl_add_u64 v[190:191], v[190:191], 0, s[50:51]
	s_waitcnt vmcnt(6)
	v_mfma_f32_16x16x32_bf16 v[12:15], v[196:199], v[232:235], v[12:15]
	v_mfma_f32_16x16x32_bf16 v[8:11], v[196:199], v[236:239], v[8:11]
	v_mfma_f32_16x16x32_bf16 v[4:7], v[196:199], v[240:243], v[4:7]
	v_mfma_f32_16x16x32_bf16 v[0:3], v[196:199], v[244:247], v[0:3]
	global_load_dwordx4 v[196:199], v[190:191], off
	v_lshl_add_u64 v[190:191], v[190:191], 0, s[50:51]
	s_waitcnt lgkmcnt(0)
	s_waitcnt vmcnt(6)
	v_mfma_f32_16x16x32_bf16 v[128:131], v[200:203], v[44:47], v[128:131]
	v_mfma_f32_16x16x32_bf16 v[124:127], v[200:203], v[174:177], v[124:127]
	v_mfma_f32_16x16x32_bf16 v[120:123], v[200:203], v[178:181], v[120:123]
	v_mfma_f32_16x16x32_bf16 v[116:119], v[200:203], v[186:189], v[116:119]
	global_load_dwordx4 v[200:203], v[190:191], off
	v_lshl_add_u64 v[190:191], v[190:191], 0, s[62:63]
	ds_read_b128 v[232:235], v169 offset:12288
	ds_read_b128 v[236:239], v169 offset:12544
	ds_read_b128 v[240:243], v169 offset:12800
	ds_read_b128 v[244:247], v169 offset:13056
	s_waitcnt vmcnt(6)
	v_mfma_f32_16x16x32_bf16 v[112:115], v[204:207], v[44:47], v[112:115]
	v_mfma_f32_16x16x32_bf16 v[108:111], v[204:207], v[174:177], v[108:111]
	v_mfma_f32_16x16x32_bf16 v[104:107], v[204:207], v[178:181], v[104:107]
	v_mfma_f32_16x16x32_bf16 v[100:103], v[204:207], v[186:189], v[100:103]
	global_load_dwordx4 v[204:207], v[190:191], off
	v_lshl_add_u64 v[190:191], v[190:191], 0, s[50:51]
	s_waitcnt vmcnt(6)
	v_mfma_f32_16x16x32_bf16 v[96:99], v[208:211], v[44:47], v[96:99]
	v_mfma_f32_16x16x32_bf16 v[92:95], v[208:211], v[174:177], v[92:95]
	v_mfma_f32_16x16x32_bf16 v[88:91], v[208:211], v[178:181], v[88:91]
	v_mfma_f32_16x16x32_bf16 v[84:87], v[208:211], v[186:189], v[84:87]
	global_load_dwordx4 v[208:211], v[190:191], off
	v_lshl_add_u64 v[190:191], v[190:191], 0, s[50:51]
	s_waitcnt vmcnt(6)
; #define LAS __attribute__((address_space(3)))
; template <int PMODE> __device__ __forceinline__ void ssm_c_task(unsigned char* ws, LAS unsigned char* lds, int l, int task, int tid_in) {
;     ...
;     { const bf16* WC = (const bf16*)(ws + WS_WC) + ((size_t)(g * 1024 + wid * 128 + rr) * 256 + 8 * kk);
; #pragma unroll 1
;       for (int ks = 0; ks < 8; ++ks) {
;           bf16x8 bfr[4], afr[8];
; #pragma unroll
;           for (int a = 0; a < 8; ++a) afr[a] = *(const bf16x8*)(WC + (size_t)a * 16 * 256 + ks * 32);
; #pragma unroll
;           for (int c = 0; c < 4; ++c) bfr[c] = *(const LAS bf16x8*)(lds + SS_UB + (((ks * 4 + kk) * 64 + c * 16 + rr) * 16));
; #pragma unroll
;           for (int a = 0; a < 8; ++a)
; #pragma unroll
;               for (int c = 0; c < 4; ++c) acc[a][c] = __builtin_amdgcn_mfma_f32_16x16x32_bf16(afr[a], bfr[c], acc[a][c], 0, 0, 0);
;       } }
	v_mfma_f32_16x16x32_bf16 v[80:83], v[212:215], v[44:47], v[80:83]
	v_mfma_f32_16x16x32_bf16 v[76:79], v[212:215], v[174:177], v[76:79]
	v_mfma_f32_16x16x32_bf16 v[72:75], v[212:215], v[178:181], v[72:75]
	v_mfma_f32_16x16x32_bf16 v[68:71], v[212:215], v[186:189], v[68:71]
	global_load_dwordx4 v[212:215], v[190:191], off
	v_lshl_add_u64 v[190:191], v[190:191], 0, s[50:51]
	s_waitcnt vmcnt(6)
	v_mfma_f32_16x16x32_bf16 v[64:67], v[170:173], v[44:47], v[64:67]
	v_mfma_f32_16x16x32_bf16 v[60:63], v[170:173], v[174:177], v[60:63]
	v_mfma_f32_16x16x32_bf16 v[56:59], v[170:173], v[178:181], v[56:59]
	v_mfma_f32_16x16x32_bf16 v[52:55], v[170:173], v[186:189], v[52:55]
	global_load_dwordx4 v[170:173], v[190:191], off
	v_lshl_add_u64 v[190:191], v[190:191], 0, s[50:51]
	s_waitcnt vmcnt(6)
	v_mfma_f32_16x16x32_bf16 v[48:51], v[192:195], v[44:47], v[48:51]
	v_mfma_f32_16x16x32_bf16 v[40:43], v[192:195], v[174:177], v[40:43]
	v_mfma_f32_16x16x32_bf16 v[36:39], v[192:195], v[178:181], v[36:39]
	v_mfma_f32_16x16x32_bf16 v[32:35], v[192:195], v[186:189], v[32:35]
	global_load_dwordx4 v[192:195], v[190:191], off
	v_lshl_add_u64 v[190:191], v[190:191], 0, s[50:51]
	s_waitcnt vmcnt(6)
	v_mfma_f32_16x16x32_bf16 v[28:31], v[196:199], v[44:47], v[28:31]
	v_mfma_f32_16x16x32_bf16 v[24:27], v[196:199], v[174:177], v[24:27]
	v_mfma_f32_16x16x32_bf16 v[20:23], v[196:199], v[178:181], v[20:23]
	v_mfma_f32_16x16x32_bf16 v[16:19], v[196:199], v[186:189], v[16:19]
	global_load_dwordx4 v[196:199], v[190:191], off
	v_lshl_add_u64 v[190:191], v[190:191], 0, s[50:51]
	s_waitcnt vmcnt(6)
	v_mfma_f32_16x16x32_bf16 v[12:15], v[200:203], v[44:47], v[12:15]
	v_mfma_f32_16x16x32_bf16 v[8:11], v[200:203], v[174:177], v[8:11]
	v_mfma_f32_16x16x32_bf16 v[4:7], v[200:203], v[178:181], v[4:7]
	v_mfma_f32_16x16x32_bf16 v[0:3], v[200:203], v[186:189], v[0:3]
	global_load_dwordx4 v[200:203], v[190:191], off
	v_lshl_add_u64 v[190:191], v[190:191], 0, s[50:51]
	s_waitcnt lgkmcnt(0)
	s_waitcnt vmcnt(6)
	v_mfma_f32_16x16x32_bf16 v[128:131], v[204:207], v[232:235], v[128:131]
	v_mfma_f32_16x16x32_bf16 v[124:127], v[204:207], v[236:239], v[124:127]
	v_mfma_f32_16x16x32_bf16 v[120:123], v[204:207], v[240:243], v[120:123]
	v_mfma_f32_16x16x32_bf16 v[116:119], v[204:207], v[244:247], v[116:119]
	global_load_dwordx4 v[204:207], v[190:191], off
	v_lshl_add_u64 v[190:191], v[190:191], 0, s[62:63]
	ds_read_b128 v[44:47], v169 offset:16384
	ds_read_b128 v[174:177], v169 offset:16640
	ds_read_b128 v[178:181], v169 offset:16896
	ds_read_b128 v[186:189], v169 offset:17152
	s_waitcnt vmcnt(6)
	v_mfma_f32_16x16x32_bf16 v[112:115], v[208:211], v[232:235], v[112:115]
	v_mfma_f32_16x16x32_bf16 v[108:111], v[208:211], v[236:239], v[108:111]
	v_mfma_f32_16x16x32_bf16 v[104:107], v[208:211], v[240:243], v[104:107]
	v_mfma_f32_16x16x32_bf16 v[100:103], v[208:211], v[244:247], v[100:103]
	global_load_dwordx4 v[208:211], v[190:191], off
	v_lshl_add_u64 v[190:191], v[190:191], 0, s[50:51]
	s_waitcnt vmcnt(6)
	v_mfma_f32_16x16x32_bf16 v[96:99], v[212:215], v[232:235], v[96:99]
	v_mfma_f32_16x16x32_bf16 v[92:95], v[212:215], v[236:239], v[92:95]
	v_mfma_f32_16x16x32_bf16 v[88:91], v[212:215], v[240:243], v[88:91]
	v_mfma_f32_16x16x32_bf16 v[84:87], v[212:215], v[244:247], v[84:87]
	global_load_dwordx4 v[212:215], v[190:191], off
	v_lshl_add_u64 v[190:191], v[190:191], 0, s[50:51]
	s_waitcnt vmcnt(6)
	v_mfma_f32_16x16x32_bf16 v[80:83], v[170:173], v[232:235], v[80:83]
	v_mfma_f32_16x16x32_bf16 v[76:79], v[170:173], v[236:239], v[76:79]
	v_mfma_f32_16x16x32_bf16 v[72:75], v[170:173], v[240:243], v[72:75]
	v_mfma_f32_16x16x32_bf16 v[68:71], v[170:173], v[244:247], v[68:71]
	global_load_dwordx4 v[170:173], v[190:191], off
	v_lshl_add_u64 v[190:191], v[190:191], 0, s[50:51]
	s_waitcnt vmcnt(6)
	v_mfma_f32_16x16x32_bf16 v[64:67], v[192:195], v[232:235], v[64:67]
	v_mfma_f32_16x16x32_bf16 v[60:63], v[192:195], v[236:239], v[60:63]
	v_mfma_f32_16x16x32_bf16 v[56:59], v[192:195], v[240:243], v[56:59]
	v_mfma_f32_16x16x32_bf16 v[52:55], v[192:195], v[244:247], v[52:55]
	global_load_dwordx4 v[192:195], v[190:191], off
	v_lshl_add_u64 v[190:191], v[190:191], 0, s[50:51]
	s_waitcnt vmcnt(6)
	v_mfma_f32_16x16x32_bf16 v[48:51], v[196:199], v[232:235], v[48:51]
	v_mfma_f32_16x16x32_bf16 v[40:43], v[196:199], v[236:239], v[40:43]
	v_mfma_f32_16x16x32_bf16 v[36:39], v[196:199], v[240:243], v[36:39]
	v_mfma_f32_16x16x32_bf16 v[32:35], v[196:199], v[244:247], v[32:35]
	global_load_dwordx4 v[196:199], v[190:191], off
	v_lshl_add_u64 v[190:191], v[190:191], 0, s[50:51]
	s_waitcnt vmcnt(6)
	v_mfma_f32_16x16x32_bf16 v[28:31], v[200:203], v[232:235], v[28:31]
	v_mfma_f32_16x16x32_bf16 v[24:27], v[200:203], v[236:239], v[24:27]
	v_mfma_f32_16x16x32_bf16 v[20:23], v[200:203], v[240:243], v[20:23]
	v_mfma_f32_16x16x32_bf16 v[16:19], v[200:203], v[244:247], v[16:19]
	global_load_dwordx4 v[200:203], v[190:191], off
	v_lshl_add_u64 v[190:191], v[190:191], 0, s[50:51]
	s_waitcnt vmcnt(6)
	v_mfma_f32_16x16x32_bf16 v[12:15], v[204:207], v[232:235], v[12:15]
	v_mfma_f32_16x16x32_bf16 v[8:11], v[204:207], v[236:239], v[8:11]
	v_mfma_f32_16x16x32_bf16 v[4:7], v[204:207], v[240:243], v[4:7]
	v_mfma_f32_16x16x32_bf16 v[0:3], v[204:207], v[244:247], v[0:3]
	global_load_dwordx4 v[204:207], v[190:191], off
	v_lshl_add_u64 v[190:191], v[190:191], 0, s[50:51]
	s_waitcnt lgkmcnt(0)
	s_waitcnt vmcnt(6)
; #define LAS __attribute__((address_space(3)))
; template <int PMODE> __device__ __forceinline__ void ssm_c_task(unsigned char* ws, LAS unsigned char* lds, int l, int task, int tid_in) {
;     ...
;     { const bf16* WC = (const bf16*)(ws + WS_WC) + ((size_t)(g * 1024 + wid * 128 + rr) * 256 + 8 * kk);
; #pragma unroll 1
;       for (int ks = 0; ks < 8; ++ks) {
;           bf16x8 bfr[4], afr[8];
; #pragma unroll
;           for (int a = 0; a < 8; ++a) afr[a] = *(const bf16x8*)(WC + (size_t)a * 16 * 256 + ks * 32);
; #pragma unroll
;           for (int c = 0; c < 4; ++c) bfr[c] = *(const LAS bf16x8*)(lds + SS_UB + (((ks * 4 + kk) * 64 + c * 16 + rr) * 16));
; #pragma unroll
;           for (int a = 0; a < 8; ++a)
; #pragma unroll
;               for (int c = 0; c < 4; ++c) acc[a][c] = __builtin_amdgcn_mfma_f32_16x16x32_bf16(afr[a], bfr[c], acc[a][c], 0, 0, 0);
;       } }
	v_mfma_f32_16x16x32_bf16 v[128:131], v[208:211], v[44:47], v[128:131]
	v_mfma_f32_16x16x32_bf16 v[124:127], v[208:211], v[174:177], v[124:127]
	v_mfma_f32_16x16x32_bf16 v[120:123], v[208:211], v[178:181], v[120:123]
	v_mfma_f32_16x16x32_bf16 v[116:119], v[208:211], v[186:189], v[116:119]
	global_load_dwordx4 v[208:211], v[190:191], off
	v_lshl_add_u64 v[190:191], v[190:191], 0, s[62:63]
	ds_read_b128 v[232:235], v169 offset:20480
	ds_read_b128 v[236:239], v169 offset:20736
	ds_read_b128 v[240:243], v169 offset:20992
	ds_read_b128 v[244:247], v169 offset:21248
	s_waitcnt vmcnt(6)
	v_mfma_f32_16x16x32_bf16 v[112:115], v[212:215], v[44:47], v[112:115]
	v_mfma_f32_16x16x32_bf16 v[108:111], v[212:215], v[174:177], v[108:111]
	v_mfma_f32_16x16x32_bf16 v[104:107], v[212:215], v[178:181], v[104:107]
	v_mfma_f32_16x16x32_bf16 v[100:103], v[212:215], v[186:189], v[100:103]
	global_load_dwordx4 v[212:215], v[190:191], off
	v_lshl_add_u64 v[190:191], v[190:191], 0, s[50:51]
	s_waitcnt vmcnt(6)
	v_mfma_f32_16x16x32_bf16 v[96:99], v[170:173], v[44:47], v[96:99]
	v_mfma_f32_16x16x32_bf16 v[92:95], v[170:173], v[174:177], v[92:95]
	v_mfma_f32_16x16x32_bf16 v[88:91], v[170:173], v[178:181], v[88:91]
	v_mfma_f32_16x16x32_bf16 v[84:87], v[170:173], v[186:189], v[84:87]
	global_load_dwordx4 v[170:173], v[190:191], off
	v_lshl_add_u64 v[190:191], v[190:191], 0, s[50:51]
	s_waitcnt vmcnt(6)
	v_mfma_f32_16x16x32_bf16 v[80:83], v[192:195], v[44:47], v[80:83]
	v_mfma_f32_16x16x32_bf16 v[76:79], v[192:195], v[174:177], v[76:79]
	v_mfma_f32_16x16x32_bf16 v[72:75], v[192:195], v[178:181], v[72:75]
	v_mfma_f32_16x16x32_bf16 v[68:71], v[192:195], v[186:189], v[68:71]
	global_load_dwordx4 v[192:195], v[190:191], off
	v_lshl_add_u64 v[190:191], v[190:191], 0, s[50:51]
	s_waitcnt vmcnt(6)
	v_mfma_f32_16x16x32_bf16 v[64:67], v[196:199], v[44:47], v[64:67]
	v_mfma_f32_16x16x32_bf16 v[60:63], v[196:199], v[174:177], v[60:63]
	v_mfma_f32_16x16x32_bf16 v[56:59], v[196:199], v[178:181], v[56:59]
	v_mfma_f32_16x16x32_bf16 v[52:55], v[196:199], v[186:189], v[52:55]
	global_load_dwordx4 v[196:199], v[190:191], off
	v_lshl_add_u64 v[190:191], v[190:191], 0, s[50:51]
	s_waitcnt vmcnt(6)
	v_mfma_f32_16x16x32_bf16 v[48:51], v[200:203], v[44:47], v[48:51]
	v_mfma_f32_16x16x32_bf16 v[40:43], v[200:203], v[174:177], v[40:43]
	v_mfma_f32_16x16x32_bf16 v[36:39], v[200:203], v[178:181], v[36:39]
	v_mfma_f32_16x16x32_bf16 v[32:35], v[200:203], v[186:189], v[32:35]
	global_load_dwordx4 v[200:203], v[190:191], off
	v_lshl_add_u64 v[190:191], v[190:191], 0, s[50:51]
	s_waitcnt vmcnt(6)
	v_mfma_f32_16x16x32_bf16 v[28:31], v[204:207], v[44:47], v[28:31]
	v_mfma_f32_16x16x32_bf16 v[24:27], v[204:207], v[174:177], v[24:27]
	v_mfma_f32_16x16x32_bf16 v[20:23], v[204:207], v[178:181], v[20:23]
	v_mfma_f32_16x16x32_bf16 v[16:19], v[204:207], v[186:189], v[16:19]
	global_load_dwordx4 v[204:207], v[190:191], off
	v_lshl_add_u64 v[190:191], v[190:191], 0, s[50:51]
	s_waitcnt vmcnt(6)
	v_mfma_f32_16x16x32_bf16 v[12:15], v[208:211], v[44:47], v[12:15]
	v_mfma_f32_16x16x32_bf16 v[8:11], v[208:211], v[174:177], v[8:11]
	v_mfma_f32_16x16x32_bf16 v[4:7], v[208:211], v[178:181], v[4:7]
	v_mfma_f32_16x16x32_bf16 v[0:3], v[208:211], v[186:189], v[0:3]
	global_load_dwordx4 v[208:211], v[190:191], off
	v_lshl_add_u64 v[190:191], v[190:191], 0, s[50:51]
	s_waitcnt lgkmcnt(0)
	s_waitcnt vmcnt(6)
	v_mfma_f32_16x16x32_bf16 v[128:131], v[212:215], v[232:235], v[128:131]
	v_mfma_f32_16x16x32_bf16 v[124:127], v[212:215], v[236:239], v[124:127]
	v_mfma_f32_16x16x32_bf16 v[120:123], v[212:215], v[240:243], v[120:123]
	v_mfma_f32_16x16x32_bf16 v[116:119], v[212:215], v[244:247], v[116:119]
	global_load_dwordx4 v[212:215], v[190:191], off
	v_lshl_add_u64 v[190:191], v[190:191], 0, s[62:63]
	ds_read_b128 v[44:47], v169 offset:24576
	ds_read_b128 v[174:177], v169 offset:24832
	ds_read_b128 v[178:181], v169 offset:25088
	ds_read_b128 v[186:189], v169 offset:25344
	s_waitcnt vmcnt(6)
	v_mfma_f32_16x16x32_bf16 v[112:115], v[170:173], v[232:235], v[112:115]
	v_mfma_f32_16x16x32_bf16 v[108:111], v[170:173], v[236:239], v[108:111]
	v_mfma_f32_16x16x32_bf16 v[104:107], v[170:173], v[240:243], v[104:107]
	v_mfma_f32_16x16x32_bf16 v[100:103], v[170:173], v[244:247], v[100:103]
	global_load_dwordx4 v[170:173], v[190:191], off
	v_lshl_add_u64 v[190:191], v[190:191], 0, s[50:51]
	s_waitcnt vmcnt(6)
	v_mfma_f32_16x16x32_bf16 v[96:99], v[192:195], v[232:235], v[96:99]
	v_mfma_f32_16x16x32_bf16 v[92:95], v[192:195], v[236:239], v[92:95]
	v_mfma_f32_16x16x32_bf16 v[88:91], v[192:195], v[240:243], v[88:91]
	v_mfma_f32_16x16x32_bf16 v[84:87], v[192:195], v[244:247], v[84:87]
	global_load_dwordx4 v[192:195], v[190:191], off
	v_lshl_add_u64 v[190:191], v[190:191], 0, s[50:51]
	s_waitcnt vmcnt(6)
	v_mfma_f32_16x16x32_bf16 v[80:83], v[196:199], v[232:235], v[80:83]
	v_mfma_f32_16x16x32_bf16 v[76:79], v[196:199], v[236:239], v[76:79]
	v_mfma_f32_16x16x32_bf16 v[72:75], v[196:199], v[240:243], v[72:75]
	v_mfma_f32_16x16x32_bf16 v[68:71], v[196:199], v[244:247], v[68:71]
	global_load_dwordx4 v[196:199], v[190:191], off
	v_lshl_add_u64 v[190:191], v[190:191], 0, s[50:51]
	s_waitcnt vmcnt(6)
	v_mfma_f32_16x16x32_bf16 v[64:67], v[200:203], v[232:235], v[64:67]
	v_mfma_f32_16x16x32_bf16 v[60:63], v[200:203], v[236:239], v[60:63]
	v_mfma_f32_16x16x32_bf16 v[56:59], v[200:203], v[240:243], v[56:59]
	v_mfma_f32_16x16x32_bf16 v[52:55], v[200:203], v[244:247], v[52:55]
	global_load_dwordx4 v[200:203], v[190:191], off
	v_lshl_add_u64 v[190:191], v[190:191], 0, s[50:51]
	s_waitcnt vmcnt(6)
; #define LAS __attribute__((address_space(3)))
; template <int PMODE> __device__ __forceinline__ void ssm_c_task(unsigned char* ws, LAS unsigned char* lds, int l, int task, int tid_in) {
;     ...
;     { const bf16* WC = (const bf16*)(ws + WS_WC) + ((size_t)(g * 1024 + wid * 128 + rr) * 256 + 8 * kk);
; #pragma unroll 1
;       for (int ks = 0; ks < 8; ++ks) {
;           bf16x8 bfr[4], afr[8];
; #pragma unroll
;           for (int a = 0; a < 8; ++a) afr[a] = *(const bf16x8*)(WC + (size_t)a * 16 * 256 + ks * 32);
; #pragma unroll
;           for (int c = 0; c < 4; ++c) bfr[c] = *(const LAS bf16x8*)(lds + SS_UB + (((ks * 4 + kk) * 64 + c * 16 + rr) * 16));
; #pragma unroll
;           for (int a = 0; a < 8; ++a)
; #pragma unroll
;               for (int c = 0; c < 4; ++c) acc[a][c] = __builtin_amdgcn_mfma_f32_16x16x32_bf16(afr[a], bfr[c], acc[a][c], 0, 0, 0);
;       } }
	v_mfma_f32_16x16x32_bf16 v[48:51], v[204:207], v[232:235], v[48:51]
	v_mfma_f32_16x16x32_bf16 v[40:43], v[204:207], v[236:239], v[40:43]
	v_mfma_f32_16x16x32_bf16 v[36:39], v[204:207], v[240:243], v[36:39]
	v_mfma_f32_16x16x32_bf16 v[32:35], v[204:207], v[244:247], v[32:35]
	global_load_dwordx4 v[204:207], v[190:191], off
	v_lshl_add_u64 v[190:191], v[190:191], 0, s[50:51]
	s_waitcnt vmcnt(6)
	v_mfma_f32_16x16x32_bf16 v[28:31], v[208:211], v[232:235], v[28:31]
	v_mfma_f32_16x16x32_bf16 v[24:27], v[208:211], v[236:239], v[24:27]
	v_mfma_f32_16x16x32_bf16 v[20:23], v[208:211], v[240:243], v[20:23]
	v_mfma_f32_16x16x32_bf16 v[16:19], v[208:211], v[244:247], v[16:19]
	global_load_dwordx4 v[208:211], v[190:191], off
	v_lshl_add_u64 v[190:191], v[190:191], 0, s[50:51]
	s_waitcnt vmcnt(6)
	v_mfma_f32_16x16x32_bf16 v[12:15], v[212:215], v[232:235], v[12:15]
	v_mfma_f32_16x16x32_bf16 v[8:11], v[212:215], v[236:239], v[8:11]
	v_mfma_f32_16x16x32_bf16 v[4:7], v[212:215], v[240:243], v[4:7]
	v_mfma_f32_16x16x32_bf16 v[0:3], v[212:215], v[244:247], v[0:3]
	global_load_dwordx4 v[212:215], v[190:191], off
	v_lshl_add_u64 v[190:191], v[190:191], 0, s[50:51]
	s_waitcnt lgkmcnt(0)
	s_waitcnt vmcnt(6)
	v_mfma_f32_16x16x32_bf16 v[128:131], v[170:173], v[44:47], v[128:131]
	v_mfma_f32_16x16x32_bf16 v[124:127], v[170:173], v[174:177], v[124:127]
	v_mfma_f32_16x16x32_bf16 v[120:123], v[170:173], v[178:181], v[120:123]
	v_mfma_f32_16x16x32_bf16 v[116:119], v[170:173], v[186:189], v[116:119]
	global_load_dwordx4 v[170:173], v[190:191], off
	v_lshl_add_u64 v[190:191], v[190:191], 0, s[62:63]
	ds_read_b128 v[232:235], v169 offset:28672
	ds_read_b128 v[236:239], v169 offset:28928
	ds_read_b128 v[240:243], v169 offset:29184
	ds_read_b128 v[244:247], v169 offset:29440
	s_waitcnt vmcnt(6)
	v_mfma_f32_16x16x32_bf16 v[112:115], v[192:195], v[44:47], v[112:115]
	v_mfma_f32_16x16x32_bf16 v[108:111], v[192:195], v[174:177], v[108:111]
	v_mfma_f32_16x16x32_bf16 v[104:107], v[192:195], v[178:181], v[104:107]
	v_mfma_f32_16x16x32_bf16 v[100:103], v[192:195], v[186:189], v[100:103]
	global_load_dwordx4 v[192:195], v[190:191], off
	v_lshl_add_u64 v[190:191], v[190:191], 0, s[50:51]
	s_waitcnt vmcnt(6)
	v_mfma_f32_16x16x32_bf16 v[96:99], v[196:199], v[44:47], v[96:99]
	v_mfma_f32_16x16x32_bf16 v[92:95], v[196:199], v[174:177], v[92:95]
	v_mfma_f32_16x16x32_bf16 v[88:91], v[196:199], v[178:181], v[88:91]
	v_mfma_f32_16x16x32_bf16 v[84:87], v[196:199], v[186:189], v[84:87]
	global_load_dwordx4 v[196:199], v[190:191], off
	v_lshl_add_u64 v[190:191], v[190:191], 0, s[50:51]
	s_waitcnt vmcnt(6)
	v_mfma_f32_16x16x32_bf16 v[80:83], v[200:203], v[44:47], v[80:83]
	v_mfma_f32_16x16x32_bf16 v[76:79], v[200:203], v[174:177], v[76:79]
	v_mfma_f32_16x16x32_bf16 v[72:75], v[200:203], v[178:181], v[72:75]
	v_mfma_f32_16x16x32_bf16 v[68:71], v[200:203], v[186:189], v[68:71]
	global_load_dwordx4 v[200:203], v[190:191], off
	v_lshl_add_u64 v[190:191], v[190:191], 0, s[50:51]
	s_waitcnt vmcnt(6)
	v_mfma_f32_16x16x32_bf16 v[64:67], v[204:207], v[44:47], v[64:67]
	v_mfma_f32_16x16x32_bf16 v[60:63], v[204:207], v[174:177], v[60:63]
	v_mfma_f32_16x16x32_bf16 v[56:59], v[204:207], v[178:181], v[56:59]
	v_mfma_f32_16x16x32_bf16 v[52:55], v[204:207], v[186:189], v[52:55]
	global_load_dwordx4 v[204:207], v[190:191], off
	v_lshl_add_u64 v[190:191], v[190:191], 0, s[50:51]
	s_waitcnt vmcnt(6)
	v_mfma_f32_16x16x32_bf16 v[48:51], v[208:211], v[44:47], v[48:51]
	v_mfma_f32_16x16x32_bf16 v[40:43], v[208:211], v[174:177], v[40:43]
	v_mfma_f32_16x16x32_bf16 v[36:39], v[208:211], v[178:181], v[36:39]
	v_mfma_f32_16x16x32_bf16 v[32:35], v[208:211], v[186:189], v[32:35]
	global_load_dwordx4 v[208:211], v[190:191], off
	v_lshl_add_u64 v[190:191], v[190:191], 0, s[50:51]
	s_waitcnt vmcnt(6)
	v_mfma_f32_16x16x32_bf16 v[28:31], v[212:215], v[44:47], v[28:31]
	v_mfma_f32_16x16x32_bf16 v[24:27], v[212:215], v[174:177], v[24:27]
	v_mfma_f32_16x16x32_bf16 v[20:23], v[212:215], v[178:181], v[20:23]
	v_mfma_f32_16x16x32_bf16 v[16:19], v[212:215], v[186:189], v[16:19]
	global_load_dwordx4 v[212:215], v[190:191], off
	v_lshl_add_u64 v[190:191], v[190:191], 0, s[50:51]
	s_waitcnt vmcnt(6)
	v_mfma_f32_16x16x32_bf16 v[12:15], v[170:173], v[44:47], v[12:15]
	v_mfma_f32_16x16x32_bf16 v[8:11], v[170:173], v[174:177], v[8:11]
	v_mfma_f32_16x16x32_bf16 v[4:7], v[170:173], v[178:181], v[4:7]
	v_mfma_f32_16x16x32_bf16 v[0:3], v[170:173], v[186:189], v[0:3]
	global_load_dwordx4 v[170:173], v[190:191], off
	v_lshl_add_u64 v[190:191], v[190:191], 0, s[50:51]
	s_waitcnt lgkmcnt(0)
	s_waitcnt vmcnt(6)
	v_mfma_f32_16x16x32_bf16 v[128:131], v[192:195], v[232:235], v[128:131]
	v_mfma_f32_16x16x32_bf16 v[124:127], v[192:195], v[236:239], v[124:127]
	v_mfma_f32_16x16x32_bf16 v[120:123], v[192:195], v[240:243], v[120:123]
	v_mfma_f32_16x16x32_bf16 v[116:119], v[192:195], v[244:247], v[116:119]
	global_load_dwordx4 v[192:195], v[190:191], off
	v_lshl_add_u64 v[190:191], v[190:191], 0, s[62:63]
	s_waitcnt vmcnt(6)
	v_mfma_f32_16x16x32_bf16 v[112:115], v[196:199], v[232:235], v[112:115]
	v_mfma_f32_16x16x32_bf16 v[108:111], v[196:199], v[236:239], v[108:111]
	v_mfma_f32_16x16x32_bf16 v[104:107], v[196:199], v[240:243], v[104:107]
	v_mfma_f32_16x16x32_bf16 v[100:103], v[196:199], v[244:247], v[100:103]
	s_waitcnt vmcnt(5)
	v_mfma_f32_16x16x32_bf16 v[96:99], v[200:203], v[232:235], v[96:99]
	v_mfma_f32_16x16x32_bf16 v[92:95], v[200:203], v[236:239], v[92:95]
	v_mfma_f32_16x16x32_bf16 v[88:91], v[200:203], v[240:243], v[88:91]
	v_mfma_f32_16x16x32_bf16 v[84:87], v[200:203], v[244:247], v[84:87]
	s_waitcnt vmcnt(4)
; #define LAS __attribute__((address_space(3)))
; __device__ __forceinline__ unsigned pk2(float lo, float hi) { return pg8::cvt_pk_bf16(lo, hi); }
; template <int PMODE> __device__ __forceinline__ void ssm_c_task(unsigned char* ws, LAS unsigned char* lds, int l, int task, int tid_in) {
;     ...
;       for (int ks = 0; ks < 8; ++ks) {
;           bf16x8 bfr[4], afr[8];
; #pragma unroll
;           for (int a = 0; a < 8; ++a) afr[a] = *(const bf16x8*)(WC + (size_t)a * 16 * 256 + ks * 32);
; #pragma unroll
;           for (int c = 0; c < 4; ++c) bfr[c] = *(const LAS bf16x8*)(lds + SS_UB + (((ks * 4 + kk) * 64 + c * 16 + rr) * 16));
; #pragma unroll
;           for (int a = 0; a < 8; ++a)
; #pragma unroll
;               for (int c = 0; c < 4; ++c) acc[a][c] = __builtin_amdgcn_mfma_f32_16x16x32_bf16(afr[a], bfr[c], acc[a][c], 0, 0, 0);
;       } }
;     __syncthreads();
;     if (PMODE == 1) {
; #pragma unroll
;         for (int a = 0; a < 8; ++a)
; #pragma unroll
;             for (int c = 0; c < 4; ++c) asm volatile("" :: "v"(acc[a][c]));
;         return; }
;     int rr_e = rr; asm volatile("" : "+v"(rr_e));
;     bf16* yb = (bf16*)(ws + AR_YG) + ((size_t)g * NTOK + (size_t)cb * 4096 + (size_t)rr_e * 64 + wid * 8) * 16 + 4 * kk;
;     const f32x4 dv = *(const f32x4*)((const float*)(ws + WS_SMALL) + SM_DD + (size_t)l * NG * NP + g * NP + 4 * kk);
; #pragma unroll
;     for (int a0 = 0; a0 < 8; a0 += 4) {
;         u32x2 uw[4][4];
; #pragma unroll
;         for (int a = 0; a < 4; ++a)
; #pragma unroll
;             for (int c = 0; c < 4; ++c) { const int col = cb * 64 + c * 16 + rr_e; const size_t tok = (size_t)col * 64 + wid * 8 + a0 + a; uw[a][c] = *(const u32x2*)(U + tok * 512 + g * 16 + 4 * kk); }
; #pragma unroll
;         for (int a = 0; a < 4; ++a)
; #pragma unroll
;             for (int c = 0; c < 4; ++c) { const int col = cb * 64 + c * 16 + rr_e; const size_t tok = (size_t)col * 64 + wid * 8 + a0 + a;
;                 const f32x4 av = acc[a0 + a][c];
;                 const float y0 = av[0] + dv[0] * bflo(uw[a][c].x), y1 = av[1] + dv[1] * bfhi(uw[a][c].x), y2 = av[2] + dv[2] * bflo(uw[a][c].y), y3 = av[3] + dv[3] * bfhi(uw[a][c].y);
;                 u32x2 o; o.x = pk2(gelu_tanh(y0), gelu_tanh(y1)); o.y = pk2(gelu_tanh(y2), gelu_tanh(y3));
;                 if (PMODE == 4) asm volatile("" :: "v"(o)); else *(u32x2*)(yb + (c * 1024 + a0 + a) * 16) = o; }
	v_mfma_f32_16x16x32_bf16 v[80:83], v[204:207], v[232:235], v[80:83]
	v_mfma_f32_16x16x32_bf16 v[76:79], v[204:207], v[236:239], v[76:79]
	v_mfma_f32_16x16x32_bf16 v[72:75], v[204:207], v[240:243], v[72:75]
	v_mfma_f32_16x16x32_bf16 v[68:71], v[204:207], v[244:247], v[68:71]
	s_waitcnt vmcnt(3)
	v_mfma_f32_16x16x32_bf16 v[64:67], v[208:211], v[232:235], v[64:67]
	v_mfma_f32_16x16x32_bf16 v[60:63], v[208:211], v[236:239], v[60:63]
	v_mfma_f32_16x16x32_bf16 v[56:59], v[208:211], v[240:243], v[56:59]
	v_mfma_f32_16x16x32_bf16 v[52:55], v[208:211], v[244:247], v[52:55]
	s_waitcnt vmcnt(2)
	v_mfma_f32_16x16x32_bf16 v[48:51], v[212:215], v[232:235], v[48:51]
	v_mfma_f32_16x16x32_bf16 v[40:43], v[212:215], v[236:239], v[40:43]
	v_mfma_f32_16x16x32_bf16 v[36:39], v[212:215], v[240:243], v[36:39]
	v_mfma_f32_16x16x32_bf16 v[32:35], v[212:215], v[244:247], v[32:35]
	s_waitcnt vmcnt(1)
	v_mfma_f32_16x16x32_bf16 v[28:31], v[170:173], v[232:235], v[28:31]
	v_mfma_f32_16x16x32_bf16 v[24:27], v[170:173], v[236:239], v[24:27]
	v_mfma_f32_16x16x32_bf16 v[20:23], v[170:173], v[240:243], v[20:23]
	v_mfma_f32_16x16x32_bf16 v[16:19], v[170:173], v[244:247], v[16:19]
	s_waitcnt vmcnt(0)
	v_mfma_f32_16x16x32_bf16 v[12:15], v[192:195], v[232:235], v[12:15]
	v_mfma_f32_16x16x32_bf16 v[8:11], v[192:195], v[236:239], v[8:11]
	v_mfma_f32_16x16x32_bf16 v[4:7], v[192:195], v[240:243], v[4:7]
	v_mfma_f32_16x16x32_bf16 v[0:3], v[192:195], v[244:247], v[0:3]
	v_mov_b32_e32 v132, v216
	s_barrier
	v_mov_b32_e32 v169, v185
	v_lshl_add_u32 v170, s16, 6, v132
	v_ashrrev_i32_e32 v171, 31, v170
	v_lshl_add_u64 v[174:175], s[60:61], 0, v[168:169]
	v_lshlrev_b64 v[44:45], 16, v[170:171]
	v_lshl_add_u64 v[134:135], v[174:175], 0, v[44:45]
	v_lshl_add_u64 v[176:177], v[134:135], 0, v[156:157]
	global_load_dwordx2 v[186:187], v[176:177], off
	v_lshl_add_u64 v[44:45], s[58:59], 2, v[154:155]
	global_load_dwordx4 v[44:47], v[44:45], off
	v_ashrrev_i32_e32 v133, 31, v132
	v_lshlrev_b64 v[132:133], 11, v[132:133]
	v_add_u32_e32 v178, 16, v170
	v_lshl_add_u64 v[172:173], s[88:89], 0, v[152:153]
	s_lshl_b64 s[14:15], s[56:57], 20
	v_lshl_add_u64 v[132:133], s[18:19], 0, v[132:133]
	v_ashrrev_i32_e32 v179, 31, v178
	v_lshlrev_b64 v[172:173], 5, v[172:173]
	v_lshl_add_u64 v[132:133], v[132:133], 0, s[14:15]
	v_lshlrev_b64 v[178:179], 16, v[178:179]
	v_lshl_add_u64 v[132:133], v[132:133], 0, v[172:173]
	v_lshl_add_u64 v[172:173], v[174:175], 0, v[178:179]
	v_lshl_add_u64 v[178:179], v[172:173], 0, v[156:157]
	global_load_dwordx2 v[214:215], v[178:179], off
	v_add_u32_e32 v180, 32, v170
	v_add_u32_e32 v170, 48, v170
	v_ashrrev_i32_e32 v181, 31, v180
	v_ashrrev_i32_e32 v171, 31, v170
	v_lshlrev_b64 v[180:181], 16, v[180:181]
	v_lshlrev_b64 v[182:183], 16, v[170:171]
	v_lshl_add_u64 v[170:171], v[174:175], 0, v[180:181]
	v_lshl_add_u64 v[174:175], v[174:175], 0, v[182:183]
	v_lshl_add_u64 v[132:133], v[132:133], 0, v[168:169]
	v_lshl_add_u64 v[188:189], v[170:171], 0, v[156:157]
	v_lshl_add_u64 v[190:191], v[174:175], 0, v[156:157]
	global_load_dwordx2 v[208:209], v[176:177], off offset:1024
	global_load_dwordx2 v[200:201], v[176:177], off offset:2048
	global_load_dwordx2 v[182:183], v[176:177], off offset:3072
	global_load_dwordx2 v[212:213], v[188:189], off
	global_load_dwordx2 v[206:207], v[178:179], off offset:1024
	global_load_dwordx2 v[198:199], v[178:179], off offset:2048
	global_load_dwordx2 v[180:181], v[178:179], off offset:3072
	global_load_dwordx2 v[210:211], v[190:191], off
	global_load_dwordx2 v[204:205], v[188:189], off offset:1024
	global_load_dwordx2 v[196:197], v[188:189], off offset:2048
	s_nop 0
	global_load_dwordx2 v[178:179], v[188:189], off offset:3072
	global_load_dwordx2 v[202:203], v[190:191], off offset:1024
	global_load_dwordx2 v[194:195], v[190:191], off offset:2048
	global_load_dwordx2 v[176:177], v[190:191], off offset:3072
	s_mov_b32 s3, 0x8000
	s_add_i32 s54, s54, s76
	s_cmpk_gt_i32 s54, 0xff
	s_waitcnt vmcnt(16)
	v_lshlrev_b32_e32 v169, 16, v186
	v_and_b32_e32 v184, 0xffff0000, v186
	v_lshlrev_b32_e32 v186, 16, v187
	s_waitcnt vmcnt(15)
	v_fma_f32 v128, v44, v169, v128
	v_fma_f32 v129, v45, v184, v129
	v_fma_f32 v130, v46, v186, v130
	v_mul_f32_e32 v169, 0x3d372713, v128
	v_mul_f32_e32 v186, 0x3d372713, v129
	v_and_b32_e32 v187, 0xffff0000, v187
	v_mul_f32_e32 v169, v128, v169
	v_mul_f32_e32 v186, v129, v186
	v_fmac_f32_e32 v131, v47, v187
	v_mul_f32_e32 v184, 0.5, v128
	v_mul_f32_e32 v187, 0.5, v129
	v_mul_f32_e32 v188, 0x3d372713, v130
	v_fma_f32 v128, v128, v169, v128
	v_fma_f32 v129, v129, v186, v129
	v_mul_f32_e32 v188, v130, v188
	v_mul_f32_e32 v128, 0x3f4c422a, v128
	v_mul_f32_e32 v129, 0x3f4c422a, v129
	v_mul_f32_e32 v189, 0x3d372713, v131
	v_fma_f32 v169, v130, v188, v130
	v_add_f32_e32 v128, v128, v128
	v_add_f32_e32 v129, v129, v129
	v_mul_f32_e32 v189, v131, v189
	v_mul_f32_e32 v169, 0x3f4c422a, v169
	v_mul_f32_e32 v128, 0x3fb8aa3b, v128
	v_mul_f32_e32 v129, 0x3fb8aa3b, v129
	v_fma_f32 v186, v131, v189, v131
	v_add_f32_e32 v169, v169, v169
	v_exp_f32_e32 v128, v128
	v_exp_f32_e32 v129, v129
	v_mul_f32_e32 v186, 0x3f4c422a, v186
	v_mul_f32_e32 v169, 0x3fb8aa3b, v169
	v_add_f32_e32 v186, v186, v186
	v_exp_f32_e32 v169, v169
	v_mul_f32_e32 v186, 0x3fb8aa3b, v186
	v_exp_f32_e32 v186, v186
	v_add_f32_e32 v128, 1.0, v128
	v_add_f32_e32 v129, 1.0, v129
	v_rcp_f32_e32 v128, v128
	v_rcp_f32_e32 v129, v129
	v_add_f32_e32 v169, 1.0, v169
	v_rcp_f32_e32 v169, v169
	v_add_f32_e32 v186, 1.0, v186
	v_rcp_f32_e32 v186, v186
	v_fma_f32 v128, v128, -2.0, 1.0
	v_fma_f32 v129, v129, -2.0, 1.0
	v_add_f32_e32 v128, 1.0, v128
	v_add_f32_e32 v129, 1.0, v129
	v_fma_f32 v169, v169, -2.0, 1.0
	v_mul_f32_e32 v128, v184, v128
	v_mul_f32_e32 v129, v187, v129
	v_cvt_pk_bf16_f32 v128, v128, v129
	v_mul_f32_e32 v129, 0.5, v130
	v_add_f32_e32 v130, 1.0, v169
	v_mul_f32_e32 v129, v129, v130
	v_fma_f32 v130, v186, -2.0, 1.0
	v_mul_f32_e32 v131, 0.5, v131
	v_add_f32_e32 v130, 1.0, v130
	v_mul_f32_e32 v130, v131, v130
	v_cvt_pk_bf16_f32 v129, v129, v130
	global_store_dwordx2 v[132:133], v[128:129], off
	s_waitcnt vmcnt(15)
; __device__ __forceinline__ unsigned pk2(float lo, float hi) { return pg8::cvt_pk_bf16(lo, hi); }
; __device__ __forceinline__ float gelu_tanh(float x) { const float z = 0.7978845608028654f * (x + 0.044715f * x * x * x); const float t = 1.f - 2.f * __builtin_amdgcn_rcpf(__expf(2.f * z) + 1.f); return 0.5f * x * (1.f + t); }
; template <int PMODE> __device__ __forceinline__ void ssm_c_task(unsigned char* ws, LAS unsigned char* lds, int l, int task, int tid_in) {
;     ...
;     for (int a0 = 0; a0 < 8; a0 += 4) {
;         u32x2 uw[4][4];
; #pragma unroll
;         for (int a = 0; a < 4; ++a)
; #pragma unroll
;             for (int c = 0; c < 4; ++c) { const int col = cb * 64 + c * 16 + rr_e; const size_t tok = (size_t)col * 64 + wid * 8 + a0 + a; uw[a][c] = *(const u32x2*)(U + tok * 512 + g * 16 + 4 * kk); }
; #pragma unroll
;         for (int a = 0; a < 4; ++a)
; #pragma unroll
;             for (int c = 0; c < 4; ++c) { const int col = cb * 64 + c * 16 + rr_e; const size_t tok = (size_t)col * 64 + wid * 8 + a0 + a;
;                 const f32x4 av = acc[a0 + a][c];
;                 const float y0 = av[0] + dv[0] * bflo(uw[a][c].x), y1 = av[1] + dv[1] * bfhi(uw[a][c].x), y2 = av[2] + dv[2] * bflo(uw[a][c].y), y3 = av[3] + dv[3] * bfhi(uw[a][c].y);
;                 u32x2 o; o.x = pk2(gelu_tanh(y0), gelu_tanh(y1)); o.y = pk2(gelu_tanh(y2), gelu_tanh(y3));
;                 if (PMODE == 4) asm volatile("" :: "v"(o)); else *(u32x2*)(yb + (c * 1024 + a0 + a) * 16) = o; }
	v_lshlrev_b32_e32 v128, 16, v214
	v_fma_f32 v124, v44, v128, v124
	v_mul_f32_e32 v128, 0x3d372713, v124
	v_mul_f32_e32 v128, v124, v128
	v_fma_f32 v128, v124, v128, v124
	v_mul_f32_e32 v128, 0x3f4c422a, v128
	v_add_f32_e32 v128, v128, v128
	v_mul_f32_e32 v128, 0x3fb8aa3b, v128
	v_exp_f32_e32 v128, v128
	v_and_b32_e32 v129, 0xffff0000, v214
	v_fma_f32 v125, v45, v129, v125
	v_lshlrev_b32_e32 v129, 16, v215
	v_add_f32_e32 v128, 1.0, v128
	v_rcp_f32_e32 v128, v128
	v_fma_f32 v129, v46, v129, v126
	v_and_b32_e32 v126, 0xffff0000, v215
	v_fmac_f32_e32 v127, v47, v126
	v_fma_f32 v126, v128, -2.0, 1.0
	v_mul_f32_e32 v128, 0x3d372713, v125
	v_mul_f32_e32 v128, v125, v128
	v_fma_f32 v128, v125, v128, v125
	v_mul_f32_e32 v128, 0x3f4c422a, v128
	v_add_f32_e32 v128, v128, v128
	v_mul_f32_e32 v128, 0x3fb8aa3b, v128
	v_exp_f32_e32 v128, v128
	v_mul_f32_e32 v124, 0.5, v124
	v_add_f32_e32 v126, 1.0, v126
	v_mul_f32_e32 v124, v124, v126
	v_add_f32_e32 v126, 1.0, v128
	v_mul_f32_e32 v128, 0x3d372713, v129
	v_mul_f32_e32 v128, v129, v128
	v_mul_f32_e32 v130, 0x3d372713, v127
	v_fma_f32 v128, v129, v128, v129
	v_mul_f32_e32 v130, v127, v130
	v_mul_f32_e32 v128, 0x3f4c422a, v128
	v_fma_f32 v130, v127, v130, v127
	v_rcp_f32_e32 v126, v126
	v_add_f32_e32 v128, v128, v128
	v_mul_f32_e32 v130, 0x3f4c422a, v130
	v_mul_f32_e32 v128, 0x3fb8aa3b, v128
	v_add_f32_e32 v130, v130, v130
	v_exp_f32_e32 v128, v128
	v_mul_f32_e32 v130, 0x3fb8aa3b, v130
	v_exp_f32_e32 v130, v130
	v_fma_f32 v126, v126, -2.0, 1.0
	v_mul_f32_e32 v125, 0.5, v125
	v_add_f32_e32 v126, 1.0, v126
	v_add_f32_e32 v128, 1.0, v128
	v_mul_f32_e32 v125, v125, v126
	v_rcp_f32_e32 v128, v128
	v_cvt_pk_bf16_f32 v126, v124, v125
	v_add_f32_e32 v125, 1.0, v130
	v_rcp_f32_e32 v125, v125
	v_fma_f32 v124, v128, -2.0, 1.0
	v_mul_f32_e32 v128, 0.5, v129
	v_add_f32_e32 v124, 1.0, v124
	v_fma_f32 v125, v125, -2.0, 1.0
	v_mul_f32_e32 v124, v128, v124
	v_mul_f32_e32 v127, 0.5, v127
	v_add_f32_e32 v125, 1.0, v125
	v_mul_f32_e32 v125, v127, v125
	v_cvt_pk_bf16_f32 v127, v124, v125
	v_add_co_u32_e64 v124, s[50:51], s3, v132
	s_mov_b32 s3, 0x10000
	s_nop 0
	v_addc_co_u32_e64 v125, s[50:51], 0, v133, s[50:51]
	global_store_dwordx2 v[124:125], v[126:127], off
	s_waitcnt vmcnt(12)
	v_lshlrev_b32_e32 v126, 16, v212
	v_fma_f32 v120, v44, v126, v120
	v_mul_f32_e32 v126, 0x3d372713, v120
	v_mul_f32_e32 v126, v120, v126
	v_fma_f32 v126, v120, v126, v120
	v_mul_f32_e32 v126, 0x3f4c422a, v126
	v_add_f32_e32 v126, v126, v126
	v_mul_f32_e32 v126, 0x3fb8aa3b, v126
	v_exp_f32_e32 v126, v126
	v_and_b32_e32 v127, 0xffff0000, v212
	v_fma_f32 v121, v45, v127, v121
	v_lshlrev_b32_e32 v127, 16, v213
	v_add_f32_e32 v126, 1.0, v126
	v_rcp_f32_e32 v126, v126
	v_fma_f32 v127, v46, v127, v122
	v_and_b32_e32 v122, 0xffff0000, v213
	v_fmac_f32_e32 v123, v47, v122
	v_fma_f32 v122, v126, -2.0, 1.0
	v_mul_f32_e32 v126, 0x3d372713, v121
	v_mul_f32_e32 v126, v121, v126
	v_fma_f32 v126, v121, v126, v121
	v_mul_f32_e32 v126, 0x3f4c422a, v126
	v_add_f32_e32 v126, v126, v126
	v_mul_f32_e32 v126, 0x3fb8aa3b, v126
	v_exp_f32_e32 v126, v126
	v_mul_f32_e32 v120, 0.5, v120
	v_add_f32_e32 v122, 1.0, v122
	v_mul_f32_e32 v120, v120, v122
	v_add_f32_e32 v122, 1.0, v126
	v_mul_f32_e32 v126, 0x3d372713, v127
	v_mul_f32_e32 v126, v127, v126
	v_mul_f32_e32 v128, 0x3d372713, v123
	v_fma_f32 v126, v127, v126, v127
	v_mul_f32_e32 v128, v123, v128
	v_mul_f32_e32 v126, 0x3f4c422a, v126
	v_fma_f32 v128, v123, v128, v123
	v_rcp_f32_e32 v122, v122
	v_add_f32_e32 v126, v126, v126
	v_mul_f32_e32 v128, 0x3f4c422a, v128
	v_mul_f32_e32 v126, 0x3fb8aa3b, v126
	v_add_f32_e32 v128, v128, v128
	v_exp_f32_e32 v126, v126
	v_mul_f32_e32 v128, 0x3fb8aa3b, v128
	v_exp_f32_e32 v128, v128
	v_fma_f32 v122, v122, -2.0, 1.0
	v_mul_f32_e32 v121, 0.5, v121
	v_add_f32_e32 v122, 1.0, v122
	v_add_f32_e32 v126, 1.0, v126
	v_mul_f32_e32 v121, v121, v122
	v_rcp_f32_e32 v126, v126
	v_cvt_pk_bf16_f32 v122, v120, v121
	v_add_f32_e32 v121, 1.0, v128
	v_rcp_f32_e32 v121, v121
	v_fma_f32 v120, v126, -2.0, 1.0
	v_mul_f32_e32 v126, 0.5, v127
	v_add_f32_e32 v120, 1.0, v120
	v_fma_f32 v121, v121, -2.0, 1.0
	v_mul_f32_e32 v120, v126, v120
	v_mul_f32_e32 v123, 0.5, v123
	v_add_f32_e32 v121, 1.0, v121
	v_mul_f32_e32 v121, v123, v121
	v_cvt_pk_bf16_f32 v123, v120, v121
	v_add_co_u32_e64 v120, s[50:51], s3, v132
	s_mov_b32 s3, 0x18000
	s_nop 0
	v_addc_co_u32_e64 v121, s[50:51], 0, v133, s[50:51]
	global_store_dwordx2 v[120:121], v[122:123], off
	s_waitcnt vmcnt(9)
; __device__ __forceinline__ unsigned pk2(float lo, float hi) { return pg8::cvt_pk_bf16(lo, hi); }
; __device__ __forceinline__ float gelu_tanh(float x) { const float z = 0.7978845608028654f * (x + 0.044715f * x * x * x); const float t = 1.f - 2.f * __builtin_amdgcn_rcpf(__expf(2.f * z) + 1.f); return 0.5f * x * (1.f + t); }
; template <int PMODE> __device__ __forceinline__ void ssm_c_task(unsigned char* ws, LAS unsigned char* lds, int l, int task, int tid_in) {
;     ...
;     for (int a0 = 0; a0 < 8; a0 += 4) {
;         u32x2 uw[4][4];
; #pragma unroll
;         for (int a = 0; a < 4; ++a)
; #pragma unroll
;             for (int c = 0; c < 4; ++c) { const int col = cb * 64 + c * 16 + rr_e; const size_t tok = (size_t)col * 64 + wid * 8 + a0 + a; uw[a][c] = *(const u32x2*)(U + tok * 512 + g * 16 + 4 * kk); }
; #pragma unroll
;         for (int a = 0; a < 4; ++a)
; #pragma unroll
;             for (int c = 0; c < 4; ++c) { const int col = cb * 64 + c * 16 + rr_e; const size_t tok = (size_t)col * 64 + wid * 8 + a0 + a;
;                 const f32x4 av = acc[a0 + a][c];
;                 const float y0 = av[0] + dv[0] * bflo(uw[a][c].x), y1 = av[1] + dv[1] * bfhi(uw[a][c].x), y2 = av[2] + dv[2] * bflo(uw[a][c].y), y3 = av[3] + dv[3] * bfhi(uw[a][c].y);
;                 u32x2 o; o.x = pk2(gelu_tanh(y0), gelu_tanh(y1)); o.y = pk2(gelu_tanh(y2), gelu_tanh(y3));
;                 if (PMODE == 4) asm volatile("" :: "v"(o)); else *(u32x2*)(yb + (c * 1024 + a0 + a) * 16) = o; }
	v_lshlrev_b32_e32 v122, 16, v210
	v_fma_f32 v116, v44, v122, v116
	v_mul_f32_e32 v122, 0x3d372713, v116
	v_mul_f32_e32 v122, v116, v122
	v_fma_f32 v122, v116, v122, v116
	v_mul_f32_e32 v122, 0x3f4c422a, v122
	v_add_f32_e32 v122, v122, v122
	v_mul_f32_e32 v122, 0x3fb8aa3b, v122
	v_exp_f32_e32 v122, v122
	v_and_b32_e32 v123, 0xffff0000, v210
	v_fma_f32 v117, v45, v123, v117
	v_lshlrev_b32_e32 v123, 16, v211
	v_add_f32_e32 v122, 1.0, v122
	v_rcp_f32_e32 v122, v122
	v_fma_f32 v123, v46, v123, v118
	v_and_b32_e32 v118, 0xffff0000, v211
	v_fmac_f32_e32 v119, v47, v118
	v_fma_f32 v118, v122, -2.0, 1.0
	v_mul_f32_e32 v122, 0x3d372713, v117
	v_mul_f32_e32 v122, v117, v122
	v_fma_f32 v122, v117, v122, v117
	v_mul_f32_e32 v122, 0x3f4c422a, v122
	v_add_f32_e32 v122, v122, v122
	v_mul_f32_e32 v122, 0x3fb8aa3b, v122
	v_exp_f32_e32 v122, v122
	v_mul_f32_e32 v116, 0.5, v116
	v_add_f32_e32 v118, 1.0, v118
	v_mul_f32_e32 v116, v116, v118
	v_add_f32_e32 v118, 1.0, v122
	v_mul_f32_e32 v122, 0x3d372713, v123
	v_mul_f32_e32 v122, v123, v122
	v_mul_f32_e32 v126, 0x3d372713, v119
	v_fma_f32 v122, v123, v122, v123
	v_mul_f32_e32 v126, v119, v126
	v_mul_f32_e32 v122, 0x3f4c422a, v122
	v_fma_f32 v126, v119, v126, v119
	v_rcp_f32_e32 v118, v118
	v_add_f32_e32 v122, v122, v122
	v_mul_f32_e32 v126, 0x3f4c422a, v126
	v_mul_f32_e32 v122, 0x3fb8aa3b, v122
	v_add_f32_e32 v126, v126, v126
	v_exp_f32_e32 v122, v122
	v_mul_f32_e32 v126, 0x3fb8aa3b, v126
	v_exp_f32_e32 v126, v126
	v_fma_f32 v118, v118, -2.0, 1.0
	v_mul_f32_e32 v117, 0.5, v117
	v_add_f32_e32 v118, 1.0, v118
	v_add_f32_e32 v122, 1.0, v122
	v_mul_f32_e32 v117, v117, v118
	v_rcp_f32_e32 v122, v122
	v_cvt_pk_bf16_f32 v118, v116, v117
	v_add_f32_e32 v117, 1.0, v126
	v_rcp_f32_e32 v117, v117
	v_fma_f32 v116, v122, -2.0, 1.0
	v_mul_f32_e32 v122, 0.5, v123
	v_add_f32_e32 v116, 1.0, v116
	v_fma_f32 v117, v117, -2.0, 1.0
	v_mul_f32_e32 v116, v122, v116
	v_mul_f32_e32 v119, 0.5, v119
	v_add_f32_e32 v117, 1.0, v117
	v_mul_f32_e32 v117, v119, v117
	v_cvt_pk_bf16_f32 v119, v116, v117
	v_add_co_u32_e64 v116, s[50:51], s3, v132
	s_nop 1
	v_addc_co_u32_e64 v117, s[50:51], 0, v133, s[50:51]
	global_store_dwordx2 v[116:117], v[118:119], off
	v_lshlrev_b32_e32 v118, 16, v208
	v_fma_f32 v112, v44, v118, v112
	v_mul_f32_e32 v118, 0x3d372713, v112
	v_mul_f32_e32 v118, v112, v118
	v_fma_f32 v118, v112, v118, v112
	v_mul_f32_e32 v118, 0x3f4c422a, v118
	v_add_f32_e32 v118, v118, v118
	v_and_b32_e32 v119, 0xffff0000, v208
	v_mul_f32_e32 v118, 0x3fb8aa3b, v118
	v_fma_f32 v113, v45, v119, v113
	v_lshlrev_b32_e32 v119, 16, v209
	v_exp_f32_e32 v118, v118
	v_fma_f32 v114, v46, v119, v114
	v_and_b32_e32 v119, 0xffff0000, v209
	v_fmac_f32_e32 v115, v47, v119
	v_mul_f32_e32 v119, 0x3d372713, v113
	v_mul_f32_e32 v119, v113, v119
	v_fma_f32 v119, v113, v119, v113
	v_add_f32_e32 v118, 1.0, v118
	v_mul_f32_e32 v119, 0x3f4c422a, v119
	v_rcp_f32_e32 v118, v118
	v_add_f32_e32 v119, v119, v119
	v_mul_f32_e32 v119, 0x3fb8aa3b, v119
	v_exp_f32_e32 v119, v119
	v_fma_f32 v118, v118, -2.0, 1.0
	v_mul_f32_e32 v112, 0.5, v112
	v_add_f32_e32 v118, 1.0, v118
	v_mul_f32_e32 v112, v112, v118
	v_add_f32_e32 v118, 1.0, v119
	v_mul_f32_e32 v119, 0x3d372713, v114
	v_mul_f32_e32 v119, v114, v119
	v_fma_f32 v119, v114, v119, v114
	v_mul_f32_e32 v122, 0x3d372713, v115
	v_mul_f32_e32 v119, 0x3f4c422a, v119
	v_mul_f32_e32 v122, v115, v122
	v_add_f32_e32 v119, v119, v119
	v_fma_f32 v122, v115, v122, v115
	v_mul_f32_e32 v119, 0x3fb8aa3b, v119
	v_mul_f32_e32 v122, 0x3f4c422a, v122
	v_rcp_f32_e32 v118, v118
	v_exp_f32_e32 v119, v119
	v_add_f32_e32 v122, v122, v122
	v_mul_f32_e32 v122, 0x3fb8aa3b, v122
	v_exp_f32_e32 v122, v122
	v_fma_f32 v118, v118, -2.0, 1.0
	v_add_f32_e32 v119, 1.0, v119
	v_mul_f32_e32 v113, 0.5, v113
	v_add_f32_e32 v118, 1.0, v118
	v_rcp_f32_e32 v119, v119
	v_mul_f32_e32 v113, v113, v118
	v_add_f32_e32 v118, 1.0, v122
	v_rcp_f32_e32 v118, v118
	v_cvt_pk_bf16_f32 v112, v112, v113
	v_fma_f32 v113, v119, -2.0, 1.0
	v_mul_f32_e32 v114, 0.5, v114
	v_add_f32_e32 v113, 1.0, v113
	v_mul_f32_e32 v113, v114, v113
	v_fma_f32 v114, v118, -2.0, 1.0
	v_mul_f32_e32 v115, 0.5, v115
	v_add_f32_e32 v114, 1.0, v114
	v_mul_f32_e32 v114, v115, v114
	v_cvt_pk_bf16_f32 v113, v113, v114
	global_store_dwordx2 v[132:133], v[112:113], off offset:32
	v_lshlrev_b32_e32 v112, 16, v206
	v_fma_f32 v108, v44, v112, v108
	v_mul_f32_e32 v112, 0x3d372713, v108
	v_mul_f32_e32 v112, v108, v112
	v_fma_f32 v112, v108, v112, v108
	v_mul_f32_e32 v112, 0x3f4c422a, v112
	v_add_f32_e32 v112, v112, v112
	v_and_b32_e32 v113, 0xffff0000, v206
	v_mul_f32_e32 v112, 0x3fb8aa3b, v112
	v_fma_f32 v109, v45, v113, v109
	v_lshlrev_b32_e32 v113, 16, v207
	v_exp_f32_e32 v112, v112
	v_fma_f32 v110, v46, v113, v110
	v_and_b32_e32 v113, 0xffff0000, v207
	v_fmac_f32_e32 v111, v47, v113
	v_mul_f32_e32 v113, 0x3d372713, v109
	v_mul_f32_e32 v113, v109, v113
	v_fma_f32 v113, v109, v113, v109
	v_add_f32_e32 v112, 1.0, v112
	v_mul_f32_e32 v113, 0x3f4c422a, v113
	v_rcp_f32_e32 v112, v112
	v_add_f32_e32 v113, v113, v113
	v_mul_f32_e32 v113, 0x3fb8aa3b, v113
	v_exp_f32_e32 v113, v113
	v_fma_f32 v112, v112, -2.0, 1.0
	v_mul_f32_e32 v108, 0.5, v108
	v_add_f32_e32 v112, 1.0, v112
	v_mul_f32_e32 v108, v108, v112
	v_add_f32_e32 v112, 1.0, v113
	v_mul_f32_e32 v113, 0x3d372713, v110
	v_mul_f32_e32 v113, v110, v113
	v_fma_f32 v113, v110, v113, v110
	v_mul_f32_e32 v114, 0x3d372713, v111
	v_mul_f32_e32 v113, 0x3f4c422a, v113
	v_mul_f32_e32 v114, v111, v114
	v_add_f32_e32 v113, v113, v113
	v_fma_f32 v114, v111, v114, v111
	v_mul_f32_e32 v113, 0x3fb8aa3b, v113
	v_mul_f32_e32 v114, 0x3f4c422a, v114
	v_rcp_f32_e32 v112, v112
	v_exp_f32_e32 v113, v113
	v_add_f32_e32 v114, v114, v114
	v_mul_f32_e32 v114, 0x3fb8aa3b, v114
	v_exp_f32_e32 v114, v114
	v_fma_f32 v112, v112, -2.0, 1.0
	v_add_f32_e32 v113, 1.0, v113
	v_mul_f32_e32 v109, 0.5, v109
	v_add_f32_e32 v112, 1.0, v112
	v_rcp_f32_e32 v113, v113
	v_mul_f32_e32 v109, v109, v112
	v_add_f32_e32 v112, 1.0, v114
	v_rcp_f32_e32 v112, v112
	v_cvt_pk_bf16_f32 v108, v108, v109
	v_fma_f32 v109, v113, -2.0, 1.0
	v_mul_f32_e32 v110, 0.5, v110
	v_add_f32_e32 v109, 1.0, v109
	v_mul_f32_e32 v109, v110, v109
	v_fma_f32 v110, v112, -2.0, 1.0
	v_mul_f32_e32 v111, 0.5, v111
	v_add_f32_e32 v110, 1.0, v110
	v_mul_f32_e32 v110, v111, v110
	v_cvt_pk_bf16_f32 v109, v109, v110
	global_store_dwordx2 v[124:125], v[108:109], off offset:32
	s_waitcnt vmcnt(11)
; __device__ __forceinline__ unsigned pk2(float lo, float hi) { return pg8::cvt_pk_bf16(lo, hi); }
; __device__ __forceinline__ float gelu_tanh(float x) { const float z = 0.7978845608028654f * (x + 0.044715f * x * x * x); const float t = 1.f - 2.f * __builtin_amdgcn_rcpf(__expf(2.f * z) + 1.f); return 0.5f * x * (1.f + t); }
; template <int PMODE> __device__ __forceinline__ void ssm_c_task(unsigned char* ws, LAS unsigned char* lds, int l, int task, int tid_in) {
;     ...
;     for (int a0 = 0; a0 < 8; a0 += 4) {
;         u32x2 uw[4][4];
; #pragma unroll
;         for (int a = 0; a < 4; ++a)
; #pragma unroll
;             for (int c = 0; c < 4; ++c) { const int col = cb * 64 + c * 16 + rr_e; const size_t tok = (size_t)col * 64 + wid * 8 + a0 + a; uw[a][c] = *(const u32x2*)(U + tok * 512 + g * 16 + 4 * kk); }
; #pragma unroll
;         for (int a = 0; a < 4; ++a)
; #pragma unroll
;             for (int c = 0; c < 4; ++c) { const int col = cb * 64 + c * 16 + rr_e; const size_t tok = (size_t)col * 64 + wid * 8 + a0 + a;
;                 const f32x4 av = acc[a0 + a][c];
;                 const float y0 = av[0] + dv[0] * bflo(uw[a][c].x), y1 = av[1] + dv[1] * bfhi(uw[a][c].x), y2 = av[2] + dv[2] * bflo(uw[a][c].y), y3 = av[3] + dv[3] * bfhi(uw[a][c].y);
;                 u32x2 o; o.x = pk2(gelu_tanh(y0), gelu_tanh(y1)); o.y = pk2(gelu_tanh(y2), gelu_tanh(y3));
;                 if (PMODE == 4) asm volatile("" :: "v"(o)); else *(u32x2*)(yb + (c * 1024 + a0 + a) * 16) = o; }
	v_lshlrev_b32_e32 v108, 16, v204
	v_fma_f32 v104, v44, v108, v104
	v_mul_f32_e32 v108, 0x3d372713, v104
	v_mul_f32_e32 v108, v104, v108
	v_fma_f32 v108, v104, v108, v104
	v_mul_f32_e32 v108, 0x3f4c422a, v108
	v_add_f32_e32 v108, v108, v108
	v_and_b32_e32 v109, 0xffff0000, v204
	v_mul_f32_e32 v108, 0x3fb8aa3b, v108
	v_fma_f32 v105, v45, v109, v105
	v_lshlrev_b32_e32 v109, 16, v205
	v_exp_f32_e32 v108, v108
	v_fma_f32 v106, v46, v109, v106
	v_and_b32_e32 v109, 0xffff0000, v205
	v_fmac_f32_e32 v107, v47, v109
	v_mul_f32_e32 v109, 0x3d372713, v105
	v_mul_f32_e32 v109, v105, v109
	v_fma_f32 v109, v105, v109, v105
	v_add_f32_e32 v108, 1.0, v108
	v_mul_f32_e32 v109, 0x3f4c422a, v109
	v_rcp_f32_e32 v108, v108
	v_add_f32_e32 v109, v109, v109
	v_mul_f32_e32 v109, 0x3fb8aa3b, v109
	v_exp_f32_e32 v109, v109
	v_fma_f32 v108, v108, -2.0, 1.0
	v_mul_f32_e32 v104, 0.5, v104
	v_add_f32_e32 v108, 1.0, v108
	v_mul_f32_e32 v104, v104, v108
	v_add_f32_e32 v108, 1.0, v109
	v_mul_f32_e32 v109, 0x3d372713, v106
	v_mul_f32_e32 v109, v106, v109
	v_fma_f32 v109, v106, v109, v106
	v_mul_f32_e32 v110, 0x3d372713, v107
	v_mul_f32_e32 v109, 0x3f4c422a, v109
	v_mul_f32_e32 v110, v107, v110
	v_add_f32_e32 v109, v109, v109
	v_fma_f32 v110, v107, v110, v107
	v_mul_f32_e32 v109, 0x3fb8aa3b, v109
	v_mul_f32_e32 v110, 0x3f4c422a, v110
	v_rcp_f32_e32 v108, v108
	v_exp_f32_e32 v109, v109
	v_add_f32_e32 v110, v110, v110
	v_mul_f32_e32 v110, 0x3fb8aa3b, v110
	v_exp_f32_e32 v110, v110
	v_fma_f32 v108, v108, -2.0, 1.0
	v_add_f32_e32 v109, 1.0, v109
	v_mul_f32_e32 v105, 0.5, v105
	v_add_f32_e32 v108, 1.0, v108
	v_rcp_f32_e32 v109, v109
	v_mul_f32_e32 v105, v105, v108
	v_add_f32_e32 v108, 1.0, v110
	v_rcp_f32_e32 v108, v108
	v_cvt_pk_bf16_f32 v104, v104, v105
	v_fma_f32 v105, v109, -2.0, 1.0
	v_mul_f32_e32 v106, 0.5, v106
	v_add_f32_e32 v105, 1.0, v105
	v_mul_f32_e32 v105, v106, v105
	v_fma_f32 v106, v108, -2.0, 1.0
	v_mul_f32_e32 v107, 0.5, v107
	v_add_f32_e32 v106, 1.0, v106
	v_mul_f32_e32 v106, v107, v106
	v_cvt_pk_bf16_f32 v105, v105, v106
	global_store_dwordx2 v[120:121], v[104:105], off offset:32
	s_waitcnt vmcnt(9)
	v_lshlrev_b32_e32 v104, 16, v202
	v_fma_f32 v100, v44, v104, v100
	v_mul_f32_e32 v104, 0x3d372713, v100
	v_mul_f32_e32 v104, v100, v104
	v_fma_f32 v104, v100, v104, v100
	v_mul_f32_e32 v104, 0x3f4c422a, v104
	v_add_f32_e32 v104, v104, v104
	v_and_b32_e32 v105, 0xffff0000, v202
	v_mul_f32_e32 v104, 0x3fb8aa3b, v104
	v_fma_f32 v101, v45, v105, v101
	v_lshlrev_b32_e32 v105, 16, v203
	v_exp_f32_e32 v104, v104
	v_fma_f32 v102, v46, v105, v102
	v_and_b32_e32 v105, 0xffff0000, v203
	v_fmac_f32_e32 v103, v47, v105
	v_mul_f32_e32 v105, 0x3d372713, v101
	v_mul_f32_e32 v105, v101, v105
	v_fma_f32 v105, v101, v105, v101
	v_add_f32_e32 v104, 1.0, v104
	v_mul_f32_e32 v105, 0x3f4c422a, v105
	v_rcp_f32_e32 v104, v104
	v_add_f32_e32 v105, v105, v105
	v_mul_f32_e32 v105, 0x3fb8aa3b, v105
	v_exp_f32_e32 v105, v105
	v_fma_f32 v104, v104, -2.0, 1.0
	v_mul_f32_e32 v100, 0.5, v100
	v_add_f32_e32 v104, 1.0, v104
	v_mul_f32_e32 v100, v100, v104
	v_add_f32_e32 v104, 1.0, v105
	v_mul_f32_e32 v105, 0x3d372713, v102
	v_mul_f32_e32 v105, v102, v105
	v_fma_f32 v105, v102, v105, v102
	v_mul_f32_e32 v106, 0x3d372713, v103
	v_mul_f32_e32 v105, 0x3f4c422a, v105
	v_mul_f32_e32 v106, v103, v106
	v_add_f32_e32 v105, v105, v105
	v_fma_f32 v106, v103, v106, v103
	v_mul_f32_e32 v105, 0x3fb8aa3b, v105
	v_mul_f32_e32 v106, 0x3f4c422a, v106
	v_rcp_f32_e32 v104, v104
	v_exp_f32_e32 v105, v105
	v_add_f32_e32 v106, v106, v106
	v_mul_f32_e32 v106, 0x3fb8aa3b, v106
	v_exp_f32_e32 v106, v106
	v_fma_f32 v104, v104, -2.0, 1.0
	v_add_f32_e32 v105, 1.0, v105
	v_mul_f32_e32 v101, 0.5, v101
	v_add_f32_e32 v104, 1.0, v104
	v_rcp_f32_e32 v105, v105
	v_mul_f32_e32 v101, v101, v104
	v_add_f32_e32 v104, 1.0, v106
	v_rcp_f32_e32 v104, v104
	v_cvt_pk_bf16_f32 v100, v100, v101
	v_fma_f32 v101, v105, -2.0, 1.0
	v_mul_f32_e32 v102, 0.5, v102
	v_add_f32_e32 v101, 1.0, v101
	v_mul_f32_e32 v101, v102, v101
	v_fma_f32 v102, v104, -2.0, 1.0
	v_mul_f32_e32 v103, 0.5, v103
	v_add_f32_e32 v102, 1.0, v102
	v_mul_f32_e32 v102, v103, v102
	v_cvt_pk_bf16_f32 v101, v101, v102
	global_store_dwordx2 v[116:117], v[100:101], off offset:32
	v_lshlrev_b32_e32 v100, 16, v200
	v_fma_f32 v96, v44, v100, v96
	v_mul_f32_e32 v100, 0x3d372713, v96
	v_mul_f32_e32 v100, v96, v100
	v_fma_f32 v100, v96, v100, v96
	v_mul_f32_e32 v100, 0x3f4c422a, v100
	v_add_f32_e32 v100, v100, v100
	v_and_b32_e32 v101, 0xffff0000, v200
	v_mul_f32_e32 v100, 0x3fb8aa3b, v100
	v_fma_f32 v97, v45, v101, v97
	v_lshlrev_b32_e32 v101, 16, v201
	v_exp_f32_e32 v100, v100
	v_fma_f32 v98, v46, v101, v98
	v_and_b32_e32 v101, 0xffff0000, v201
	v_fmac_f32_e32 v99, v47, v101
	v_mul_f32_e32 v101, 0x3d372713, v97
	v_mul_f32_e32 v101, v97, v101
	v_fma_f32 v101, v97, v101, v97
	v_add_f32_e32 v100, 1.0, v100
	v_mul_f32_e32 v101, 0x3f4c422a, v101
	v_rcp_f32_e32 v100, v100
	v_add_f32_e32 v101, v101, v101
	v_mul_f32_e32 v101, 0x3fb8aa3b, v101
	v_exp_f32_e32 v101, v101
	v_fma_f32 v100, v100, -2.0, 1.0
	v_mul_f32_e32 v96, 0.5, v96
	v_add_f32_e32 v100, 1.0, v100
	v_mul_f32_e32 v96, v96, v100
	v_add_f32_e32 v100, 1.0, v101
	v_mul_f32_e32 v101, 0x3d372713, v98
	v_mul_f32_e32 v101, v98, v101
	v_fma_f32 v101, v98, v101, v98
	v_mul_f32_e32 v102, 0x3d372713, v99
	v_mul_f32_e32 v101, 0x3f4c422a, v101
	v_mul_f32_e32 v102, v99, v102
	v_add_f32_e32 v101, v101, v101
	v_fma_f32 v102, v99, v102, v99
	v_mul_f32_e32 v101, 0x3fb8aa3b, v101
	v_mul_f32_e32 v102, 0x3f4c422a, v102
	v_rcp_f32_e32 v100, v100
	v_exp_f32_e32 v101, v101
	v_add_f32_e32 v102, v102, v102
	v_mul_f32_e32 v102, 0x3fb8aa3b, v102
	v_exp_f32_e32 v102, v102
; __device__ __forceinline__ unsigned pk2(float lo, float hi) { return pg8::cvt_pk_bf16(lo, hi); }
; __device__ __forceinline__ float gelu_tanh(float x) { const float z = 0.7978845608028654f * (x + 0.044715f * x * x * x); const float t = 1.f - 2.f * __builtin_amdgcn_rcpf(__expf(2.f * z) + 1.f); return 0.5f * x * (1.f + t); }
; template <int PMODE> __device__ __forceinline__ void ssm_c_task(unsigned char* ws, LAS unsigned char* lds, int l, int task, int tid_in) {
;     ...
;     for (int a0 = 0; a0 < 8; a0 += 4) {
;         u32x2 uw[4][4];
; #pragma unroll
;         for (int a = 0; a < 4; ++a)
; #pragma unroll
;             for (int c = 0; c < 4; ++c) { const int col = cb * 64 + c * 16 + rr_e; const size_t tok = (size_t)col * 64 + wid * 8 + a0 + a; uw[a][c] = *(const u32x2*)(U + tok * 512 + g * 16 + 4 * kk); }
; #pragma unroll
;         for (int a = 0; a < 4; ++a)
; #pragma unroll
;             for (int c = 0; c < 4; ++c) { const int col = cb * 64 + c * 16 + rr_e; const size_t tok = (size_t)col * 64 + wid * 8 + a0 + a;
;                 const f32x4 av = acc[a0 + a][c];
;                 const float y0 = av[0] + dv[0] * bflo(uw[a][c].x), y1 = av[1] + dv[1] * bfhi(uw[a][c].x), y2 = av[2] + dv[2] * bflo(uw[a][c].y), y3 = av[3] + dv[3] * bfhi(uw[a][c].y);
;                 u32x2 o; o.x = pk2(gelu_tanh(y0), gelu_tanh(y1)); o.y = pk2(gelu_tanh(y2), gelu_tanh(y3));
;                 if (PMODE == 4) asm volatile("" :: "v"(o)); else *(u32x2*)(yb + (c * 1024 + a0 + a) * 16) = o; }
	v_fma_f32 v100, v100, -2.0, 1.0
	v_add_f32_e32 v101, 1.0, v101
	v_mul_f32_e32 v97, 0.5, v97
	v_add_f32_e32 v100, 1.0, v100
	v_rcp_f32_e32 v101, v101
	v_mul_f32_e32 v97, v97, v100
	v_add_f32_e32 v100, 1.0, v102
	v_rcp_f32_e32 v100, v100
	v_cvt_pk_bf16_f32 v96, v96, v97
	v_fma_f32 v97, v101, -2.0, 1.0
	v_mul_f32_e32 v98, 0.5, v98
	v_add_f32_e32 v97, 1.0, v97
	v_mul_f32_e32 v97, v98, v97
	v_fma_f32 v98, v100, -2.0, 1.0
	v_mul_f32_e32 v99, 0.5, v99
	v_add_f32_e32 v98, 1.0, v98
	v_mul_f32_e32 v98, v99, v98
	v_cvt_pk_bf16_f32 v97, v97, v98
	global_store_dwordx2 v[132:133], v[96:97], off offset:64
	v_lshlrev_b32_e32 v96, 16, v198
	v_fma_f32 v92, v44, v96, v92
	v_mul_f32_e32 v96, 0x3d372713, v92
	v_mul_f32_e32 v96, v92, v96
	v_fma_f32 v96, v92, v96, v92
	v_mul_f32_e32 v96, 0x3f4c422a, v96
	v_add_f32_e32 v96, v96, v96
	v_and_b32_e32 v97, 0xffff0000, v198
	v_mul_f32_e32 v96, 0x3fb8aa3b, v96
	v_fma_f32 v93, v45, v97, v93
	v_lshlrev_b32_e32 v97, 16, v199
	v_exp_f32_e32 v96, v96
	v_fma_f32 v94, v46, v97, v94
	v_and_b32_e32 v97, 0xffff0000, v199
	v_fmac_f32_e32 v95, v47, v97
	v_mul_f32_e32 v97, 0x3d372713, v93
	v_mul_f32_e32 v97, v93, v97
	v_fma_f32 v97, v93, v97, v93
	v_add_f32_e32 v96, 1.0, v96
	v_mul_f32_e32 v97, 0x3f4c422a, v97
	v_rcp_f32_e32 v96, v96
	v_add_f32_e32 v97, v97, v97
	v_mul_f32_e32 v97, 0x3fb8aa3b, v97
	v_exp_f32_e32 v97, v97
	v_fma_f32 v96, v96, -2.0, 1.0
	v_mul_f32_e32 v92, 0.5, v92
	v_add_f32_e32 v96, 1.0, v96
	v_mul_f32_e32 v92, v92, v96
	v_add_f32_e32 v96, 1.0, v97
	v_mul_f32_e32 v97, 0x3d372713, v94
	v_mul_f32_e32 v97, v94, v97
	v_fma_f32 v97, v94, v97, v94
	v_mul_f32_e32 v98, 0x3d372713, v95
	v_mul_f32_e32 v97, 0x3f4c422a, v97
	v_mul_f32_e32 v98, v95, v98
	v_add_f32_e32 v97, v97, v97
	v_fma_f32 v98, v95, v98, v95
	v_mul_f32_e32 v97, 0x3fb8aa3b, v97
	v_mul_f32_e32 v98, 0x3f4c422a, v98
	v_rcp_f32_e32 v96, v96
	v_exp_f32_e32 v97, v97
	v_add_f32_e32 v98, v98, v98
	v_mul_f32_e32 v98, 0x3fb8aa3b, v98
	v_exp_f32_e32 v98, v98
	v_fma_f32 v96, v96, -2.0, 1.0
	v_add_f32_e32 v97, 1.0, v97
	v_mul_f32_e32 v93, 0.5, v93
	v_add_f32_e32 v96, 1.0, v96
	v_rcp_f32_e32 v97, v97
	v_mul_f32_e32 v93, v93, v96
	v_add_f32_e32 v96, 1.0, v98
	v_rcp_f32_e32 v96, v96
	v_cvt_pk_bf16_f32 v92, v92, v93
	v_fma_f32 v93, v97, -2.0, 1.0
	v_mul_f32_e32 v94, 0.5, v94
	v_add_f32_e32 v93, 1.0, v93
	v_mul_f32_e32 v93, v94, v93
	v_fma_f32 v94, v96, -2.0, 1.0
	v_mul_f32_e32 v95, 0.5, v95
	v_add_f32_e32 v94, 1.0, v94
	v_mul_f32_e32 v94, v95, v94
	v_cvt_pk_bf16_f32 v93, v93, v94
	global_store_dwordx2 v[124:125], v[92:93], off offset:64
	v_lshlrev_b32_e32 v92, 16, v196
	v_fma_f32 v88, v44, v92, v88
	v_mul_f32_e32 v92, 0x3d372713, v88
	v_mul_f32_e32 v92, v88, v92
	v_fma_f32 v92, v88, v92, v88
	v_mul_f32_e32 v92, 0x3f4c422a, v92
	v_add_f32_e32 v92, v92, v92
	v_and_b32_e32 v93, 0xffff0000, v196
	v_mul_f32_e32 v92, 0x3fb8aa3b, v92
	v_fma_f32 v89, v45, v93, v89
	v_lshlrev_b32_e32 v93, 16, v197
	v_exp_f32_e32 v92, v92
	v_fma_f32 v90, v46, v93, v90
	v_and_b32_e32 v93, 0xffff0000, v197
	v_fmac_f32_e32 v91, v47, v93
	v_mul_f32_e32 v93, 0x3d372713, v89
	v_mul_f32_e32 v93, v89, v93
	v_fma_f32 v93, v89, v93, v89
	v_add_f32_e32 v92, 1.0, v92
	v_mul_f32_e32 v93, 0x3f4c422a, v93
	v_rcp_f32_e32 v92, v92
	v_add_f32_e32 v93, v93, v93
	v_mul_f32_e32 v93, 0x3fb8aa3b, v93
	v_exp_f32_e32 v93, v93
	v_fma_f32 v92, v92, -2.0, 1.0
	v_mul_f32_e32 v88, 0.5, v88
	v_add_f32_e32 v92, 1.0, v92
	v_mul_f32_e32 v88, v88, v92
	v_add_f32_e32 v92, 1.0, v93
	v_mul_f32_e32 v93, 0x3d372713, v90
	v_mul_f32_e32 v93, v90, v93
	v_fma_f32 v93, v90, v93, v90
	v_mul_f32_e32 v94, 0x3d372713, v91
	v_mul_f32_e32 v93, 0x3f4c422a, v93
	v_mul_f32_e32 v94, v91, v94
	v_add_f32_e32 v93, v93, v93
	v_fma_f32 v94, v91, v94, v91
	v_mul_f32_e32 v93, 0x3fb8aa3b, v93
	v_mul_f32_e32 v94, 0x3f4c422a, v94
	v_rcp_f32_e32 v92, v92
	v_exp_f32_e32 v93, v93
	v_add_f32_e32 v94, v94, v94
	v_mul_f32_e32 v94, 0x3fb8aa3b, v94
	v_exp_f32_e32 v94, v94
	v_fma_f32 v92, v92, -2.0, 1.0
	v_add_f32_e32 v93, 1.0, v93
	v_mul_f32_e32 v89, 0.5, v89
	v_add_f32_e32 v92, 1.0, v92
	v_rcp_f32_e32 v93, v93
	v_mul_f32_e32 v89, v89, v92
	v_add_f32_e32 v92, 1.0, v94
	v_rcp_f32_e32 v92, v92
	v_cvt_pk_bf16_f32 v88, v88, v89
	v_fma_f32 v89, v93, -2.0, 1.0
	v_mul_f32_e32 v90, 0.5, v90
	v_add_f32_e32 v89, 1.0, v89
	v_mul_f32_e32 v89, v90, v89
	v_fma_f32 v90, v92, -2.0, 1.0
	v_mul_f32_e32 v91, 0.5, v91
	v_add_f32_e32 v90, 1.0, v90
	v_mul_f32_e32 v90, v91, v90
	v_cvt_pk_bf16_f32 v89, v89, v90
	global_store_dwordx2 v[120:121], v[88:89], off offset:64
	s_waitcnt vmcnt(12)
; __device__ __forceinline__ unsigned pk2(float lo, float hi) { return pg8::cvt_pk_bf16(lo, hi); }
; __device__ __forceinline__ float gelu_tanh(float x) { const float z = 0.7978845608028654f * (x + 0.044715f * x * x * x); const float t = 1.f - 2.f * __builtin_amdgcn_rcpf(__expf(2.f * z) + 1.f); return 0.5f * x * (1.f + t); }
; template <int PMODE> __device__ __forceinline__ void ssm_c_task(unsigned char* ws, LAS unsigned char* lds, int l, int task, int tid_in) {
;     ...
;     for (int a0 = 0; a0 < 8; a0 += 4) {
;         u32x2 uw[4][4];
; #pragma unroll
;         for (int a = 0; a < 4; ++a)
; #pragma unroll
;             for (int c = 0; c < 4; ++c) { const int col = cb * 64 + c * 16 + rr_e; const size_t tok = (size_t)col * 64 + wid * 8 + a0 + a; uw[a][c] = *(const u32x2*)(U + tok * 512 + g * 16 + 4 * kk); }
; #pragma unroll
;         for (int a = 0; a < 4; ++a)
; #pragma unroll
;             for (int c = 0; c < 4; ++c) { const int col = cb * 64 + c * 16 + rr_e; const size_t tok = (size_t)col * 64 + wid * 8 + a0 + a;
;                 const f32x4 av = acc[a0 + a][c];
;                 const float y0 = av[0] + dv[0] * bflo(uw[a][c].x), y1 = av[1] + dv[1] * bfhi(uw[a][c].x), y2 = av[2] + dv[2] * bflo(uw[a][c].y), y3 = av[3] + dv[3] * bfhi(uw[a][c].y);
;                 u32x2 o; o.x = pk2(gelu_tanh(y0), gelu_tanh(y1)); o.y = pk2(gelu_tanh(y2), gelu_tanh(y3));
;                 if (PMODE == 4) asm volatile("" :: "v"(o)); else *(u32x2*)(yb + (c * 1024 + a0 + a) * 16) = o; }
	v_lshlrev_b32_e32 v88, 16, v194
	v_fma_f32 v84, v44, v88, v84
	v_mul_f32_e32 v88, 0x3d372713, v84
	v_mul_f32_e32 v88, v84, v88
	v_fma_f32 v88, v84, v88, v84
	v_mul_f32_e32 v88, 0x3f4c422a, v88
	v_add_f32_e32 v88, v88, v88
	v_and_b32_e32 v89, 0xffff0000, v194
	v_mul_f32_e32 v88, 0x3fb8aa3b, v88
	v_fma_f32 v85, v45, v89, v85
	v_lshlrev_b32_e32 v89, 16, v195
	v_exp_f32_e32 v88, v88
	v_fma_f32 v86, v46, v89, v86
	v_and_b32_e32 v89, 0xffff0000, v195
	v_fmac_f32_e32 v87, v47, v89
	v_mul_f32_e32 v89, 0x3d372713, v85
	v_mul_f32_e32 v89, v85, v89
	v_fma_f32 v89, v85, v89, v85
	v_add_f32_e32 v88, 1.0, v88
	v_mul_f32_e32 v89, 0x3f4c422a, v89
	v_rcp_f32_e32 v88, v88
	v_add_f32_e32 v89, v89, v89
	v_mul_f32_e32 v89, 0x3fb8aa3b, v89
	v_exp_f32_e32 v89, v89
	v_fma_f32 v88, v88, -2.0, 1.0
	v_mul_f32_e32 v84, 0.5, v84
	v_add_f32_e32 v88, 1.0, v88
	v_mul_f32_e32 v84, v84, v88
	v_add_f32_e32 v88, 1.0, v89
	v_mul_f32_e32 v89, 0x3d372713, v86
	v_mul_f32_e32 v89, v86, v89
	v_fma_f32 v89, v86, v89, v86
	v_mul_f32_e32 v90, 0x3d372713, v87
	v_mul_f32_e32 v89, 0x3f4c422a, v89
	v_mul_f32_e32 v90, v87, v90
	v_add_f32_e32 v89, v89, v89
	v_fma_f32 v90, v87, v90, v87
	v_mul_f32_e32 v89, 0x3fb8aa3b, v89
	v_mul_f32_e32 v90, 0x3f4c422a, v90
	v_rcp_f32_e32 v88, v88
	v_exp_f32_e32 v89, v89
	v_add_f32_e32 v90, v90, v90
	v_mul_f32_e32 v90, 0x3fb8aa3b, v90
	v_exp_f32_e32 v90, v90
	v_fma_f32 v88, v88, -2.0, 1.0
	v_add_f32_e32 v89, 1.0, v89
	v_mul_f32_e32 v85, 0.5, v85
	v_add_f32_e32 v88, 1.0, v88
	v_rcp_f32_e32 v89, v89
	v_mul_f32_e32 v85, v85, v88
	v_add_f32_e32 v88, 1.0, v90
	v_rcp_f32_e32 v88, v88
	v_cvt_pk_bf16_f32 v84, v84, v85
	v_fma_f32 v85, v89, -2.0, 1.0
	v_mul_f32_e32 v86, 0.5, v86
	v_add_f32_e32 v85, 1.0, v85
	v_mul_f32_e32 v85, v86, v85
	v_fma_f32 v86, v88, -2.0, 1.0
	v_mul_f32_e32 v87, 0.5, v87
	v_add_f32_e32 v86, 1.0, v86
	v_mul_f32_e32 v86, v87, v86
	v_cvt_pk_bf16_f32 v85, v85, v86
	global_store_dwordx2 v[116:117], v[84:85], off offset:64
	v_lshlrev_b32_e32 v84, 16, v182
	v_fma_f32 v80, v44, v84, v80
	v_mul_f32_e32 v84, 0x3d372713, v80
	v_mul_f32_e32 v84, v80, v84
	v_fma_f32 v84, v80, v84, v80
	v_mul_f32_e32 v84, 0x3f4c422a, v84
	v_add_f32_e32 v84, v84, v84
	v_and_b32_e32 v85, 0xffff0000, v182
	v_mul_f32_e32 v84, 0x3fb8aa3b, v84
	v_fma_f32 v81, v45, v85, v81
	v_lshlrev_b32_e32 v85, 16, v183
	v_exp_f32_e32 v84, v84
	v_fma_f32 v82, v46, v85, v82
	v_and_b32_e32 v85, 0xffff0000, v183
	v_fmac_f32_e32 v83, v47, v85
	v_mul_f32_e32 v85, 0x3d372713, v81
	v_mul_f32_e32 v85, v81, v85
	v_fma_f32 v85, v81, v85, v81
	v_add_f32_e32 v84, 1.0, v84
	v_mul_f32_e32 v85, 0x3f4c422a, v85
	v_rcp_f32_e32 v84, v84
	v_add_f32_e32 v85, v85, v85
	v_mul_f32_e32 v85, 0x3fb8aa3b, v85
	v_exp_f32_e32 v85, v85
	v_fma_f32 v84, v84, -2.0, 1.0
	v_mul_f32_e32 v80, 0.5, v80
	v_add_f32_e32 v84, 1.0, v84
	v_mul_f32_e32 v80, v80, v84
	v_add_f32_e32 v84, 1.0, v85
	v_mul_f32_e32 v85, 0x3d372713, v82
	v_mul_f32_e32 v85, v82, v85
	v_fma_f32 v85, v82, v85, v82
	v_mul_f32_e32 v86, 0x3d372713, v83
	v_mul_f32_e32 v85, 0x3f4c422a, v85
	v_mul_f32_e32 v86, v83, v86
	v_add_f32_e32 v85, v85, v85
	v_fma_f32 v86, v83, v86, v83
	v_mul_f32_e32 v85, 0x3fb8aa3b, v85
	v_mul_f32_e32 v86, 0x3f4c422a, v86
	v_rcp_f32_e32 v84, v84
	v_exp_f32_e32 v85, v85
	v_add_f32_e32 v86, v86, v86
	v_mul_f32_e32 v86, 0x3fb8aa3b, v86
	v_exp_f32_e32 v86, v86
	v_fma_f32 v84, v84, -2.0, 1.0
	v_add_f32_e32 v85, 1.0, v85
	v_mul_f32_e32 v81, 0.5, v81
	v_add_f32_e32 v84, 1.0, v84
	v_rcp_f32_e32 v85, v85
	v_mul_f32_e32 v81, v81, v84
	v_add_f32_e32 v84, 1.0, v86
	v_rcp_f32_e32 v84, v84
	v_cvt_pk_bf16_f32 v80, v80, v81
	v_fma_f32 v81, v85, -2.0, 1.0
	v_mul_f32_e32 v82, 0.5, v82
	v_add_f32_e32 v81, 1.0, v81
	v_mul_f32_e32 v81, v82, v81
	v_fma_f32 v82, v84, -2.0, 1.0
	v_mul_f32_e32 v83, 0.5, v83
	v_add_f32_e32 v82, 1.0, v82
	v_mul_f32_e32 v82, v83, v82
	v_cvt_pk_bf16_f32 v81, v81, v82
	global_store_dwordx2 v[132:133], v[80:81], off offset:96
	v_lshlrev_b32_e32 v80, 16, v180
	v_fma_f32 v76, v44, v80, v76
	v_mul_f32_e32 v80, 0x3d372713, v76
	v_mul_f32_e32 v80, v76, v80
	v_fma_f32 v80, v76, v80, v76
	v_mul_f32_e32 v80, 0x3f4c422a, v80
	v_add_f32_e32 v80, v80, v80
	v_and_b32_e32 v81, 0xffff0000, v180
	v_mul_f32_e32 v80, 0x3fb8aa3b, v80
	v_fma_f32 v77, v45, v81, v77
	v_lshlrev_b32_e32 v81, 16, v181
	v_exp_f32_e32 v80, v80
	v_fma_f32 v78, v46, v81, v78
	v_and_b32_e32 v81, 0xffff0000, v181
	v_fmac_f32_e32 v79, v47, v81
	v_mul_f32_e32 v81, 0x3d372713, v77
	v_mul_f32_e32 v81, v77, v81
	v_fma_f32 v81, v77, v81, v77
	v_add_f32_e32 v80, 1.0, v80
	v_mul_f32_e32 v81, 0x3f4c422a, v81
	v_rcp_f32_e32 v80, v80
	v_add_f32_e32 v81, v81, v81
	v_mul_f32_e32 v81, 0x3fb8aa3b, v81
	v_exp_f32_e32 v81, v81
	v_fma_f32 v80, v80, -2.0, 1.0
	v_mul_f32_e32 v76, 0.5, v76
	v_add_f32_e32 v80, 1.0, v80
	v_mul_f32_e32 v76, v76, v80
	v_add_f32_e32 v80, 1.0, v81
	v_mul_f32_e32 v81, 0x3d372713, v78
	v_mul_f32_e32 v81, v78, v81
	v_fma_f32 v81, v78, v81, v78
	v_mul_f32_e32 v82, 0x3d372713, v79
	v_mul_f32_e32 v81, 0x3f4c422a, v81
	v_mul_f32_e32 v82, v79, v82
	v_add_f32_e32 v81, v81, v81
	v_fma_f32 v82, v79, v82, v79
	v_mul_f32_e32 v81, 0x3fb8aa3b, v81
	v_mul_f32_e32 v82, 0x3f4c422a, v82
	v_rcp_f32_e32 v80, v80
	v_exp_f32_e32 v81, v81
	v_add_f32_e32 v82, v82, v82
	v_mul_f32_e32 v82, 0x3fb8aa3b, v82
	v_exp_f32_e32 v82, v82
	v_fma_f32 v80, v80, -2.0, 1.0
	v_add_f32_e32 v81, 1.0, v81
	v_mul_f32_e32 v77, 0.5, v77
	v_add_f32_e32 v80, 1.0, v80
	v_rcp_f32_e32 v81, v81
	v_mul_f32_e32 v77, v77, v80
	v_add_f32_e32 v80, 1.0, v82
	v_rcp_f32_e32 v80, v80
	v_cvt_pk_bf16_f32 v76, v76, v77
	v_fma_f32 v77, v81, -2.0, 1.0
	v_mul_f32_e32 v78, 0.5, v78
	v_add_f32_e32 v77, 1.0, v77
	v_mul_f32_e32 v77, v78, v77
; __device__ __forceinline__ unsigned pk2(float lo, float hi) { return pg8::cvt_pk_bf16(lo, hi); }
; __device__ __forceinline__ float gelu_tanh(float x) { const float z = 0.7978845608028654f * (x + 0.044715f * x * x * x); const float t = 1.f - 2.f * __builtin_amdgcn_rcpf(__expf(2.f * z) + 1.f); return 0.5f * x * (1.f + t); }
; template <int PMODE> __device__ __forceinline__ void ssm_c_task(unsigned char* ws, LAS unsigned char* lds, int l, int task, int tid_in) {
;     ...
;     for (int a0 = 0; a0 < 8; a0 += 4) {
;         u32x2 uw[4][4];
; #pragma unroll
;         for (int a = 0; a < 4; ++a)
; #pragma unroll
;             for (int c = 0; c < 4; ++c) { const int col = cb * 64 + c * 16 + rr_e; const size_t tok = (size_t)col * 64 + wid * 8 + a0 + a; uw[a][c] = *(const u32x2*)(U + tok * 512 + g * 16 + 4 * kk); }
; #pragma unroll
;         for (int a = 0; a < 4; ++a)
; #pragma unroll
;             for (int c = 0; c < 4; ++c) { const int col = cb * 64 + c * 16 + rr_e; const size_t tok = (size_t)col * 64 + wid * 8 + a0 + a;
;                 const f32x4 av = acc[a0 + a][c];
;                 const float y0 = av[0] + dv[0] * bflo(uw[a][c].x), y1 = av[1] + dv[1] * bfhi(uw[a][c].x), y2 = av[2] + dv[2] * bflo(uw[a][c].y), y3 = av[3] + dv[3] * bfhi(uw[a][c].y);
;                 u32x2 o; o.x = pk2(gelu_tanh(y0), gelu_tanh(y1)); o.y = pk2(gelu_tanh(y2), gelu_tanh(y3));
;                 if (PMODE == 4) asm volatile("" :: "v"(o)); else *(u32x2*)(yb + (c * 1024 + a0 + a) * 16) = o; }
	v_fma_f32 v78, v80, -2.0, 1.0
	v_mul_f32_e32 v79, 0.5, v79
	v_add_f32_e32 v78, 1.0, v78
	v_mul_f32_e32 v78, v79, v78
	v_cvt_pk_bf16_f32 v77, v77, v78
	global_store_dwordx2 v[124:125], v[76:77], off offset:96
	v_lshlrev_b32_e32 v76, 16, v178
	v_fma_f32 v72, v44, v76, v72
	v_mul_f32_e32 v76, 0x3d372713, v72
	v_mul_f32_e32 v76, v72, v76
	v_fma_f32 v76, v72, v76, v72
	v_mul_f32_e32 v76, 0x3f4c422a, v76
	v_add_f32_e32 v76, v76, v76
	v_and_b32_e32 v77, 0xffff0000, v178
	v_mul_f32_e32 v76, 0x3fb8aa3b, v76
	v_fma_f32 v73, v45, v77, v73
	v_lshlrev_b32_e32 v77, 16, v179
	v_exp_f32_e32 v76, v76
	v_fma_f32 v74, v46, v77, v74
	v_and_b32_e32 v77, 0xffff0000, v179
	v_fmac_f32_e32 v75, v47, v77
	v_mul_f32_e32 v77, 0x3d372713, v73
	v_mul_f32_e32 v77, v73, v77
	v_fma_f32 v77, v73, v77, v73
	v_add_f32_e32 v76, 1.0, v76
	v_mul_f32_e32 v77, 0x3f4c422a, v77
	v_rcp_f32_e32 v76, v76
	v_add_f32_e32 v77, v77, v77
	v_mul_f32_e32 v77, 0x3fb8aa3b, v77
	v_exp_f32_e32 v77, v77
	v_fma_f32 v76, v76, -2.0, 1.0
	v_mul_f32_e32 v72, 0.5, v72
	v_add_f32_e32 v76, 1.0, v76
	v_mul_f32_e32 v72, v72, v76
	v_add_f32_e32 v76, 1.0, v77
	v_mul_f32_e32 v77, 0x3d372713, v74
	v_mul_f32_e32 v77, v74, v77
	v_fma_f32 v77, v74, v77, v74
	v_mul_f32_e32 v78, 0x3d372713, v75
	v_mul_f32_e32 v77, 0x3f4c422a, v77
	v_mul_f32_e32 v78, v75, v78
	v_add_f32_e32 v77, v77, v77
	v_fma_f32 v78, v75, v78, v75
	v_mul_f32_e32 v77, 0x3fb8aa3b, v77
	v_mul_f32_e32 v78, 0x3f4c422a, v78
	v_rcp_f32_e32 v76, v76
	v_exp_f32_e32 v77, v77
	v_add_f32_e32 v78, v78, v78
	v_mul_f32_e32 v78, 0x3fb8aa3b, v78
	v_exp_f32_e32 v78, v78
	v_fma_f32 v76, v76, -2.0, 1.0
	v_add_f32_e32 v77, 1.0, v77
	v_mul_f32_e32 v73, 0.5, v73
	v_add_f32_e32 v76, 1.0, v76
	v_rcp_f32_e32 v77, v77
	v_mul_f32_e32 v73, v73, v76
	v_add_f32_e32 v76, 1.0, v78
	v_rcp_f32_e32 v76, v76
	v_cvt_pk_bf16_f32 v72, v72, v73
	v_fma_f32 v73, v77, -2.0, 1.0
	v_mul_f32_e32 v74, 0.5, v74
	v_add_f32_e32 v73, 1.0, v73
	v_mul_f32_e32 v73, v74, v73
	v_fma_f32 v74, v76, -2.0, 1.0
	v_mul_f32_e32 v75, 0.5, v75
	v_add_f32_e32 v74, 1.0, v74
	v_mul_f32_e32 v74, v75, v74
	v_cvt_pk_bf16_f32 v73, v73, v74
	global_store_dwordx2 v[120:121], v[72:73], off offset:96
	s_waitcnt vmcnt(15)
	v_lshlrev_b32_e32 v72, 16, v176
	v_fma_f32 v68, v44, v72, v68
	v_mul_f32_e32 v72, 0x3d372713, v68
	v_mul_f32_e32 v72, v68, v72
	v_fma_f32 v72, v68, v72, v68
	v_mul_f32_e32 v72, 0x3f4c422a, v72
	v_add_f32_e32 v72, v72, v72
	v_and_b32_e32 v73, 0xffff0000, v176
	v_mul_f32_e32 v72, 0x3fb8aa3b, v72
	v_fma_f32 v69, v45, v73, v69
	v_lshlrev_b32_e32 v73, 16, v177
	v_exp_f32_e32 v72, v72
	v_fma_f32 v70, v46, v73, v70
	v_and_b32_e32 v73, 0xffff0000, v177
	v_fmac_f32_e32 v71, v47, v73
	v_mul_f32_e32 v73, 0x3d372713, v69
	v_mul_f32_e32 v73, v69, v73
	v_fma_f32 v73, v69, v73, v69
	v_add_f32_e32 v72, 1.0, v72
	v_mul_f32_e32 v73, 0x3f4c422a, v73
	v_rcp_f32_e32 v72, v72
	v_add_f32_e32 v73, v73, v73
	v_mul_f32_e32 v73, 0x3fb8aa3b, v73
	v_exp_f32_e32 v73, v73
	v_fma_f32 v72, v72, -2.0, 1.0
	v_mul_f32_e32 v68, 0.5, v68
	v_add_f32_e32 v72, 1.0, v72
	v_mul_f32_e32 v68, v68, v72
	v_add_f32_e32 v72, 1.0, v73
	v_mul_f32_e32 v73, 0x3d372713, v70
	v_mul_f32_e32 v73, v70, v73
	v_fma_f32 v73, v70, v73, v70
	v_mul_f32_e32 v74, 0x3d372713, v71
	v_mul_f32_e32 v73, 0x3f4c422a, v73
	v_mul_f32_e32 v74, v71, v74
	v_add_f32_e32 v73, v73, v73
	v_fma_f32 v74, v71, v74, v71
	v_mul_f32_e32 v73, 0x3fb8aa3b, v73
	v_mul_f32_e32 v74, 0x3f4c422a, v74
	v_rcp_f32_e32 v72, v72
	v_exp_f32_e32 v73, v73
	v_add_f32_e32 v74, v74, v74
	v_mul_f32_e32 v74, 0x3fb8aa3b, v74
	v_exp_f32_e32 v74, v74
	v_fma_f32 v72, v72, -2.0, 1.0
	v_add_f32_e32 v73, 1.0, v73
	v_mul_f32_e32 v69, 0.5, v69
	v_add_f32_e32 v72, 1.0, v72
	v_rcp_f32_e32 v73, v73
	v_mul_f32_e32 v69, v69, v72
	v_add_f32_e32 v72, 1.0, v74
	v_rcp_f32_e32 v72, v72
	v_cvt_pk_bf16_f32 v68, v68, v69
	v_fma_f32 v69, v73, -2.0, 1.0
	v_mul_f32_e32 v70, 0.5, v70
	v_add_f32_e32 v69, 1.0, v69
	v_mul_f32_e32 v69, v70, v69
	v_fma_f32 v70, v72, -2.0, 1.0
	v_mul_f32_e32 v71, 0.5, v71
	v_add_f32_e32 v70, 1.0, v70
	v_mul_f32_e32 v70, v71, v70
	v_cvt_pk_bf16_f32 v69, v69, v70
	global_store_dwordx2 v[116:117], v[68:69], off offset:96
	v_lshl_add_u64 v[68:69], v[134:135], 0, v[158:159]
	global_load_dwordx2 v[98:99], v[68:69], off
	v_lshl_add_u64 v[68:69], v[172:173], 0, v[158:159]
	v_lshl_add_u64 v[70:71], v[170:171], 0, v[158:159]
	v_lshl_add_u64 v[72:73], v[174:175], 0, v[158:159]
	global_load_dwordx2 v[96:97], v[68:69], off
	global_load_dwordx2 v[94:95], v[70:71], off
	global_load_dwordx2 v[92:93], v[72:73], off
	v_lshl_add_u64 v[68:69], v[134:135], 0, v[160:161]
	v_lshl_add_u64 v[70:71], v[172:173], 0, v[160:161]
	v_lshl_add_u64 v[72:73], v[170:171], 0, v[160:161]
	v_lshl_add_u64 v[74:75], v[174:175], 0, v[160:161]
	global_load_dwordx2 v[90:91], v[68:69], off
	global_load_dwordx2 v[88:89], v[70:71], off
	global_load_dwordx2 v[86:87], v[72:73], off
	global_load_dwordx2 v[84:85], v[74:75], off
	v_lshl_add_u64 v[68:69], v[134:135], 0, v[162:163]
	v_lshl_add_u64 v[70:71], v[172:173], 0, v[162:163]
	v_lshl_add_u64 v[72:73], v[170:171], 0, v[162:163]
	v_lshl_add_u64 v[74:75], v[174:175], 0, v[162:163]
	global_load_dwordx2 v[82:83], v[68:69], off
	global_load_dwordx2 v[80:81], v[70:71], off
	global_load_dwordx2 v[78:79], v[72:73], off
	global_load_dwordx2 v[76:77], v[74:75], off
	v_lshl_add_u64 v[68:69], v[134:135], 0, v[164:165]
	v_lshl_add_u64 v[70:71], v[172:173], 0, v[164:165]
	v_lshl_add_u64 v[100:101], v[170:171], 0, v[164:165]
	v_lshl_add_u64 v[102:103], v[174:175], 0, v[164:165]
	global_load_dwordx2 v[74:75], v[68:69], off
	global_load_dwordx2 v[72:73], v[70:71], off
	s_nop 0
	global_load_dwordx2 v[70:71], v[100:101], off
	global_load_dwordx2 v[68:69], v[102:103], off
	s_waitcnt vmcnt(15)
; __device__ __forceinline__ unsigned pk2(float lo, float hi) { return pg8::cvt_pk_bf16(lo, hi); }
; __device__ __forceinline__ float gelu_tanh(float x) { const float z = 0.7978845608028654f * (x + 0.044715f * x * x * x); const float t = 1.f - 2.f * __builtin_amdgcn_rcpf(__expf(2.f * z) + 1.f); return 0.5f * x * (1.f + t); }
; template <int PMODE> __device__ __forceinline__ void ssm_c_task(unsigned char* ws, LAS unsigned char* lds, int l, int task, int tid_in) {
;     ...
;     for (int a0 = 0; a0 < 8; a0 += 4) {
;         u32x2 uw[4][4];
; #pragma unroll
;         for (int a = 0; a < 4; ++a)
; #pragma unroll
;             for (int c = 0; c < 4; ++c) { const int col = cb * 64 + c * 16 + rr_e; const size_t tok = (size_t)col * 64 + wid * 8 + a0 + a; uw[a][c] = *(const u32x2*)(U + tok * 512 + g * 16 + 4 * kk); }
; #pragma unroll
;         for (int a = 0; a < 4; ++a)
; #pragma unroll
;             for (int c = 0; c < 4; ++c) { const int col = cb * 64 + c * 16 + rr_e; const size_t tok = (size_t)col * 64 + wid * 8 + a0 + a;
;                 const f32x4 av = acc[a0 + a][c];
;                 const float y0 = av[0] + dv[0] * bflo(uw[a][c].x), y1 = av[1] + dv[1] * bfhi(uw[a][c].x), y2 = av[2] + dv[2] * bflo(uw[a][c].y), y3 = av[3] + dv[3] * bfhi(uw[a][c].y);
;                 u32x2 o; o.x = pk2(gelu_tanh(y0), gelu_tanh(y1)); o.y = pk2(gelu_tanh(y2), gelu_tanh(y3));
;                 if (PMODE == 4) asm volatile("" :: "v"(o)); else *(u32x2*)(yb + (c * 1024 + a0 + a) * 16) = o; }
	v_lshlrev_b32_e32 v100, 16, v98
	v_fma_f32 v64, v44, v100, v64
	v_mul_f32_e32 v100, 0x3d372713, v64
	v_mul_f32_e32 v100, v64, v100
	v_fma_f32 v100, v64, v100, v64
	v_mul_f32_e32 v100, 0x3f4c422a, v100
	v_add_f32_e32 v100, v100, v100
	v_mul_f32_e32 v100, 0x3fb8aa3b, v100
	v_and_b32_e32 v98, 0xffff0000, v98
	v_exp_f32_e32 v100, v100
	v_fma_f32 v65, v45, v98, v65
	v_lshlrev_b32_e32 v98, 16, v99
	v_fma_f32 v66, v46, v98, v66
	v_and_b32_e32 v98, 0xffff0000, v99
	v_mul_f32_e32 v99, 0x3d372713, v65
	v_mul_f32_e32 v99, v65, v99
	v_fma_f32 v99, v65, v99, v65
	v_add_f32_e32 v100, 1.0, v100
	v_mul_f32_e32 v99, 0x3f4c422a, v99
	v_rcp_f32_e32 v100, v100
	v_add_f32_e32 v99, v99, v99
	v_mul_f32_e32 v99, 0x3fb8aa3b, v99
	v_exp_f32_e32 v99, v99
	v_fmac_f32_e32 v67, v47, v98
	v_fma_f32 v98, v100, -2.0, 1.0
	v_mul_f32_e32 v64, 0.5, v64
	v_add_f32_e32 v98, 1.0, v98
	v_mul_f32_e32 v64, v64, v98
	v_add_f32_e32 v98, 1.0, v99
	v_mul_f32_e32 v99, 0x3d372713, v66
	v_mul_f32_e32 v99, v66, v99
	v_fma_f32 v99, v66, v99, v66
	v_mul_f32_e32 v100, 0x3d372713, v67
	v_mul_f32_e32 v99, 0x3f4c422a, v99
	v_mul_f32_e32 v100, v67, v100
	v_add_f32_e32 v99, v99, v99
	v_fma_f32 v100, v67, v100, v67
	v_mul_f32_e32 v99, 0x3fb8aa3b, v99
	v_mul_f32_e32 v100, 0x3f4c422a, v100
	v_rcp_f32_e32 v98, v98
	v_exp_f32_e32 v99, v99
	v_add_f32_e32 v100, v100, v100
	v_mul_f32_e32 v100, 0x3fb8aa3b, v100
	v_exp_f32_e32 v100, v100
	v_fma_f32 v98, v98, -2.0, 1.0
	v_add_f32_e32 v99, 1.0, v99
	v_mul_f32_e32 v65, 0.5, v65
	v_add_f32_e32 v98, 1.0, v98
	v_rcp_f32_e32 v99, v99
	v_mul_f32_e32 v65, v65, v98
	v_add_f32_e32 v98, 1.0, v100
	v_rcp_f32_e32 v98, v98
	v_cvt_pk_bf16_f32 v64, v64, v65
	v_fma_f32 v65, v99, -2.0, 1.0
	v_mul_f32_e32 v66, 0.5, v66
	v_add_f32_e32 v65, 1.0, v65
	v_mul_f32_e32 v65, v66, v65
	v_fma_f32 v66, v98, -2.0, 1.0
	v_mul_f32_e32 v67, 0.5, v67
	v_add_f32_e32 v66, 1.0, v66
	v_mul_f32_e32 v66, v67, v66
	v_cvt_pk_bf16_f32 v65, v65, v66
	global_store_dwordx2 v[132:133], v[64:65], off offset:128
	s_waitcnt vmcnt(15)
	v_lshlrev_b32_e32 v64, 16, v96
	v_fma_f32 v60, v44, v64, v60
	v_mul_f32_e32 v64, 0x3d372713, v60
	v_mul_f32_e32 v64, v60, v64
	v_fma_f32 v64, v60, v64, v60
	v_mul_f32_e32 v64, 0x3f4c422a, v64
	v_add_f32_e32 v64, v64, v64
	v_and_b32_e32 v65, 0xffff0000, v96
	v_mul_f32_e32 v64, 0x3fb8aa3b, v64
	v_fma_f32 v61, v45, v65, v61
	v_lshlrev_b32_e32 v65, 16, v97
	v_exp_f32_e32 v64, v64
	v_fma_f32 v62, v46, v65, v62
	v_and_b32_e32 v65, 0xffff0000, v97
	v_fmac_f32_e32 v63, v47, v65
	v_mul_f32_e32 v65, 0x3d372713, v61
	v_mul_f32_e32 v65, v61, v65
	v_fma_f32 v65, v61, v65, v61
	v_add_f32_e32 v64, 1.0, v64
	v_mul_f32_e32 v65, 0x3f4c422a, v65
	v_rcp_f32_e32 v64, v64
	v_add_f32_e32 v65, v65, v65
	v_mul_f32_e32 v65, 0x3fb8aa3b, v65
	v_exp_f32_e32 v65, v65
	v_fma_f32 v64, v64, -2.0, 1.0
	v_mul_f32_e32 v60, 0.5, v60
	v_add_f32_e32 v64, 1.0, v64
	v_mul_f32_e32 v60, v60, v64
	v_add_f32_e32 v64, 1.0, v65
	v_mul_f32_e32 v65, 0x3d372713, v62
	v_mul_f32_e32 v65, v62, v65
	v_fma_f32 v65, v62, v65, v62
	v_mul_f32_e32 v66, 0x3d372713, v63
	v_mul_f32_e32 v65, 0x3f4c422a, v65
	v_mul_f32_e32 v66, v63, v66
	v_add_f32_e32 v65, v65, v65
	v_fma_f32 v66, v63, v66, v63
	v_mul_f32_e32 v65, 0x3fb8aa3b, v65
	v_mul_f32_e32 v66, 0x3f4c422a, v66
	v_rcp_f32_e32 v64, v64
	v_exp_f32_e32 v65, v65
	v_add_f32_e32 v66, v66, v66
	v_mul_f32_e32 v66, 0x3fb8aa3b, v66
	v_exp_f32_e32 v66, v66
	v_fma_f32 v64, v64, -2.0, 1.0
	v_add_f32_e32 v65, 1.0, v65
	v_mul_f32_e32 v61, 0.5, v61
	v_add_f32_e32 v64, 1.0, v64
	v_rcp_f32_e32 v65, v65
	v_mul_f32_e32 v61, v61, v64
	v_add_f32_e32 v64, 1.0, v66
	v_rcp_f32_e32 v64, v64
	v_cvt_pk_bf16_f32 v60, v60, v61
	v_fma_f32 v61, v65, -2.0, 1.0
	v_mul_f32_e32 v62, 0.5, v62
	v_add_f32_e32 v61, 1.0, v61
	v_mul_f32_e32 v61, v62, v61
	v_fma_f32 v62, v64, -2.0, 1.0
	v_mul_f32_e32 v63, 0.5, v63
	v_add_f32_e32 v62, 1.0, v62
	v_mul_f32_e32 v62, v63, v62
	v_cvt_pk_bf16_f32 v61, v61, v62
	global_store_dwordx2 v[124:125], v[60:61], off offset:128
	s_waitcnt vmcnt(15)
	v_lshlrev_b32_e32 v60, 16, v94
	v_fma_f32 v56, v44, v60, v56
	v_mul_f32_e32 v60, 0x3d372713, v56
	v_mul_f32_e32 v60, v56, v60
	v_fma_f32 v60, v56, v60, v56
	v_mul_f32_e32 v60, 0x3f4c422a, v60
	v_add_f32_e32 v60, v60, v60
	v_and_b32_e32 v61, 0xffff0000, v94
	v_mul_f32_e32 v60, 0x3fb8aa3b, v60
	v_fma_f32 v57, v45, v61, v57
	v_lshlrev_b32_e32 v61, 16, v95
	v_exp_f32_e32 v60, v60
	v_fma_f32 v58, v46, v61, v58
	v_and_b32_e32 v61, 0xffff0000, v95
	v_fmac_f32_e32 v59, v47, v61
	v_mul_f32_e32 v61, 0x3d372713, v57
	v_mul_f32_e32 v61, v57, v61
	v_fma_f32 v61, v57, v61, v57
	v_add_f32_e32 v60, 1.0, v60
	v_mul_f32_e32 v61, 0x3f4c422a, v61
	v_rcp_f32_e32 v60, v60
	v_add_f32_e32 v61, v61, v61
	v_mul_f32_e32 v61, 0x3fb8aa3b, v61
	v_exp_f32_e32 v61, v61
	v_fma_f32 v60, v60, -2.0, 1.0
	v_mul_f32_e32 v56, 0.5, v56
	v_add_f32_e32 v60, 1.0, v60
	v_mul_f32_e32 v56, v56, v60
	v_add_f32_e32 v60, 1.0, v61
	v_mul_f32_e32 v61, 0x3d372713, v58
	v_mul_f32_e32 v61, v58, v61
	v_fma_f32 v61, v58, v61, v58
	v_mul_f32_e32 v62, 0x3d372713, v59
	v_mul_f32_e32 v61, 0x3f4c422a, v61
	v_mul_f32_e32 v62, v59, v62
	v_add_f32_e32 v61, v61, v61
	v_fma_f32 v62, v59, v62, v59
	v_mul_f32_e32 v61, 0x3fb8aa3b, v61
	v_mul_f32_e32 v62, 0x3f4c422a, v62
	v_rcp_f32_e32 v60, v60
	v_exp_f32_e32 v61, v61
	v_add_f32_e32 v62, v62, v62
	v_mul_f32_e32 v62, 0x3fb8aa3b, v62
	v_exp_f32_e32 v62, v62
	v_fma_f32 v60, v60, -2.0, 1.0
	v_add_f32_e32 v61, 1.0, v61
	v_mul_f32_e32 v57, 0.5, v57
	v_add_f32_e32 v60, 1.0, v60
	v_rcp_f32_e32 v61, v61
	v_mul_f32_e32 v57, v57, v60
	v_add_f32_e32 v60, 1.0, v62
	v_rcp_f32_e32 v60, v60
	v_cvt_pk_bf16_f32 v56, v56, v57
	v_fma_f32 v57, v61, -2.0, 1.0
	v_mul_f32_e32 v58, 0.5, v58
	v_add_f32_e32 v57, 1.0, v57
	v_mul_f32_e32 v57, v58, v57
	v_fma_f32 v58, v60, -2.0, 1.0
	v_mul_f32_e32 v59, 0.5, v59
	v_add_f32_e32 v58, 1.0, v58
	v_mul_f32_e32 v58, v59, v58
	v_cvt_pk_bf16_f32 v57, v57, v58
	global_store_dwordx2 v[120:121], v[56:57], off offset:128
	s_waitcnt vmcnt(15)
; __device__ __forceinline__ unsigned pk2(float lo, float hi) { return pg8::cvt_pk_bf16(lo, hi); }
; __device__ __forceinline__ float gelu_tanh(float x) { const float z = 0.7978845608028654f * (x + 0.044715f * x * x * x); const float t = 1.f - 2.f * __builtin_amdgcn_rcpf(__expf(2.f * z) + 1.f); return 0.5f * x * (1.f + t); }
; template <int PMODE> __device__ __forceinline__ void ssm_c_task(unsigned char* ws, LAS unsigned char* lds, int l, int task, int tid_in) {
;     ...
;     for (int a0 = 0; a0 < 8; a0 += 4) {
;         u32x2 uw[4][4];
; #pragma unroll
;         for (int a = 0; a < 4; ++a)
; #pragma unroll
;             for (int c = 0; c < 4; ++c) { const int col = cb * 64 + c * 16 + rr_e; const size_t tok = (size_t)col * 64 + wid * 8 + a0 + a; uw[a][c] = *(const u32x2*)(U + tok * 512 + g * 16 + 4 * kk); }
; #pragma unroll
;         for (int a = 0; a < 4; ++a)
; #pragma unroll
;             for (int c = 0; c < 4; ++c) { const int col = cb * 64 + c * 16 + rr_e; const size_t tok = (size_t)col * 64 + wid * 8 + a0 + a;
;                 const f32x4 av = acc[a0 + a][c];
;                 const float y0 = av[0] + dv[0] * bflo(uw[a][c].x), y1 = av[1] + dv[1] * bfhi(uw[a][c].x), y2 = av[2] + dv[2] * bflo(uw[a][c].y), y3 = av[3] + dv[3] * bfhi(uw[a][c].y);
;                 u32x2 o; o.x = pk2(gelu_tanh(y0), gelu_tanh(y1)); o.y = pk2(gelu_tanh(y2), gelu_tanh(y3));
;                 if (PMODE == 4) asm volatile("" :: "v"(o)); else *(u32x2*)(yb + (c * 1024 + a0 + a) * 16) = o; }
	v_lshlrev_b32_e32 v56, 16, v92
	v_fma_f32 v52, v44, v56, v52
	v_mul_f32_e32 v56, 0x3d372713, v52
	v_mul_f32_e32 v56, v52, v56
	v_fma_f32 v56, v52, v56, v52
	v_mul_f32_e32 v56, 0x3f4c422a, v56
	v_add_f32_e32 v56, v56, v56
	v_and_b32_e32 v57, 0xffff0000, v92
	v_mul_f32_e32 v56, 0x3fb8aa3b, v56
	v_fma_f32 v53, v45, v57, v53
	v_lshlrev_b32_e32 v57, 16, v93
	v_exp_f32_e32 v56, v56
	v_fma_f32 v54, v46, v57, v54
	v_and_b32_e32 v57, 0xffff0000, v93
	v_fmac_f32_e32 v55, v47, v57
	v_mul_f32_e32 v57, 0x3d372713, v53
	v_mul_f32_e32 v57, v53, v57
	v_fma_f32 v57, v53, v57, v53
	v_add_f32_e32 v56, 1.0, v56
	v_mul_f32_e32 v57, 0x3f4c422a, v57
	v_rcp_f32_e32 v56, v56
	v_add_f32_e32 v57, v57, v57
	v_mul_f32_e32 v57, 0x3fb8aa3b, v57
	v_exp_f32_e32 v57, v57
	v_fma_f32 v56, v56, -2.0, 1.0
	v_mul_f32_e32 v52, 0.5, v52
	v_add_f32_e32 v56, 1.0, v56
	v_mul_f32_e32 v52, v52, v56
	v_add_f32_e32 v56, 1.0, v57
	v_mul_f32_e32 v57, 0x3d372713, v54
	v_mul_f32_e32 v57, v54, v57
	v_fma_f32 v57, v54, v57, v54
	v_mul_f32_e32 v58, 0x3d372713, v55
	v_mul_f32_e32 v57, 0x3f4c422a, v57
	v_mul_f32_e32 v58, v55, v58
	v_add_f32_e32 v57, v57, v57
	v_fma_f32 v58, v55, v58, v55
	v_mul_f32_e32 v57, 0x3fb8aa3b, v57
	v_mul_f32_e32 v58, 0x3f4c422a, v58
	v_rcp_f32_e32 v56, v56
	v_exp_f32_e32 v57, v57
	v_add_f32_e32 v58, v58, v58
	v_mul_f32_e32 v58, 0x3fb8aa3b, v58
	v_exp_f32_e32 v58, v58
	v_fma_f32 v56, v56, -2.0, 1.0
	v_add_f32_e32 v57, 1.0, v57
	v_mul_f32_e32 v53, 0.5, v53
	v_add_f32_e32 v56, 1.0, v56
	v_rcp_f32_e32 v57, v57
	v_mul_f32_e32 v53, v53, v56
	v_add_f32_e32 v56, 1.0, v58
	v_rcp_f32_e32 v56, v56
	v_cvt_pk_bf16_f32 v52, v52, v53
	v_fma_f32 v53, v57, -2.0, 1.0
	v_mul_f32_e32 v54, 0.5, v54
	v_add_f32_e32 v53, 1.0, v53
	v_mul_f32_e32 v53, v54, v53
	v_fma_f32 v54, v56, -2.0, 1.0
	v_mul_f32_e32 v55, 0.5, v55
	v_add_f32_e32 v54, 1.0, v54
	v_mul_f32_e32 v54, v55, v54
	v_cvt_pk_bf16_f32 v53, v53, v54
	global_store_dwordx2 v[116:117], v[52:53], off offset:128
	s_waitcnt vmcnt(15)
	v_lshlrev_b32_e32 v52, 16, v90
	v_fma_f32 v48, v44, v52, v48
	v_mul_f32_e32 v52, 0x3d372713, v48
	v_mul_f32_e32 v52, v48, v52
	v_fma_f32 v52, v48, v52, v48
	v_mul_f32_e32 v52, 0x3f4c422a, v52
	v_add_f32_e32 v52, v52, v52
	v_and_b32_e32 v53, 0xffff0000, v90
	v_mul_f32_e32 v52, 0x3fb8aa3b, v52
	v_fma_f32 v49, v45, v53, v49
	v_lshlrev_b32_e32 v53, 16, v91
	v_exp_f32_e32 v52, v52
	v_fma_f32 v50, v46, v53, v50
	v_and_b32_e32 v53, 0xffff0000, v91
	v_fmac_f32_e32 v51, v47, v53
	v_mul_f32_e32 v53, 0x3d372713, v49
	v_mul_f32_e32 v53, v49, v53
	v_fma_f32 v53, v49, v53, v49
	v_add_f32_e32 v52, 1.0, v52
	v_mul_f32_e32 v53, 0x3f4c422a, v53
	v_rcp_f32_e32 v52, v52
	v_add_f32_e32 v53, v53, v53
	v_mul_f32_e32 v53, 0x3fb8aa3b, v53
	v_exp_f32_e32 v53, v53
	v_fma_f32 v52, v52, -2.0, 1.0
	v_mul_f32_e32 v48, 0.5, v48
	v_add_f32_e32 v52, 1.0, v52
	v_mul_f32_e32 v48, v48, v52
	v_add_f32_e32 v52, 1.0, v53
	v_mul_f32_e32 v53, 0x3d372713, v50
	v_mul_f32_e32 v53, v50, v53
	v_fma_f32 v53, v50, v53, v50
	v_mul_f32_e32 v54, 0x3d372713, v51
	v_mul_f32_e32 v53, 0x3f4c422a, v53
	v_mul_f32_e32 v54, v51, v54
	v_add_f32_e32 v53, v53, v53
	v_fma_f32 v54, v51, v54, v51
	v_mul_f32_e32 v53, 0x3fb8aa3b, v53
	v_mul_f32_e32 v54, 0x3f4c422a, v54
	v_rcp_f32_e32 v52, v52
	v_exp_f32_e32 v53, v53
	v_add_f32_e32 v54, v54, v54
	v_mul_f32_e32 v54, 0x3fb8aa3b, v54
	v_exp_f32_e32 v54, v54
	v_fma_f32 v52, v52, -2.0, 1.0
	v_add_f32_e32 v53, 1.0, v53
	v_mul_f32_e32 v49, 0.5, v49
	v_add_f32_e32 v52, 1.0, v52
	v_rcp_f32_e32 v53, v53
	v_mul_f32_e32 v49, v49, v52
	v_add_f32_e32 v52, 1.0, v54
	v_rcp_f32_e32 v52, v52
	v_cvt_pk_bf16_f32 v48, v48, v49
	v_fma_f32 v49, v53, -2.0, 1.0
	v_mul_f32_e32 v50, 0.5, v50
	v_add_f32_e32 v49, 1.0, v49
	v_mul_f32_e32 v49, v50, v49
	v_fma_f32 v50, v52, -2.0, 1.0
	v_mul_f32_e32 v51, 0.5, v51
	v_add_f32_e32 v50, 1.0, v50
	v_mul_f32_e32 v50, v51, v50
	v_cvt_pk_bf16_f32 v49, v49, v50
	global_store_dwordx2 v[132:133], v[48:49], off offset:160
	s_waitcnt vmcnt(15)
	v_lshlrev_b32_e32 v48, 16, v88
	v_fma_f32 v40, v44, v48, v40
	v_mul_f32_e32 v48, 0x3d372713, v40
	v_mul_f32_e32 v48, v40, v48
	v_fma_f32 v48, v40, v48, v40
	v_mul_f32_e32 v48, 0x3f4c422a, v48
	v_add_f32_e32 v48, v48, v48
	v_and_b32_e32 v49, 0xffff0000, v88
	v_mul_f32_e32 v48, 0x3fb8aa3b, v48
	v_fma_f32 v41, v45, v49, v41
	v_lshlrev_b32_e32 v49, 16, v89
	v_exp_f32_e32 v48, v48
	v_fma_f32 v42, v46, v49, v42
	v_and_b32_e32 v49, 0xffff0000, v89
	v_fmac_f32_e32 v43, v47, v49
	v_mul_f32_e32 v49, 0x3d372713, v41
	v_mul_f32_e32 v49, v41, v49
	v_fma_f32 v49, v41, v49, v41
	v_add_f32_e32 v48, 1.0, v48
	v_mul_f32_e32 v49, 0x3f4c422a, v49
	v_rcp_f32_e32 v48, v48
	v_add_f32_e32 v49, v49, v49
	v_mul_f32_e32 v49, 0x3fb8aa3b, v49
	v_exp_f32_e32 v49, v49
	v_fma_f32 v48, v48, -2.0, 1.0
	v_mul_f32_e32 v40, 0.5, v40
	v_add_f32_e32 v48, 1.0, v48
	v_mul_f32_e32 v40, v40, v48
	v_add_f32_e32 v48, 1.0, v49
	v_mul_f32_e32 v49, 0x3d372713, v42
	v_mul_f32_e32 v49, v42, v49
	v_fma_f32 v49, v42, v49, v42
	v_mul_f32_e32 v50, 0x3d372713, v43
	v_mul_f32_e32 v49, 0x3f4c422a, v49
	v_mul_f32_e32 v50, v43, v50
	v_add_f32_e32 v49, v49, v49
	v_fma_f32 v50, v43, v50, v43
	v_mul_f32_e32 v49, 0x3fb8aa3b, v49
	v_mul_f32_e32 v50, 0x3f4c422a, v50
	v_rcp_f32_e32 v48, v48
	v_exp_f32_e32 v49, v49
	v_add_f32_e32 v50, v50, v50
	v_mul_f32_e32 v50, 0x3fb8aa3b, v50
	v_exp_f32_e32 v50, v50
	v_fma_f32 v48, v48, -2.0, 1.0
	v_add_f32_e32 v49, 1.0, v49
	v_mul_f32_e32 v41, 0.5, v41
	v_add_f32_e32 v48, 1.0, v48
	v_rcp_f32_e32 v49, v49
	v_mul_f32_e32 v41, v41, v48
	v_add_f32_e32 v48, 1.0, v50
	v_rcp_f32_e32 v48, v48
	v_cvt_pk_bf16_f32 v40, v40, v41
	v_fma_f32 v41, v49, -2.0, 1.0
	v_mul_f32_e32 v42, 0.5, v42
	v_add_f32_e32 v41, 1.0, v41
	v_mul_f32_e32 v41, v42, v41
	v_fma_f32 v42, v48, -2.0, 1.0
	v_mul_f32_e32 v43, 0.5, v43
	v_add_f32_e32 v42, 1.0, v42
	v_mul_f32_e32 v42, v43, v42
	v_cvt_pk_bf16_f32 v41, v41, v42
	global_store_dwordx2 v[124:125], v[40:41], off offset:160
	s_waitcnt vmcnt(15)
; __device__ __forceinline__ unsigned pk2(float lo, float hi) { return pg8::cvt_pk_bf16(lo, hi); }
; __device__ __forceinline__ float gelu_tanh(float x) { const float z = 0.7978845608028654f * (x + 0.044715f * x * x * x); const float t = 1.f - 2.f * __builtin_amdgcn_rcpf(__expf(2.f * z) + 1.f); return 0.5f * x * (1.f + t); }
; template <int PMODE> __device__ __forceinline__ void ssm_c_task(unsigned char* ws, LAS unsigned char* lds, int l, int task, int tid_in) {
;     ...
;             for (int c = 0; c < 4; ++c) { const int col = cb * 64 + c * 16 + rr_e; const size_t tok = (size_t)col * 64 + wid * 8 + a0 + a;
;                 const f32x4 av = acc[a0 + a][c];
;                 const float y0 = av[0] + dv[0] * bflo(uw[a][c].x), y1 = av[1] + dv[1] * bfhi(uw[a][c].x), y2 = av[2] + dv[2] * bflo(uw[a][c].y), y3 = av[3] + dv[3] * bfhi(uw[a][c].y);
;                 u32x2 o; o.x = pk2(gelu_tanh(y0), gelu_tanh(y1)); o.y = pk2(gelu_tanh(y2), gelu_tanh(y3));
;                 if (PMODE == 4) asm volatile("" :: "v"(o)); else *(u32x2*)(yb + (c * 1024 + a0 + a) * 16) = o; }
	v_lshlrev_b32_e32 v40, 16, v86
	v_fma_f32 v36, v44, v40, v36
	v_mul_f32_e32 v40, 0x3d372713, v36
	v_mul_f32_e32 v40, v36, v40
	v_fma_f32 v40, v36, v40, v36
	v_mul_f32_e32 v40, 0x3f4c422a, v40
	v_add_f32_e32 v40, v40, v40
	v_and_b32_e32 v41, 0xffff0000, v86
	v_mul_f32_e32 v40, 0x3fb8aa3b, v40
	v_fma_f32 v37, v45, v41, v37
	v_lshlrev_b32_e32 v41, 16, v87
	v_exp_f32_e32 v40, v40
	v_fma_f32 v38, v46, v41, v38
	v_and_b32_e32 v41, 0xffff0000, v87
	v_fmac_f32_e32 v39, v47, v41
	v_mul_f32_e32 v41, 0x3d372713, v37
	v_mul_f32_e32 v41, v37, v41
	v_fma_f32 v41, v37, v41, v37
	v_add_f32_e32 v40, 1.0, v40
	v_mul_f32_e32 v41, 0x3f4c422a, v41
	v_rcp_f32_e32 v40, v40
	v_add_f32_e32 v41, v41, v41
	v_mul_f32_e32 v41, 0x3fb8aa3b, v41
	v_exp_f32_e32 v41, v41
	v_fma_f32 v40, v40, -2.0, 1.0
	v_mul_f32_e32 v36, 0.5, v36
	v_add_f32_e32 v40, 1.0, v40
	v_mul_f32_e32 v36, v36, v40
	v_add_f32_e32 v40, 1.0, v41
	v_mul_f32_e32 v41, 0x3d372713, v38
	v_mul_f32_e32 v41, v38, v41
	v_fma_f32 v41, v38, v41, v38
	v_mul_f32_e32 v42, 0x3d372713, v39
	v_mul_f32_e32 v41, 0x3f4c422a, v41
	v_mul_f32_e32 v42, v39, v42
	v_add_f32_e32 v41, v41, v41
	v_fma_f32 v42, v39, v42, v39
	v_mul_f32_e32 v41, 0x3fb8aa3b, v41
	v_mul_f32_e32 v42, 0x3f4c422a, v42
	v_rcp_f32_e32 v40, v40
	v_exp_f32_e32 v41, v41
	v_add_f32_e32 v42, v42, v42
	v_mul_f32_e32 v42, 0x3fb8aa3b, v42
	v_exp_f32_e32 v42, v42
	v_fma_f32 v40, v40, -2.0, 1.0
	v_add_f32_e32 v41, 1.0, v41
	v_mul_f32_e32 v37, 0.5, v37
	v_add_f32_e32 v40, 1.0, v40
	v_rcp_f32_e32 v41, v41
	v_mul_f32_e32 v37, v37, v40
	v_add_f32_e32 v40, 1.0, v42
	v_rcp_f32_e32 v40, v40
	v_cvt_pk_bf16_f32 v36, v36, v37
	v_fma_f32 v37, v41, -2.0, 1.0
	v_mul_f32_e32 v38, 0.5, v38
	v_add_f32_e32 v37, 1.0, v37
	v_mul_f32_e32 v37, v38, v37
	v_fma_f32 v38, v40, -2.0, 1.0
	v_mul_f32_e32 v39, 0.5, v39
	v_add_f32_e32 v38, 1.0, v38
	v_mul_f32_e32 v38, v39, v38
	v_cvt_pk_bf16_f32 v37, v37, v38
	global_store_dwordx2 v[120:121], v[36:37], off offset:160
	s_waitcnt vmcnt(15)
	v_lshlrev_b32_e32 v36, 16, v84
	v_fma_f32 v32, v44, v36, v32
	v_mul_f32_e32 v36, 0x3d372713, v32
	v_mul_f32_e32 v36, v32, v36
	v_fma_f32 v36, v32, v36, v32
	v_mul_f32_e32 v36, 0x3f4c422a, v36
	v_add_f32_e32 v36, v36, v36
	v_and_b32_e32 v37, 0xffff0000, v84
	v_mul_f32_e32 v36, 0x3fb8aa3b, v36
	v_fma_f32 v33, v45, v37, v33
	v_lshlrev_b32_e32 v37, 16, v85
	v_exp_f32_e32 v36, v36
	v_fma_f32 v34, v46, v37, v34
	v_and_b32_e32 v37, 0xffff0000, v85
	v_fmac_f32_e32 v35, v47, v37
	v_mul_f32_e32 v37, 0x3d372713, v33
	v_mul_f32_e32 v37, v33, v37
	v_fma_f32 v37, v33, v37, v33
	v_add_f32_e32 v36, 1.0, v36
	v_mul_f32_e32 v37, 0x3f4c422a, v37
	v_rcp_f32_e32 v36, v36
	v_add_f32_e32 v37, v37, v37
	v_mul_f32_e32 v37, 0x3fb8aa3b, v37
	v_exp_f32_e32 v37, v37
	v_fma_f32 v36, v36, -2.0, 1.0
	v_mul_f32_e32 v32, 0.5, v32
	v_add_f32_e32 v36, 1.0, v36
	v_mul_f32_e32 v32, v32, v36
	v_add_f32_e32 v36, 1.0, v37
	v_mul_f32_e32 v37, 0x3d372713, v34
	v_mul_f32_e32 v37, v34, v37
	v_fma_f32 v37, v34, v37, v34
	v_mul_f32_e32 v38, 0x3d372713, v35
	v_mul_f32_e32 v37, 0x3f4c422a, v37
	v_mul_f32_e32 v38, v35, v38
	v_add_f32_e32 v37, v37, v37
	v_fma_f32 v38, v35, v38, v35
	v_mul_f32_e32 v37, 0x3fb8aa3b, v37
	v_mul_f32_e32 v38, 0x3f4c422a, v38
	v_rcp_f32_e32 v36, v36
	v_exp_f32_e32 v37, v37
	v_add_f32_e32 v38, v38, v38
	v_mul_f32_e32 v38, 0x3fb8aa3b, v38
	v_exp_f32_e32 v38, v38
	v_fma_f32 v36, v36, -2.0, 1.0
	v_add_f32_e32 v37, 1.0, v37
	v_mul_f32_e32 v33, 0.5, v33
	v_add_f32_e32 v36, 1.0, v36
	v_rcp_f32_e32 v37, v37
	v_mul_f32_e32 v33, v33, v36
	v_add_f32_e32 v36, 1.0, v38
	v_rcp_f32_e32 v36, v36
	v_cvt_pk_bf16_f32 v32, v32, v33
	v_fma_f32 v33, v37, -2.0, 1.0
	v_mul_f32_e32 v34, 0.5, v34
	v_add_f32_e32 v33, 1.0, v33
	v_mul_f32_e32 v33, v34, v33
	v_fma_f32 v34, v36, -2.0, 1.0
	v_mul_f32_e32 v35, 0.5, v35
	v_add_f32_e32 v34, 1.0, v34
	v_mul_f32_e32 v34, v35, v34
	v_cvt_pk_bf16_f32 v33, v33, v34
	global_store_dwordx2 v[116:117], v[32:33], off offset:160
	s_waitcnt vmcnt(15)
	v_lshlrev_b32_e32 v32, 16, v82
	v_fma_f32 v28, v44, v32, v28
	v_mul_f32_e32 v32, 0x3d372713, v28
	v_mul_f32_e32 v32, v28, v32
	v_fma_f32 v32, v28, v32, v28
	v_mul_f32_e32 v32, 0x3f4c422a, v32
	v_add_f32_e32 v32, v32, v32
	v_and_b32_e32 v33, 0xffff0000, v82
	v_mul_f32_e32 v32, 0x3fb8aa3b, v32
	v_fma_f32 v29, v45, v33, v29
	v_lshlrev_b32_e32 v33, 16, v83
	v_exp_f32_e32 v32, v32
	v_fma_f32 v30, v46, v33, v30
	v_and_b32_e32 v33, 0xffff0000, v83
	v_fmac_f32_e32 v31, v47, v33
	v_mul_f32_e32 v33, 0x3d372713, v29
	v_mul_f32_e32 v33, v29, v33
	v_fma_f32 v33, v29, v33, v29
	v_add_f32_e32 v32, 1.0, v32
	v_mul_f32_e32 v33, 0x3f4c422a, v33
	v_rcp_f32_e32 v32, v32
	v_add_f32_e32 v33, v33, v33
	v_mul_f32_e32 v33, 0x3fb8aa3b, v33
	v_exp_f32_e32 v33, v33
	v_fma_f32 v32, v32, -2.0, 1.0
	v_mul_f32_e32 v28, 0.5, v28
	v_add_f32_e32 v32, 1.0, v32
	v_mul_f32_e32 v28, v28, v32
	v_add_f32_e32 v32, 1.0, v33
	v_mul_f32_e32 v33, 0x3d372713, v30
	v_mul_f32_e32 v33, v30, v33
	v_fma_f32 v33, v30, v33, v30
	v_mul_f32_e32 v34, 0x3d372713, v31
	v_mul_f32_e32 v33, 0x3f4c422a, v33
	v_mul_f32_e32 v34, v31, v34
	v_add_f32_e32 v33, v33, v33
	v_fma_f32 v34, v31, v34, v31
	v_mul_f32_e32 v33, 0x3fb8aa3b, v33
	v_mul_f32_e32 v34, 0x3f4c422a, v34
	v_rcp_f32_e32 v32, v32
	v_exp_f32_e32 v33, v33
	v_add_f32_e32 v34, v34, v34
	v_mul_f32_e32 v34, 0x3fb8aa3b, v34
	v_exp_f32_e32 v34, v34
	v_fma_f32 v32, v32, -2.0, 1.0
	v_add_f32_e32 v33, 1.0, v33
	v_mul_f32_e32 v29, 0.5, v29
	v_add_f32_e32 v32, 1.0, v32
	v_rcp_f32_e32 v33, v33
	v_mul_f32_e32 v29, v29, v32
	v_add_f32_e32 v32, 1.0, v34
	v_rcp_f32_e32 v32, v32
	v_cvt_pk_bf16_f32 v28, v28, v29
	v_fma_f32 v29, v33, -2.0, 1.0
	v_mul_f32_e32 v30, 0.5, v30
	v_add_f32_e32 v29, 1.0, v29
	v_mul_f32_e32 v29, v30, v29
	v_fma_f32 v30, v32, -2.0, 1.0
	v_mul_f32_e32 v31, 0.5, v31
	v_add_f32_e32 v30, 1.0, v30
	v_mul_f32_e32 v30, v31, v30
	v_cvt_pk_bf16_f32 v29, v29, v30
	global_store_dwordx2 v[132:133], v[28:29], off offset:192
	s_waitcnt vmcnt(15)
; __device__ __forceinline__ unsigned pk2(float lo, float hi) { return pg8::cvt_pk_bf16(lo, hi); }
; __device__ __forceinline__ float gelu_tanh(float x) { const float z = 0.7978845608028654f * (x + 0.044715f * x * x * x); const float t = 1.f - 2.f * __builtin_amdgcn_rcpf(__expf(2.f * z) + 1.f); return 0.5f * x * (1.f + t); }
; template <int PMODE> __device__ __forceinline__ void ssm_c_task(unsigned char* ws, LAS unsigned char* lds, int l, int task, int tid_in) {
;     ...
;             for (int c = 0; c < 4; ++c) { const int col = cb * 64 + c * 16 + rr_e; const size_t tok = (size_t)col * 64 + wid * 8 + a0 + a;
;                 const f32x4 av = acc[a0 + a][c];
;                 const float y0 = av[0] + dv[0] * bflo(uw[a][c].x), y1 = av[1] + dv[1] * bfhi(uw[a][c].x), y2 = av[2] + dv[2] * bflo(uw[a][c].y), y3 = av[3] + dv[3] * bfhi(uw[a][c].y);
;                 u32x2 o; o.x = pk2(gelu_tanh(y0), gelu_tanh(y1)); o.y = pk2(gelu_tanh(y2), gelu_tanh(y3));
;                 if (PMODE == 4) asm volatile("" :: "v"(o)); else *(u32x2*)(yb + (c * 1024 + a0 + a) * 16) = o; }
	v_lshlrev_b32_e32 v28, 16, v80
	v_fma_f32 v24, v44, v28, v24
	v_mul_f32_e32 v28, 0x3d372713, v24
	v_mul_f32_e32 v28, v24, v28
	v_fma_f32 v28, v24, v28, v24
	v_mul_f32_e32 v28, 0x3f4c422a, v28
	v_add_f32_e32 v28, v28, v28
	v_and_b32_e32 v29, 0xffff0000, v80
	v_mul_f32_e32 v28, 0x3fb8aa3b, v28
	v_fma_f32 v25, v45, v29, v25
	v_lshlrev_b32_e32 v29, 16, v81
	v_exp_f32_e32 v28, v28
	v_fma_f32 v26, v46, v29, v26
	v_and_b32_e32 v29, 0xffff0000, v81
	v_fmac_f32_e32 v27, v47, v29
	v_mul_f32_e32 v29, 0x3d372713, v25
	v_mul_f32_e32 v29, v25, v29
	v_fma_f32 v29, v25, v29, v25
	v_add_f32_e32 v28, 1.0, v28
	v_mul_f32_e32 v29, 0x3f4c422a, v29
	v_rcp_f32_e32 v28, v28
	v_add_f32_e32 v29, v29, v29
	v_mul_f32_e32 v29, 0x3fb8aa3b, v29
	v_exp_f32_e32 v29, v29
	v_fma_f32 v28, v28, -2.0, 1.0
	v_mul_f32_e32 v24, 0.5, v24
	v_add_f32_e32 v28, 1.0, v28
	v_mul_f32_e32 v24, v24, v28
	v_add_f32_e32 v28, 1.0, v29
	v_mul_f32_e32 v29, 0x3d372713, v26
	v_mul_f32_e32 v29, v26, v29
	v_fma_f32 v29, v26, v29, v26
	v_mul_f32_e32 v30, 0x3d372713, v27
	v_mul_f32_e32 v29, 0x3f4c422a, v29
	v_mul_f32_e32 v30, v27, v30
	v_add_f32_e32 v29, v29, v29
	v_fma_f32 v30, v27, v30, v27
	v_mul_f32_e32 v29, 0x3fb8aa3b, v29
	v_mul_f32_e32 v30, 0x3f4c422a, v30
	v_rcp_f32_e32 v28, v28
	v_exp_f32_e32 v29, v29
	v_add_f32_e32 v30, v30, v30
	v_mul_f32_e32 v30, 0x3fb8aa3b, v30
	v_exp_f32_e32 v30, v30
	v_fma_f32 v28, v28, -2.0, 1.0
	v_add_f32_e32 v29, 1.0, v29
	v_mul_f32_e32 v25, 0.5, v25
	v_add_f32_e32 v28, 1.0, v28
	v_rcp_f32_e32 v29, v29
	v_mul_f32_e32 v25, v25, v28
	v_add_f32_e32 v28, 1.0, v30
	v_rcp_f32_e32 v28, v28
	v_cvt_pk_bf16_f32 v24, v24, v25
	v_fma_f32 v25, v29, -2.0, 1.0
	v_mul_f32_e32 v26, 0.5, v26
	v_add_f32_e32 v25, 1.0, v25
	v_mul_f32_e32 v25, v26, v25
	v_fma_f32 v26, v28, -2.0, 1.0
	v_mul_f32_e32 v27, 0.5, v27
	v_add_f32_e32 v26, 1.0, v26
	v_mul_f32_e32 v26, v27, v26
	v_cvt_pk_bf16_f32 v25, v25, v26
	global_store_dwordx2 v[124:125], v[24:25], off offset:192
	s_waitcnt vmcnt(15)
	v_lshlrev_b32_e32 v24, 16, v78
	v_fma_f32 v20, v44, v24, v20
	v_mul_f32_e32 v24, 0x3d372713, v20
	v_mul_f32_e32 v24, v20, v24
	v_fma_f32 v24, v20, v24, v20
	v_mul_f32_e32 v24, 0x3f4c422a, v24
	v_add_f32_e32 v24, v24, v24
	v_and_b32_e32 v25, 0xffff0000, v78
	v_mul_f32_e32 v24, 0x3fb8aa3b, v24
	v_fma_f32 v21, v45, v25, v21
	v_lshlrev_b32_e32 v25, 16, v79
	v_exp_f32_e32 v24, v24
	v_fma_f32 v22, v46, v25, v22
	v_and_b32_e32 v25, 0xffff0000, v79
	v_fmac_f32_e32 v23, v47, v25
	v_mul_f32_e32 v25, 0x3d372713, v21
	v_mul_f32_e32 v25, v21, v25
	v_fma_f32 v25, v21, v25, v21
	v_add_f32_e32 v24, 1.0, v24
	v_mul_f32_e32 v25, 0x3f4c422a, v25
	v_rcp_f32_e32 v24, v24
	v_add_f32_e32 v25, v25, v25
	v_mul_f32_e32 v25, 0x3fb8aa3b, v25
	v_exp_f32_e32 v25, v25
	v_fma_f32 v24, v24, -2.0, 1.0
	v_mul_f32_e32 v20, 0.5, v20
	v_add_f32_e32 v24, 1.0, v24
	v_mul_f32_e32 v20, v20, v24
	v_add_f32_e32 v24, 1.0, v25
	v_mul_f32_e32 v25, 0x3d372713, v22
	v_mul_f32_e32 v25, v22, v25
	v_fma_f32 v25, v22, v25, v22
	v_mul_f32_e32 v26, 0x3d372713, v23
	v_mul_f32_e32 v25, 0x3f4c422a, v25
	v_mul_f32_e32 v26, v23, v26
	v_add_f32_e32 v25, v25, v25
	v_fma_f32 v26, v23, v26, v23
	v_mul_f32_e32 v25, 0x3fb8aa3b, v25
	v_mul_f32_e32 v26, 0x3f4c422a, v26
	v_rcp_f32_e32 v24, v24
	v_exp_f32_e32 v25, v25
	v_add_f32_e32 v26, v26, v26
	v_mul_f32_e32 v26, 0x3fb8aa3b, v26
	v_exp_f32_e32 v26, v26
	v_fma_f32 v24, v24, -2.0, 1.0
	v_add_f32_e32 v25, 1.0, v25
	v_mul_f32_e32 v21, 0.5, v21
	v_add_f32_e32 v24, 1.0, v24
	v_rcp_f32_e32 v25, v25
	v_mul_f32_e32 v21, v21, v24
	v_add_f32_e32 v24, 1.0, v26
	v_rcp_f32_e32 v24, v24
	v_cvt_pk_bf16_f32 v20, v20, v21
	v_fma_f32 v21, v25, -2.0, 1.0
	v_mul_f32_e32 v22, 0.5, v22
	v_add_f32_e32 v21, 1.0, v21
	v_mul_f32_e32 v21, v22, v21
	v_fma_f32 v22, v24, -2.0, 1.0
	v_mul_f32_e32 v23, 0.5, v23
	v_add_f32_e32 v22, 1.0, v22
	v_mul_f32_e32 v22, v23, v22
	v_cvt_pk_bf16_f32 v21, v21, v22
	global_store_dwordx2 v[120:121], v[20:21], off offset:192
	s_waitcnt vmcnt(15)
	v_lshlrev_b32_e32 v20, 16, v76
	v_fma_f32 v16, v44, v20, v16
	v_mul_f32_e32 v20, 0x3d372713, v16
	v_mul_f32_e32 v20, v16, v20
	v_fma_f32 v20, v16, v20, v16
	v_mul_f32_e32 v20, 0x3f4c422a, v20
	v_add_f32_e32 v20, v20, v20
	v_and_b32_e32 v21, 0xffff0000, v76
	v_mul_f32_e32 v20, 0x3fb8aa3b, v20
	v_fma_f32 v17, v45, v21, v17
	v_lshlrev_b32_e32 v21, 16, v77
	v_exp_f32_e32 v20, v20
	v_fma_f32 v18, v46, v21, v18
	v_and_b32_e32 v21, 0xffff0000, v77
	v_fmac_f32_e32 v19, v47, v21
	v_mul_f32_e32 v21, 0x3d372713, v17
	v_mul_f32_e32 v21, v17, v21
	v_fma_f32 v21, v17, v21, v17
	v_add_f32_e32 v20, 1.0, v20
	v_mul_f32_e32 v21, 0x3f4c422a, v21
	v_rcp_f32_e32 v20, v20
	v_add_f32_e32 v21, v21, v21
	v_mul_f32_e32 v21, 0x3fb8aa3b, v21
	v_exp_f32_e32 v21, v21
	v_fma_f32 v20, v20, -2.0, 1.0
	v_mul_f32_e32 v16, 0.5, v16
	v_add_f32_e32 v20, 1.0, v20
	v_mul_f32_e32 v16, v16, v20
	v_add_f32_e32 v20, 1.0, v21
	v_mul_f32_e32 v21, 0x3d372713, v18
	v_mul_f32_e32 v21, v18, v21
	v_fma_f32 v21, v18, v21, v18
	v_mul_f32_e32 v22, 0x3d372713, v19
	v_mul_f32_e32 v21, 0x3f4c422a, v21
	v_mul_f32_e32 v22, v19, v22
	v_add_f32_e32 v21, v21, v21
	v_fma_f32 v22, v19, v22, v19
	v_mul_f32_e32 v21, 0x3fb8aa3b, v21
	v_mul_f32_e32 v22, 0x3f4c422a, v22
	v_rcp_f32_e32 v20, v20
	v_exp_f32_e32 v21, v21
	v_add_f32_e32 v22, v22, v22
	v_mul_f32_e32 v22, 0x3fb8aa3b, v22
	v_exp_f32_e32 v22, v22
	v_fma_f32 v20, v20, -2.0, 1.0
	v_add_f32_e32 v21, 1.0, v21
	v_mul_f32_e32 v17, 0.5, v17
	v_add_f32_e32 v20, 1.0, v20
	v_rcp_f32_e32 v21, v21
	v_mul_f32_e32 v17, v17, v20
	v_add_f32_e32 v20, 1.0, v22
	v_rcp_f32_e32 v20, v20
	v_cvt_pk_bf16_f32 v16, v16, v17
	v_fma_f32 v17, v21, -2.0, 1.0
	v_mul_f32_e32 v18, 0.5, v18
	v_add_f32_e32 v17, 1.0, v17
	v_mul_f32_e32 v17, v18, v17
	v_fma_f32 v18, v20, -2.0, 1.0
	v_mul_f32_e32 v19, 0.5, v19
	v_add_f32_e32 v18, 1.0, v18
	v_mul_f32_e32 v18, v19, v18
	v_cvt_pk_bf16_f32 v17, v17, v18
	global_store_dwordx2 v[116:117], v[16:17], off offset:192
	s_waitcnt vmcnt(15)
; __device__ __forceinline__ unsigned pk2(float lo, float hi) { return pg8::cvt_pk_bf16(lo, hi); }
; __device__ __forceinline__ float gelu_tanh(float x) { const float z = 0.7978845608028654f * (x + 0.044715f * x * x * x); const float t = 1.f - 2.f * __builtin_amdgcn_rcpf(__expf(2.f * z) + 1.f); return 0.5f * x * (1.f + t); }
; template <int PMODE> __device__ __forceinline__ void ssm_c_task(unsigned char* ws, LAS unsigned char* lds, int l, int task, int tid_in) {
;     ...
;             for (int c = 0; c < 4; ++c) { const int col = cb * 64 + c * 16 + rr_e; const size_t tok = (size_t)col * 64 + wid * 8 + a0 + a;
;                 const f32x4 av = acc[a0 + a][c];
;                 const float y0 = av[0] + dv[0] * bflo(uw[a][c].x), y1 = av[1] + dv[1] * bfhi(uw[a][c].x), y2 = av[2] + dv[2] * bflo(uw[a][c].y), y3 = av[3] + dv[3] * bfhi(uw[a][c].y);
;                 u32x2 o; o.x = pk2(gelu_tanh(y0), gelu_tanh(y1)); o.y = pk2(gelu_tanh(y2), gelu_tanh(y3));
;                 if (PMODE == 4) asm volatile("" :: "v"(o)); else *(u32x2*)(yb + (c * 1024 + a0 + a) * 16) = o; }
	v_lshlrev_b32_e32 v16, 16, v74
	v_fma_f32 v12, v44, v16, v12
	v_mul_f32_e32 v16, 0x3d372713, v12
	v_mul_f32_e32 v16, v12, v16
	v_fma_f32 v16, v12, v16, v12
	v_mul_f32_e32 v16, 0x3f4c422a, v16
	v_add_f32_e32 v16, v16, v16
	v_and_b32_e32 v17, 0xffff0000, v74
	v_mul_f32_e32 v16, 0x3fb8aa3b, v16
	v_fma_f32 v13, v45, v17, v13
	v_lshlrev_b32_e32 v17, 16, v75
	v_exp_f32_e32 v16, v16
	v_fma_f32 v14, v46, v17, v14
	v_and_b32_e32 v17, 0xffff0000, v75
	v_fmac_f32_e32 v15, v47, v17
	v_mul_f32_e32 v17, 0x3d372713, v13
	v_mul_f32_e32 v17, v13, v17
	v_fma_f32 v17, v13, v17, v13
	v_add_f32_e32 v16, 1.0, v16
	v_mul_f32_e32 v17, 0x3f4c422a, v17
	v_rcp_f32_e32 v16, v16
	v_add_f32_e32 v17, v17, v17
	v_mul_f32_e32 v17, 0x3fb8aa3b, v17
	v_exp_f32_e32 v17, v17
	v_fma_f32 v16, v16, -2.0, 1.0
	v_mul_f32_e32 v12, 0.5, v12
	v_add_f32_e32 v16, 1.0, v16
	v_mul_f32_e32 v12, v12, v16
	v_add_f32_e32 v16, 1.0, v17
	v_mul_f32_e32 v17, 0x3d372713, v14
	v_mul_f32_e32 v17, v14, v17
	v_fma_f32 v17, v14, v17, v14
	v_mul_f32_e32 v18, 0x3d372713, v15
	v_mul_f32_e32 v17, 0x3f4c422a, v17
	v_mul_f32_e32 v18, v15, v18
	v_add_f32_e32 v17, v17, v17
	v_fma_f32 v18, v15, v18, v15
	v_mul_f32_e32 v17, 0x3fb8aa3b, v17
	v_mul_f32_e32 v18, 0x3f4c422a, v18
	v_rcp_f32_e32 v16, v16
	v_exp_f32_e32 v17, v17
	v_add_f32_e32 v18, v18, v18
	v_mul_f32_e32 v18, 0x3fb8aa3b, v18
	v_exp_f32_e32 v18, v18
	v_fma_f32 v16, v16, -2.0, 1.0
	v_add_f32_e32 v17, 1.0, v17
	v_mul_f32_e32 v13, 0.5, v13
	v_add_f32_e32 v16, 1.0, v16
	v_rcp_f32_e32 v17, v17
	v_mul_f32_e32 v13, v13, v16
	v_add_f32_e32 v16, 1.0, v18
	v_rcp_f32_e32 v16, v16
	v_cvt_pk_bf16_f32 v12, v12, v13
	v_fma_f32 v13, v17, -2.0, 1.0
	v_mul_f32_e32 v14, 0.5, v14
	v_add_f32_e32 v13, 1.0, v13
	v_mul_f32_e32 v13, v14, v13
	v_fma_f32 v14, v16, -2.0, 1.0
	v_mul_f32_e32 v15, 0.5, v15
	v_add_f32_e32 v14, 1.0, v14
	v_mul_f32_e32 v14, v15, v14
	v_cvt_pk_bf16_f32 v13, v13, v14
	global_store_dwordx2 v[132:133], v[12:13], off offset:224
	s_waitcnt vmcnt(15)
	v_lshlrev_b32_e32 v12, 16, v72
	v_fma_f32 v8, v44, v12, v8
	v_mul_f32_e32 v12, 0x3d372713, v8
	v_mul_f32_e32 v12, v8, v12
	v_fma_f32 v12, v8, v12, v8
	v_mul_f32_e32 v12, 0x3f4c422a, v12
	v_add_f32_e32 v12, v12, v12
	v_and_b32_e32 v13, 0xffff0000, v72
	v_mul_f32_e32 v12, 0x3fb8aa3b, v12
	v_fma_f32 v9, v45, v13, v9
	v_lshlrev_b32_e32 v13, 16, v73
	v_exp_f32_e32 v12, v12
	v_fma_f32 v10, v46, v13, v10
	v_and_b32_e32 v13, 0xffff0000, v73
	v_fmac_f32_e32 v11, v47, v13
	v_mul_f32_e32 v13, 0x3d372713, v9
	v_mul_f32_e32 v13, v9, v13
	v_fma_f32 v13, v9, v13, v9
	v_add_f32_e32 v12, 1.0, v12
	v_mul_f32_e32 v13, 0x3f4c422a, v13
	v_rcp_f32_e32 v12, v12
	v_add_f32_e32 v13, v13, v13
	v_mul_f32_e32 v13, 0x3fb8aa3b, v13
	v_exp_f32_e32 v13, v13
	v_fma_f32 v12, v12, -2.0, 1.0
	v_mul_f32_e32 v8, 0.5, v8
	v_add_f32_e32 v12, 1.0, v12
	v_mul_f32_e32 v8, v8, v12
	v_add_f32_e32 v12, 1.0, v13
	v_mul_f32_e32 v13, 0x3d372713, v10
	v_mul_f32_e32 v13, v10, v13
	v_fma_f32 v13, v10, v13, v10
	v_mul_f32_e32 v14, 0x3d372713, v11
	v_mul_f32_e32 v13, 0x3f4c422a, v13
	v_mul_f32_e32 v14, v11, v14
	v_add_f32_e32 v13, v13, v13
	v_fma_f32 v14, v11, v14, v11
	v_mul_f32_e32 v13, 0x3fb8aa3b, v13
	v_mul_f32_e32 v14, 0x3f4c422a, v14
	v_rcp_f32_e32 v12, v12
	v_exp_f32_e32 v13, v13
	v_add_f32_e32 v14, v14, v14
	v_mul_f32_e32 v14, 0x3fb8aa3b, v14
	v_exp_f32_e32 v14, v14
	v_fma_f32 v12, v12, -2.0, 1.0
	v_add_f32_e32 v13, 1.0, v13
	v_mul_f32_e32 v9, 0.5, v9
	v_add_f32_e32 v12, 1.0, v12
	v_rcp_f32_e32 v13, v13
	v_mul_f32_e32 v9, v9, v12
	v_add_f32_e32 v12, 1.0, v14
	v_rcp_f32_e32 v12, v12
	v_cvt_pk_bf16_f32 v8, v8, v9
	v_fma_f32 v9, v13, -2.0, 1.0
	v_mul_f32_e32 v10, 0.5, v10
	v_add_f32_e32 v9, 1.0, v9
	v_mul_f32_e32 v9, v10, v9
	v_fma_f32 v10, v12, -2.0, 1.0
	v_mul_f32_e32 v11, 0.5, v11
	v_add_f32_e32 v10, 1.0, v10
	v_mul_f32_e32 v10, v11, v10
	v_cvt_pk_bf16_f32 v9, v9, v10
	global_store_dwordx2 v[124:125], v[8:9], off offset:224
	s_waitcnt vmcnt(15)
; __device__ __forceinline__ unsigned pk2(float lo, float hi) { return pg8::cvt_pk_bf16(lo, hi); }
; __device__ __forceinline__ float gelu_tanh(float x) { const float z = 0.7978845608028654f * (x + 0.044715f * x * x * x); const float t = 1.f - 2.f * __builtin_amdgcn_rcpf(__expf(2.f * z) + 1.f); return 0.5f * x * (1.f + t); }
; template <int PMODE> __device__ __forceinline__ void ssm_c_task(unsigned char* ws, LAS unsigned char* lds, int l, int task, int tid_in) {
;     ...
;             for (int c = 0; c < 4; ++c) { const int col = cb * 64 + c * 16 + rr_e; const size_t tok = (size_t)col * 64 + wid * 8 + a0 + a;
;                 const f32x4 av = acc[a0 + a][c];
;                 const float y0 = av[0] + dv[0] * bflo(uw[a][c].x), y1 = av[1] + dv[1] * bfhi(uw[a][c].x), y2 = av[2] + dv[2] * bflo(uw[a][c].y), y3 = av[3] + dv[3] * bfhi(uw[a][c].y);
;                 u32x2 o; o.x = pk2(gelu_tanh(y0), gelu_tanh(y1)); o.y = pk2(gelu_tanh(y2), gelu_tanh(y3));
;                 if (PMODE == 4) asm volatile("" :: "v"(o)); else *(u32x2*)(yb + (c * 1024 + a0 + a) * 16) = o; }
	v_lshlrev_b32_e32 v8, 16, v70
	v_fma_f32 v4, v44, v8, v4
	v_mul_f32_e32 v8, 0x3d372713, v4
	v_mul_f32_e32 v8, v4, v8
	v_fma_f32 v8, v4, v8, v4
	v_mul_f32_e32 v8, 0x3f4c422a, v8
	v_add_f32_e32 v8, v8, v8
	v_and_b32_e32 v9, 0xffff0000, v70
	v_mul_f32_e32 v8, 0x3fb8aa3b, v8
	v_fma_f32 v5, v45, v9, v5
	v_lshlrev_b32_e32 v9, 16, v71
	v_exp_f32_e32 v8, v8
	v_fma_f32 v6, v46, v9, v6
	v_and_b32_e32 v9, 0xffff0000, v71
	v_fmac_f32_e32 v7, v47, v9
	v_mul_f32_e32 v9, 0x3d372713, v5
	v_mul_f32_e32 v9, v5, v9
	v_fma_f32 v9, v5, v9, v5
	v_add_f32_e32 v8, 1.0, v8
	v_mul_f32_e32 v9, 0x3f4c422a, v9
	v_rcp_f32_e32 v8, v8
	v_add_f32_e32 v9, v9, v9
	v_mul_f32_e32 v9, 0x3fb8aa3b, v9
	v_exp_f32_e32 v9, v9
	v_fma_f32 v8, v8, -2.0, 1.0
	v_mul_f32_e32 v4, 0.5, v4
	v_add_f32_e32 v8, 1.0, v8
	v_mul_f32_e32 v4, v4, v8
	v_add_f32_e32 v8, 1.0, v9
	v_mul_f32_e32 v9, 0x3d372713, v6
	v_mul_f32_e32 v9, v6, v9
	v_fma_f32 v9, v6, v9, v6
	v_mul_f32_e32 v10, 0x3d372713, v7
	v_mul_f32_e32 v9, 0x3f4c422a, v9
	v_mul_f32_e32 v10, v7, v10
	v_add_f32_e32 v9, v9, v9
	v_fma_f32 v10, v7, v10, v7
	v_mul_f32_e32 v9, 0x3fb8aa3b, v9
	v_mul_f32_e32 v10, 0x3f4c422a, v10
	v_rcp_f32_e32 v8, v8
	v_exp_f32_e32 v9, v9
	v_add_f32_e32 v10, v10, v10
	v_mul_f32_e32 v10, 0x3fb8aa3b, v10
	v_exp_f32_e32 v10, v10
	v_fma_f32 v8, v8, -2.0, 1.0
	v_add_f32_e32 v9, 1.0, v9
	v_mul_f32_e32 v5, 0.5, v5
	v_add_f32_e32 v8, 1.0, v8
	v_rcp_f32_e32 v9, v9
	v_mul_f32_e32 v5, v5, v8
	v_add_f32_e32 v8, 1.0, v10
	v_rcp_f32_e32 v8, v8
	v_cvt_pk_bf16_f32 v4, v4, v5
	v_fma_f32 v5, v9, -2.0, 1.0
	v_mul_f32_e32 v6, 0.5, v6
	v_add_f32_e32 v5, 1.0, v5
	v_mul_f32_e32 v5, v6, v5
	v_fma_f32 v6, v8, -2.0, 1.0
	v_mul_f32_e32 v7, 0.5, v7
	v_add_f32_e32 v6, 1.0, v6
	v_mul_f32_e32 v6, v7, v6
	v_cvt_pk_bf16_f32 v5, v5, v6
	global_store_dwordx2 v[120:121], v[4:5], off offset:224
	s_waitcnt vmcnt(15)
	v_lshlrev_b32_e32 v4, 16, v68
	v_fma_f32 v0, v44, v4, v0
	v_mul_f32_e32 v4, 0x3d372713, v0
	v_mul_f32_e32 v4, v0, v4
	v_fma_f32 v4, v0, v4, v0
	v_mul_f32_e32 v4, 0x3f4c422a, v4
	v_add_f32_e32 v4, v4, v4
	v_and_b32_e32 v5, 0xffff0000, v68
	v_mul_f32_e32 v4, 0x3fb8aa3b, v4
	v_fma_f32 v1, v45, v5, v1
	v_lshlrev_b32_e32 v5, 16, v69
	v_exp_f32_e32 v4, v4
	v_fma_f32 v2, v46, v5, v2
	v_and_b32_e32 v5, 0xffff0000, v69
	v_fmac_f32_e32 v3, v47, v5
	v_mul_f32_e32 v5, 0x3d372713, v1
	v_mul_f32_e32 v5, v1, v5
	v_fma_f32 v5, v1, v5, v1
	v_add_f32_e32 v4, 1.0, v4
	v_mul_f32_e32 v5, 0x3f4c422a, v5
	v_rcp_f32_e32 v4, v4
	v_add_f32_e32 v5, v5, v5
	v_mul_f32_e32 v5, 0x3fb8aa3b, v5
	v_exp_f32_e32 v5, v5
	v_fma_f32 v4, v4, -2.0, 1.0
	v_mul_f32_e32 v0, 0.5, v0
	v_add_f32_e32 v4, 1.0, v4
	v_mul_f32_e32 v0, v0, v4
	v_add_f32_e32 v4, 1.0, v5
	v_mul_f32_e32 v5, 0x3d372713, v2
	v_mul_f32_e32 v5, v2, v5
	v_fma_f32 v5, v2, v5, v2
	v_mul_f32_e32 v6, 0x3d372713, v3
	v_mul_f32_e32 v5, 0x3f4c422a, v5
	v_mul_f32_e32 v6, v3, v6
	v_add_f32_e32 v5, v5, v5
	v_fma_f32 v6, v3, v6, v3
	v_mul_f32_e32 v5, 0x3fb8aa3b, v5
	v_mul_f32_e32 v6, 0x3f4c422a, v6
	v_rcp_f32_e32 v4, v4
	v_exp_f32_e32 v5, v5
	v_add_f32_e32 v6, v6, v6
	v_mul_f32_e32 v6, 0x3fb8aa3b, v6
	v_exp_f32_e32 v6, v6
	v_fma_f32 v4, v4, -2.0, 1.0
	v_add_f32_e32 v5, 1.0, v5
	v_mul_f32_e32 v1, 0.5, v1
	v_add_f32_e32 v4, 1.0, v4
	v_rcp_f32_e32 v5, v5
	v_mul_f32_e32 v1, v1, v4
	v_add_f32_e32 v4, 1.0, v6
	v_rcp_f32_e32 v4, v4
	v_cvt_pk_bf16_f32 v0, v0, v1
	v_fma_f32 v1, v5, -2.0, 1.0
	v_mul_f32_e32 v2, 0.5, v2
	v_add_f32_e32 v1, 1.0, v1
	v_mul_f32_e32 v1, v2, v1
	v_fma_f32 v2, v4, -2.0, 1.0
	v_mul_f32_e32 v3, 0.5, v3
	v_add_f32_e32 v2, 1.0, v2
	v_mul_f32_e32 v2, v3, v2
	v_cvt_pk_bf16_f32 v1, v1, v2
	global_store_dwordx2 v[116:117], v[0:1], off offset:224
	s_cbranch_scc0 .LBB0_816
